# K-loops: the s_nop fillers left by the address-add removal dropped where they do not separate an m0 write from an LDS-DMA load (147 fewer issue slots)
# baseline (speedup 1.0000x reference)
.LBB0_197:
	ds_read_b128 v[34:37], v184
	ds_read_b128 v[38:41], v184 offset:1024
	ds_read_b128 v[42:45], v184 offset:2048
	ds_read_b128 v[46:49], v184 offset:3072
	ds_read_b128 v[166:169], v185
	ds_read_b128 v[170:173], v185 offset:1024
	ds_read_b128 v[190:193], v185 offset:2048
	ds_read_b128 v[194:197], v185 offset:3072
	s_add_u32 s13, s8, 0xfffc0080
	s_addc_u32 s24, s9, -1
	s_cmp_eq_u32 s12, 12
	s_cselect_b32 s87, s15, s24
	s_cselect_b32 s86, s23, s13
	s_cselect_b32 s85, s77, vcc_hi
	s_cselect_b32 s84, s79, vcc_lo
	s_add_i32 m0, s90, 0xc000
	ds_read_b128 v[198:201], v186
	ds_read_b128 v[202:205], v186 offset:1024
	ds_read_b128 v[206:209], v186 offset:2048
	ds_read_b128 v[210:213], v186 offset:3072
	ds_read_b128 v[214:217], v186 offset:4096
	ds_read_b128 v[218:221], v186 offset:5120
	ds_read_b128 v[222:225], v186 offset:6144
	ds_read_b128 v[226:229], v186 offset:7168
	global_load_lds_dwordx4 v158, s[8:9]
	s_add_i32 m0, s90, 0xe000
	s_nop 0
	global_load_lds_dwordx4 v160, s[8:9]
	s_waitcnt vmcnt(8)
	s_waitcnt lgkmcnt(0)
	s_barrier
	s_setprio 1
	s_waitcnt lgkmcnt(0)
	v_mfma_f32_16x16x32_bf16 v[142:145], v[34:37], v[198:201], v[142:145]
	v_mfma_f32_16x16x32_bf16 v[138:141], v[42:45], v[198:201], v[138:141]
	v_mfma_f32_16x16x32_bf16 v[126:129], v[34:37], v[206:209], v[126:129]
	v_mfma_f32_16x16x32_bf16 v[122:125], v[42:45], v[206:209], v[122:125]
	v_mfma_f32_16x16x32_bf16 v[110:113], v[34:37], v[214:217], v[110:113]
	v_mfma_f32_16x16x32_bf16 v[106:109], v[42:45], v[214:217], v[106:109]
	v_mfma_f32_16x16x32_bf16 v[94:97], v[34:37], v[222:225], v[94:97]
	v_mfma_f32_16x16x32_bf16 v[90:93], v[42:45], v[222:225], v[90:93]
	v_mfma_f32_16x16x32_bf16 v[142:145], v[38:41], v[202:205], v[142:145]
	v_mfma_f32_16x16x32_bf16 v[138:141], v[46:49], v[202:205], v[138:141]
	v_mfma_f32_16x16x32_bf16 v[126:129], v[38:41], v[210:213], v[126:129]
	v_mfma_f32_16x16x32_bf16 v[122:125], v[46:49], v[210:213], v[122:125]
	v_mfma_f32_16x16x32_bf16 v[110:113], v[38:41], v[218:221], v[110:113]
	v_mfma_f32_16x16x32_bf16 v[106:109], v[46:49], v[218:221], v[106:109]
	v_mfma_f32_16x16x32_bf16 v[94:97], v[38:41], v[226:229], v[94:97]
	v_mfma_f32_16x16x32_bf16 v[90:93], v[46:49], v[226:229], v[90:93]
	s_setprio 0
	s_setprio 1
	v_mfma_f32_16x16x32_bf16 v[134:137], v[166:169], v[198:201], v[134:137]
	v_mfma_f32_16x16x32_bf16 v[130:133], v[190:193], v[198:201], v[130:133]
	v_mfma_f32_16x16x32_bf16 v[118:121], v[166:169], v[206:209], v[118:121]
	v_mfma_f32_16x16x32_bf16 v[114:117], v[190:193], v[206:209], v[114:117]
	v_mfma_f32_16x16x32_bf16 v[102:105], v[166:169], v[214:217], v[102:105]
	v_mfma_f32_16x16x32_bf16 v[98:101], v[190:193], v[214:217], v[98:101]
	v_mfma_f32_16x16x32_bf16 v[86:89], v[166:169], v[222:225], v[86:89]
	v_mfma_f32_16x16x32_bf16 v[82:85], v[190:193], v[222:225], v[82:85]
	v_mfma_f32_16x16x32_bf16 v[134:137], v[170:173], v[202:205], v[134:137]
	v_mfma_f32_16x16x32_bf16 v[130:133], v[194:197], v[202:205], v[130:133]
	v_mfma_f32_16x16x32_bf16 v[118:121], v[170:173], v[210:213], v[118:121]
	v_mfma_f32_16x16x32_bf16 v[114:117], v[194:197], v[210:213], v[114:117]
	v_mfma_f32_16x16x32_bf16 v[102:105], v[170:173], v[218:221], v[102:105]
	v_mfma_f32_16x16x32_bf16 v[98:101], v[194:197], v[218:221], v[98:101]
	v_mfma_f32_16x16x32_bf16 v[86:89], v[170:173], v[226:229], v[86:89]
	v_mfma_f32_16x16x32_bf16 v[82:85], v[194:197], v[226:229], v[82:85]
	s_setprio 0
	s_barrier
	s_add_i32 s13, s62, s89
	s_mov_b32 m0, s13
	ds_read_b128 v[198:201], v186 offset:16384
	ds_read_b128 v[202:205], v186 offset:17408
	ds_read_b128 v[206:209], v186 offset:18432
	ds_read_b128 v[210:213], v186 offset:19456
	ds_read_b128 v[214:217], v186 offset:20480
	ds_read_b128 v[218:221], v186 offset:21504
	ds_read_b128 v[222:225], v186 offset:22528
	ds_read_b128 v[226:229], v186 offset:23552
	global_load_lds_dwordx4 v150, s[84:85]
	s_add_i32 m0, s13, 0x2000
	s_add_u32 s24, s84, 0x40000
	s_addc_u32 s25, s85, 0
	s_add_i32 s13, s63, s89
	global_load_lds_dwordx4 v154, s[84:85]
	s_mov_b32 m0, s13
	s_nop 0
	global_load_lds_dwordx4 v150, s[24:25]
	s_add_i32 m0, s13, 0x2000
	s_nop 0
	global_load_lds_dwordx4 v154, s[24:25]
	s_mov_b32 m0, s90
	s_nop 0
	global_load_lds_dwordx4 v148, s[86:87]
	s_mov_b32 m0, s91
	s_nop 0
	global_load_lds_dwordx4 v152, s[86:87]
	s_waitcnt vmcnt(8)
	s_waitcnt lgkmcnt(0)
	s_barrier
	s_setprio 1
	s_waitcnt lgkmcnt(0)
	v_mfma_f32_16x16x32_bf16 v[78:81], v[34:37], v[198:201], v[78:81]
	v_mfma_f32_16x16x32_bf16 v[74:77], v[42:45], v[198:201], v[74:77]
	v_mfma_f32_16x16x32_bf16 v[62:65], v[34:37], v[206:209], v[62:65]
	v_mfma_f32_16x16x32_bf16 v[58:61], v[42:45], v[206:209], v[58:61]
	v_mfma_f32_16x16x32_bf16 v[30:33], v[34:37], v[214:217], v[30:33]
	v_mfma_f32_16x16x32_bf16 v[26:29], v[42:45], v[214:217], v[26:29]
	v_mfma_f32_16x16x32_bf16 v[14:17], v[34:37], v[222:225], v[14:17]
	v_mfma_f32_16x16x32_bf16 v[10:13], v[42:45], v[222:225], v[10:13]
	v_mfma_f32_16x16x32_bf16 v[78:81], v[38:41], v[202:205], v[78:81]
	v_mfma_f32_16x16x32_bf16 v[74:77], v[46:49], v[202:205], v[74:77]
	v_mfma_f32_16x16x32_bf16 v[62:65], v[38:41], v[210:213], v[62:65]
	v_mfma_f32_16x16x32_bf16 v[58:61], v[46:49], v[210:213], v[58:61]
	v_mfma_f32_16x16x32_bf16 v[30:33], v[38:41], v[218:221], v[30:33]
	v_mfma_f32_16x16x32_bf16 v[26:29], v[46:49], v[218:221], v[26:29]
	v_mfma_f32_16x16x32_bf16 v[14:17], v[38:41], v[226:229], v[14:17]
	v_mfma_f32_16x16x32_bf16 v[10:13], v[46:49], v[226:229], v[10:13]
	s_setprio 0
	s_setprio 1
	v_mfma_f32_16x16x32_bf16 v[22:25], v[166:169], v[214:217], v[22:25]
	v_mfma_f32_16x16x32_bf16 v[18:21], v[190:193], v[214:217], v[18:21]
	v_mfma_f32_16x16x32_bf16 v[6:9], v[166:169], v[222:225], v[6:9]
	v_mfma_f32_16x16x32_bf16 v[2:5], v[190:193], v[222:225], v[2:5]
	v_mfma_f32_16x16x32_bf16 v[34:37], v[166:169], v[198:201], v[70:73]
	v_mfma_f32_16x16x32_bf16 v[38:41], v[190:193], v[198:201], v[66:69]
	v_mfma_f32_16x16x32_bf16 v[42:45], v[166:169], v[206:209], v[54:57]
	v_mfma_f32_16x16x32_bf16 v[46:49], v[190:193], v[206:209], v[50:53]
	v_mfma_f32_16x16x32_bf16 v[22:25], v[170:173], v[218:221], v[22:25]
	v_mfma_f32_16x16x32_bf16 v[18:21], v[194:197], v[218:221], v[18:21]
	v_mfma_f32_16x16x32_bf16 v[6:9], v[170:173], v[226:229], v[6:9]
	v_mfma_f32_16x16x32_bf16 v[2:5], v[194:197], v[226:229], v[2:5]
	v_mfma_f32_16x16x32_bf16 v[34:37], v[170:173], v[202:205], v[34:37]
	v_mfma_f32_16x16x32_bf16 v[38:41], v[194:197], v[202:205], v[38:41]
	v_mfma_f32_16x16x32_bf16 v[42:45], v[170:173], v[210:213], v[42:45]
	v_mfma_f32_16x16x32_bf16 v[46:49], v[194:197], v[210:213], v[46:49]
	s_setprio 0
	s_barrier
	s_add_i32 s13, 0, 0x18000
	s_add_i32 s3, 0, 0x1c000
	v_add_u32_e32 v70, s13, v175
	v_add_u32_e32 v194, s3, v175
	ds_read_b128 v[50:53], v70
	ds_read_b128 v[54:57], v70 offset:1024
	ds_read_b128 v[66:69], v70 offset:2048
	ds_read_b128 v[70:73], v70 offset:3072
	ds_read_b128 v[166:169], v194
	ds_read_b128 v[170:173], v194 offset:1024
	ds_read_b128 v[190:193], v194 offset:2048
	ds_read_b128 v[194:197], v194 offset:3072
	s_add_u32 s24, s86, 0x40000
	s_addc_u32 s25, s87, 0
	s_mov_b32 m0, s92
	ds_read_b128 v[198:201], v186 offset:32768
	ds_read_b128 v[202:205], v186 offset:33792
	ds_read_b128 v[206:209], v186 offset:34816
	ds_read_b128 v[210:213], v186 offset:35840
	ds_read_b128 v[214:217], v186 offset:36864
	ds_read_b128 v[218:221], v186 offset:37888
	ds_read_b128 v[222:225], v186 offset:38912
	ds_read_b128 v[226:229], v186 offset:39936
	global_load_lds_dwordx4 v148, s[24:25]
	s_mov_b32 m0, s93
	s_nop 0
	global_load_lds_dwordx4 v152, s[24:25]
	s_waitcnt vmcnt(8)
	s_waitcnt lgkmcnt(0)
	s_barrier
	s_setprio 1
	s_waitcnt lgkmcnt(0)
	v_mfma_f32_16x16x32_bf16 v[142:145], v[50:53], v[198:201], v[142:145]
	v_mfma_f32_16x16x32_bf16 v[138:141], v[66:69], v[198:201], v[138:141]
	v_mfma_f32_16x16x32_bf16 v[126:129], v[50:53], v[206:209], v[126:129]
	v_mfma_f32_16x16x32_bf16 v[122:125], v[66:69], v[206:209], v[122:125]
	v_mfma_f32_16x16x32_bf16 v[110:113], v[50:53], v[214:217], v[110:113]
	v_mfma_f32_16x16x32_bf16 v[106:109], v[66:69], v[214:217], v[106:109]
	v_mfma_f32_16x16x32_bf16 v[94:97], v[50:53], v[222:225], v[94:97]
	v_mfma_f32_16x16x32_bf16 v[90:93], v[66:69], v[222:225], v[90:93]
	v_mfma_f32_16x16x32_bf16 v[142:145], v[54:57], v[202:205], v[142:145]
	v_mfma_f32_16x16x32_bf16 v[138:141], v[70:73], v[202:205], v[138:141]
	v_mfma_f32_16x16x32_bf16 v[126:129], v[54:57], v[210:213], v[126:129]
	v_mfma_f32_16x16x32_bf16 v[122:125], v[70:73], v[210:213], v[122:125]
	v_mfma_f32_16x16x32_bf16 v[110:113], v[54:57], v[218:221], v[110:113]
	v_mfma_f32_16x16x32_bf16 v[106:109], v[70:73], v[218:221], v[106:109]
	v_mfma_f32_16x16x32_bf16 v[94:97], v[54:57], v[226:229], v[94:97]
	v_mfma_f32_16x16x32_bf16 v[90:93], v[70:73], v[226:229], v[90:93]
	s_setprio 0
	s_setprio 1
	v_mfma_f32_16x16x32_bf16 v[134:137], v[166:169], v[198:201], v[134:137]
	v_mfma_f32_16x16x32_bf16 v[130:133], v[190:193], v[198:201], v[130:133]
	v_mfma_f32_16x16x32_bf16 v[118:121], v[166:169], v[206:209], v[118:121]
	v_mfma_f32_16x16x32_bf16 v[114:117], v[190:193], v[206:209], v[114:117]
	v_mfma_f32_16x16x32_bf16 v[102:105], v[166:169], v[214:217], v[102:105]
	v_mfma_f32_16x16x32_bf16 v[98:101], v[190:193], v[214:217], v[98:101]
	v_mfma_f32_16x16x32_bf16 v[86:89], v[166:169], v[222:225], v[86:89]
	v_mfma_f32_16x16x32_bf16 v[82:85], v[190:193], v[222:225], v[82:85]
	v_mfma_f32_16x16x32_bf16 v[134:137], v[170:173], v[202:205], v[134:137]
	v_mfma_f32_16x16x32_bf16 v[130:133], v[194:197], v[202:205], v[130:133]
	v_mfma_f32_16x16x32_bf16 v[118:121], v[170:173], v[210:213], v[118:121]
	v_mfma_f32_16x16x32_bf16 v[114:117], v[194:197], v[210:213], v[114:117]
	v_mfma_f32_16x16x32_bf16 v[102:105], v[170:173], v[218:221], v[102:105]
	v_mfma_f32_16x16x32_bf16 v[98:101], v[194:197], v[218:221], v[98:101]
	v_mfma_f32_16x16x32_bf16 v[86:89], v[170:173], v[226:229], v[86:89]
	v_mfma_f32_16x16x32_bf16 v[82:85], v[194:197], v[226:229], v[82:85]
	s_setprio 0
	s_barrier
	s_add_i32 s13, s13, s89
	s_mov_b32 m0, s13
	ds_read_b128 v[198:201], v186 offset:49152
	ds_read_b128 v[202:205], v186 offset:50176
	ds_read_b128 v[206:209], v186 offset:51200
	ds_read_b128 v[210:213], v186 offset:52224
	ds_read_b128 v[214:217], v186 offset:53248
	ds_read_b128 v[218:221], v186 offset:54272
	ds_read_b128 v[222:225], v186 offset:55296
	ds_read_b128 v[226:229], v186 offset:56320
	global_load_lds_dwordx4 v251, s[84:85]
	s_add_i32 m0, s13, 0x2000
	s_add_u32 s24, s84, 0x40080
	s_addc_u32 s25, s85, 0
	s_add_i32 s3, s3, s89
	global_load_lds_dwordx4 v252, s[84:85]
	s_mov_b32 m0, s3
	s_nop 0
	global_load_lds_dwordx4 v150, s[24:25]
	s_add_i32 m0, s3, 0x2000
	s_nop 0
	global_load_lds_dwordx4 v154, s[24:25]
	s_mov_b32 m0, s97
	s_nop 0
	global_load_lds_dwordx4 v253, s[86:87]
	s_mov_b32 m0, s4
	s_nop 0
	global_load_lds_dwordx4 v254, s[86:87]
	s_waitcnt vmcnt(8)
	s_waitcnt lgkmcnt(0)
	s_barrier
	s_setprio 1
	s_waitcnt lgkmcnt(0)
	v_mfma_f32_16x16x32_bf16 v[78:81], v[50:53], v[198:201], v[78:81]
	v_mfma_f32_16x16x32_bf16 v[74:77], v[66:69], v[198:201], v[74:77]
	v_mfma_f32_16x16x32_bf16 v[62:65], v[50:53], v[206:209], v[62:65]
	v_mfma_f32_16x16x32_bf16 v[58:61], v[66:69], v[206:209], v[58:61]
	v_mfma_f32_16x16x32_bf16 v[30:33], v[50:53], v[214:217], v[30:33]
	v_mfma_f32_16x16x32_bf16 v[26:29], v[66:69], v[214:217], v[26:29]
	v_mfma_f32_16x16x32_bf16 v[14:17], v[50:53], v[222:225], v[14:17]
	v_mfma_f32_16x16x32_bf16 v[10:13], v[66:69], v[222:225], v[10:13]
	v_mfma_f32_16x16x32_bf16 v[78:81], v[54:57], v[202:205], v[78:81]
	v_mfma_f32_16x16x32_bf16 v[74:77], v[70:73], v[202:205], v[74:77]
	v_mfma_f32_16x16x32_bf16 v[62:65], v[54:57], v[210:213], v[62:65]
	v_mfma_f32_16x16x32_bf16 v[58:61], v[70:73], v[210:213], v[58:61]
	v_mfma_f32_16x16x32_bf16 v[30:33], v[54:57], v[218:221], v[30:33]
	v_mfma_f32_16x16x32_bf16 v[26:29], v[70:73], v[218:221], v[26:29]
	v_mfma_f32_16x16x32_bf16 v[14:17], v[54:57], v[226:229], v[14:17]
	v_mfma_f32_16x16x32_bf16 v[10:13], v[70:73], v[226:229], v[10:13]
	s_setprio 0
	s_setprio 1
	v_mfma_f32_16x16x32_bf16 v[34:37], v[166:169], v[198:201], v[34:37]
	v_mfma_f32_16x16x32_bf16 v[70:73], v[170:173], v[202:205], v[34:37]
	v_mfma_f32_16x16x32_bf16 v[34:37], v[190:193], v[198:201], v[38:41]
	v_mfma_f32_16x16x32_bf16 v[66:69], v[194:197], v[202:205], v[34:37]
	v_mfma_f32_16x16x32_bf16 v[34:37], v[166:169], v[206:209], v[42:45]
	v_mfma_f32_16x16x32_bf16 v[54:57], v[170:173], v[210:213], v[34:37]
	v_mfma_f32_16x16x32_bf16 v[34:37], v[190:193], v[206:209], v[46:49]
	v_mfma_f32_16x16x32_bf16 v[22:25], v[166:169], v[214:217], v[22:25]
	v_mfma_f32_16x16x32_bf16 v[18:21], v[190:193], v[214:217], v[18:21]
	v_mfma_f32_16x16x32_bf16 v[6:9], v[166:169], v[222:225], v[6:9]
	v_mfma_f32_16x16x32_bf16 v[2:5], v[190:193], v[222:225], v[2:5]
	v_mfma_f32_16x16x32_bf16 v[50:53], v[194:197], v[210:213], v[34:37]
	v_mfma_f32_16x16x32_bf16 v[22:25], v[170:173], v[218:221], v[22:25]
	v_mfma_f32_16x16x32_bf16 v[18:21], v[194:197], v[218:221], v[18:21]
	v_mfma_f32_16x16x32_bf16 v[6:9], v[170:173], v[226:229], v[6:9]
	v_mfma_f32_16x16x32_bf16 v[2:5], v[194:197], v[226:229], v[2:5]
	s_setprio 0
	s_barrier
	s_add_i32 s12, s12, 2
	s_add_u32 s8, s8, 0x100
	s_addc_u32 s9, s9, 0
	s_add_u32 vcc_lo, vcc_lo, 0x100
	s_addc_u32 vcc_hi, vcc_hi, 0
	s_cmp_gt_u32 s12, 13
	s_cbranch_scc0 .LBB0_197
	s_and_b64 vcc, exec, s[74:75]
	s_cbranch_vccz .LBB0_200
	s_barrier

.LBB0_633:
	ds_read_b128 v[152:155], v148
	ds_read_b128 v[156:159], v148 offset:1024
	ds_read_b128 v[160:163], v148 offset:2048
	ds_read_b128 v[164:167], v148 offset:3072
	ds_read_b128 v[168:171], v149
	ds_read_b128 v[172:175], v149 offset:1024
	ds_read_b128 v[176:179], v149 offset:2048
	ds_read_b128 v[180:183], v149 offset:3072
	s_add_i32 s13, s12, 2
	s_add_u32 s3, s88, 0xfffc0080
	s_addc_u32 s24, s89, -1
	s_cmp_eq_u32 s81, s12
	s_cselect_b32 s93, s7, s24
	s_cselect_b32 s92, s6, s3
	s_cselect_b32 s91, s85, vcc_lo
	s_cselect_b32 s90, s84, s83
	s_add_i32 m0, s22, 0xc000
	ds_read_b128 v[184:187], v150
	ds_read_b128 v[188:191], v150 offset:1024
	ds_read_b128 v[192:195], v150 offset:2048
	ds_read_b128 v[196:199], v150 offset:3072
	ds_read_b128 v[200:203], v150 offset:4096
	ds_read_b128 v[204:207], v150 offset:5120
	ds_read_b128 v[208:211], v150 offset:6144
	ds_read_b128 v[212:215], v150 offset:7168
	global_load_lds_dwordx4 v140, s[88:89]
	s_add_i32 m0, s22, 0xe000
	s_nop 0
	global_load_lds_dwordx4 v142, s[88:89]
	s_waitcnt vmcnt(8)
	s_waitcnt lgkmcnt(0)
	s_barrier
	s_setprio 1
	s_waitcnt lgkmcnt(0)
	v_mfma_f32_16x16x32_bf16 v[126:129], v[152:155], v[184:187], v[126:129]
	v_mfma_f32_16x16x32_bf16 v[122:125], v[160:163], v[184:187], v[122:125]
	v_mfma_f32_16x16x32_bf16 v[118:121], v[152:155], v[192:195], v[118:121]
	v_mfma_f32_16x16x32_bf16 v[114:117], v[160:163], v[192:195], v[114:117]
	v_mfma_f32_16x16x32_bf16 v[106:109], v[152:155], v[200:203], v[106:109]
	v_mfma_f32_16x16x32_bf16 v[98:101], v[160:163], v[200:203], v[98:101]
	v_mfma_f32_16x16x32_bf16 v[90:93], v[152:155], v[208:211], v[90:93]
	v_mfma_f32_16x16x32_bf16 v[82:85], v[160:163], v[208:211], v[82:85]
	v_mfma_f32_16x16x32_bf16 v[126:129], v[156:159], v[188:191], v[126:129]
	v_mfma_f32_16x16x32_bf16 v[122:125], v[164:167], v[188:191], v[122:125]
	v_mfma_f32_16x16x32_bf16 v[118:121], v[156:159], v[196:199], v[118:121]
	v_mfma_f32_16x16x32_bf16 v[114:117], v[164:167], v[196:199], v[114:117]
	v_mfma_f32_16x16x32_bf16 v[106:109], v[156:159], v[204:207], v[106:109]
	v_mfma_f32_16x16x32_bf16 v[98:101], v[164:167], v[204:207], v[98:101]
	v_mfma_f32_16x16x32_bf16 v[90:93], v[156:159], v[212:215], v[90:93]
	v_mfma_f32_16x16x32_bf16 v[82:85], v[164:167], v[212:215], v[82:85]
	s_setprio 0
	s_setprio 1
	v_mfma_f32_16x16x32_bf16 v[110:113], v[168:171], v[184:187], v[110:113]
	v_mfma_f32_16x16x32_bf16 v[102:105], v[176:179], v[184:187], v[102:105]
	v_mfma_f32_16x16x32_bf16 v[94:97], v[168:171], v[192:195], v[94:97]
	v_mfma_f32_16x16x32_bf16 v[86:89], v[176:179], v[192:195], v[86:89]
	v_mfma_f32_16x16x32_bf16 v[78:81], v[168:171], v[200:203], v[78:81]
	v_mfma_f32_16x16x32_bf16 v[74:77], v[176:179], v[200:203], v[74:77]
	v_mfma_f32_16x16x32_bf16 v[70:73], v[168:171], v[208:211], v[70:73]
	v_mfma_f32_16x16x32_bf16 v[66:69], v[176:179], v[208:211], v[66:69]
	v_mfma_f32_16x16x32_bf16 v[110:113], v[172:175], v[188:191], v[110:113]
	v_mfma_f32_16x16x32_bf16 v[102:105], v[180:183], v[188:191], v[102:105]
	v_mfma_f32_16x16x32_bf16 v[94:97], v[172:175], v[196:199], v[94:97]
	v_mfma_f32_16x16x32_bf16 v[86:89], v[180:183], v[196:199], v[86:89]
	v_mfma_f32_16x16x32_bf16 v[78:81], v[172:175], v[204:207], v[78:81]
	v_mfma_f32_16x16x32_bf16 v[74:77], v[180:183], v[204:207], v[74:77]
	v_mfma_f32_16x16x32_bf16 v[70:73], v[172:175], v[212:215], v[70:73]
	v_mfma_f32_16x16x32_bf16 v[66:69], v[180:183], v[212:215], v[66:69]
	s_setprio 0
	s_barrier
	s_add_i32 s3, s60, s4
	s_mov_b32 m0, s3
	ds_read_b128 v[184:187], v150 offset:16384
	ds_read_b128 v[188:191], v150 offset:17408
	ds_read_b128 v[192:195], v150 offset:18432
	ds_read_b128 v[196:199], v150 offset:19456
	ds_read_b128 v[200:203], v150 offset:20480
	ds_read_b128 v[204:207], v150 offset:21504
	ds_read_b128 v[208:211], v150 offset:22528
	ds_read_b128 v[212:215], v150 offset:23552
	global_load_lds_dwordx4 v134, s[90:91]
	s_add_i32 m0, s3, 0x2000
	s_add_u32 s24, s90, 0x40000
	s_addc_u32 s25, s91, 0
	s_add_i32 s3, s61, s4
	global_load_lds_dwordx4 v130, s[90:91]
	s_mov_b32 m0, s3
	s_nop 0
	global_load_lds_dwordx4 v134, s[24:25]
	s_add_i32 m0, s3, 0x2000
	s_nop 0
	global_load_lds_dwordx4 v130, s[24:25]
	s_mov_b32 m0, s22
	s_nop 0
	global_load_lds_dwordx4 v136, s[92:93]
	s_mov_b32 m0, s23
	s_nop 0
	global_load_lds_dwordx4 v132, s[92:93]
	s_waitcnt vmcnt(8)
	s_waitcnt lgkmcnt(0)
	s_barrier
	s_setprio 1
	s_waitcnt lgkmcnt(0)
	v_mfma_f32_16x16x32_bf16 v[62:65], v[152:155], v[184:187], v[62:65]
	v_mfma_f32_16x16x32_bf16 v[58:61], v[160:163], v[184:187], v[58:61]
	v_mfma_f32_16x16x32_bf16 v[54:57], v[152:155], v[192:195], v[54:57]
	v_mfma_f32_16x16x32_bf16 v[50:53], v[160:163], v[192:195], v[50:53]
	v_mfma_f32_16x16x32_bf16 v[42:45], v[152:155], v[200:203], v[42:45]
	v_mfma_f32_16x16x32_bf16 v[34:37], v[160:163], v[200:203], v[34:37]
	v_mfma_f32_16x16x32_bf16 v[26:29], v[152:155], v[208:211], v[26:29]
	v_mfma_f32_16x16x32_bf16 v[18:21], v[160:163], v[208:211], v[18:21]
	v_mfma_f32_16x16x32_bf16 v[62:65], v[156:159], v[188:191], v[62:65]
	v_mfma_f32_16x16x32_bf16 v[58:61], v[164:167], v[188:191], v[58:61]
	v_mfma_f32_16x16x32_bf16 v[54:57], v[156:159], v[196:199], v[54:57]
	v_mfma_f32_16x16x32_bf16 v[50:53], v[164:167], v[196:199], v[50:53]
	v_mfma_f32_16x16x32_bf16 v[42:45], v[156:159], v[204:207], v[42:45]
	v_mfma_f32_16x16x32_bf16 v[34:37], v[164:167], v[204:207], v[34:37]
	v_mfma_f32_16x16x32_bf16 v[26:29], v[156:159], v[212:215], v[26:29]
	v_mfma_f32_16x16x32_bf16 v[18:21], v[164:167], v[212:215], v[18:21]
	s_setprio 0
	s_setprio 1
	v_mfma_f32_16x16x32_bf16 v[46:49], v[168:171], v[184:187], v[46:49]
	v_mfma_f32_16x16x32_bf16 v[38:41], v[176:179], v[184:187], v[38:41]
	v_mfma_f32_16x16x32_bf16 v[30:33], v[168:171], v[192:195], v[30:33]
	v_mfma_f32_16x16x32_bf16 v[22:25], v[176:179], v[192:195], v[22:25]
	v_mfma_f32_16x16x32_bf16 v[14:17], v[168:171], v[200:203], v[14:17]
	v_mfma_f32_16x16x32_bf16 v[10:13], v[176:179], v[200:203], v[10:13]
	v_mfma_f32_16x16x32_bf16 v[6:9], v[168:171], v[208:211], v[6:9]
	v_mfma_f32_16x16x32_bf16 v[2:5], v[176:179], v[208:211], v[2:5]
	v_mfma_f32_16x16x32_bf16 v[46:49], v[172:175], v[188:191], v[46:49]
	v_mfma_f32_16x16x32_bf16 v[38:41], v[180:183], v[188:191], v[38:41]
	v_mfma_f32_16x16x32_bf16 v[30:33], v[172:175], v[196:199], v[30:33]
	v_mfma_f32_16x16x32_bf16 v[22:25], v[180:183], v[196:199], v[22:25]
	v_mfma_f32_16x16x32_bf16 v[14:17], v[172:175], v[204:207], v[14:17]
	v_mfma_f32_16x16x32_bf16 v[10:13], v[180:183], v[204:207], v[10:13]
	v_mfma_f32_16x16x32_bf16 v[6:9], v[172:175], v[212:215], v[6:9]
	v_mfma_f32_16x16x32_bf16 v[2:5], v[180:183], v[212:215], v[2:5]
	s_setprio 0
	s_barrier
	s_add_i32 s3, 0, 0x18000
	v_add_u32_e32 v151, s3, v1
	s_add_i32 s12, 0, 0x1c000
	ds_read_b128 v[152:155], v151
	ds_read_b128 v[156:159], v151 offset:1024
	ds_read_b128 v[160:163], v151 offset:2048
	ds_read_b128 v[164:167], v151 offset:3072
	v_add_u32_e32 v151, s12, v1
	ds_read_b128 v[168:171], v151
	ds_read_b128 v[172:175], v151 offset:1024
	ds_read_b128 v[176:179], v151 offset:2048
	ds_read_b128 v[180:183], v151 offset:3072
	s_add_u32 s24, s92, 0x40000
	s_addc_u32 s25, s93, 0
	s_mov_b32 m0, s33
	ds_read_b128 v[184:187], v150 offset:32768
	ds_read_b128 v[188:191], v150 offset:33792
	ds_read_b128 v[192:195], v150 offset:34816
	ds_read_b128 v[196:199], v150 offset:35840
	ds_read_b128 v[200:203], v150 offset:36864
	ds_read_b128 v[204:207], v150 offset:37888
	ds_read_b128 v[208:211], v150 offset:38912
	ds_read_b128 v[212:215], v150 offset:39936
	global_load_lds_dwordx4 v136, s[24:25]
	s_mov_b32 m0, s44
	s_nop 0
	global_load_lds_dwordx4 v132, s[24:25]
	s_waitcnt vmcnt(8)
	s_waitcnt lgkmcnt(0)
	s_barrier
	s_setprio 1
	s_waitcnt lgkmcnt(0)
	v_mfma_f32_16x16x32_bf16 v[126:129], v[152:155], v[184:187], v[126:129]
	v_mfma_f32_16x16x32_bf16 v[122:125], v[160:163], v[184:187], v[122:125]
	v_mfma_f32_16x16x32_bf16 v[118:121], v[152:155], v[192:195], v[118:121]
	v_mfma_f32_16x16x32_bf16 v[114:117], v[160:163], v[192:195], v[114:117]
	v_mfma_f32_16x16x32_bf16 v[106:109], v[152:155], v[200:203], v[106:109]
	v_mfma_f32_16x16x32_bf16 v[98:101], v[160:163], v[200:203], v[98:101]
	v_mfma_f32_16x16x32_bf16 v[90:93], v[152:155], v[208:211], v[90:93]
	v_mfma_f32_16x16x32_bf16 v[82:85], v[160:163], v[208:211], v[82:85]
	v_mfma_f32_16x16x32_bf16 v[126:129], v[156:159], v[188:191], v[126:129]
	v_mfma_f32_16x16x32_bf16 v[122:125], v[164:167], v[188:191], v[122:125]
	v_mfma_f32_16x16x32_bf16 v[118:121], v[156:159], v[196:199], v[118:121]
	v_mfma_f32_16x16x32_bf16 v[114:117], v[164:167], v[196:199], v[114:117]
	v_mfma_f32_16x16x32_bf16 v[106:109], v[156:159], v[204:207], v[106:109]
	v_mfma_f32_16x16x32_bf16 v[98:101], v[164:167], v[204:207], v[98:101]
	v_mfma_f32_16x16x32_bf16 v[90:93], v[156:159], v[212:215], v[90:93]
	v_mfma_f32_16x16x32_bf16 v[82:85], v[164:167], v[212:215], v[82:85]
	s_setprio 0
	s_setprio 1
	v_mfma_f32_16x16x32_bf16 v[110:113], v[168:171], v[184:187], v[110:113]
	v_mfma_f32_16x16x32_bf16 v[102:105], v[176:179], v[184:187], v[102:105]
	v_mfma_f32_16x16x32_bf16 v[94:97], v[168:171], v[192:195], v[94:97]
	v_mfma_f32_16x16x32_bf16 v[86:89], v[176:179], v[192:195], v[86:89]
	v_mfma_f32_16x16x32_bf16 v[78:81], v[168:171], v[200:203], v[78:81]
	v_mfma_f32_16x16x32_bf16 v[74:77], v[176:179], v[200:203], v[74:77]
	v_mfma_f32_16x16x32_bf16 v[70:73], v[168:171], v[208:211], v[70:73]
	v_mfma_f32_16x16x32_bf16 v[66:69], v[176:179], v[208:211], v[66:69]
	v_mfma_f32_16x16x32_bf16 v[110:113], v[172:175], v[188:191], v[110:113]
	v_mfma_f32_16x16x32_bf16 v[102:105], v[180:183], v[188:191], v[102:105]
	v_mfma_f32_16x16x32_bf16 v[94:97], v[172:175], v[196:199], v[94:97]
	v_mfma_f32_16x16x32_bf16 v[86:89], v[180:183], v[196:199], v[86:89]
	v_mfma_f32_16x16x32_bf16 v[78:81], v[172:175], v[204:207], v[78:81]
	v_mfma_f32_16x16x32_bf16 v[74:77], v[180:183], v[204:207], v[74:77]
	v_mfma_f32_16x16x32_bf16 v[70:73], v[172:175], v[212:215], v[70:73]
	v_mfma_f32_16x16x32_bf16 v[66:69], v[180:183], v[212:215], v[66:69]
	s_setprio 0
	s_barrier
	s_add_i32 s3, s3, s4
	s_mov_b32 m0, s3
	ds_read_b128 v[184:187], v150 offset:49152
	ds_read_b128 v[188:191], v150 offset:50176
	ds_read_b128 v[192:195], v150 offset:51200
	ds_read_b128 v[196:199], v150 offset:52224
	ds_read_b128 v[200:203], v150 offset:53248
	ds_read_b128 v[204:207], v150 offset:54272
	ds_read_b128 v[208:211], v150 offset:55296
	ds_read_b128 v[212:215], v150 offset:56320
	global_load_lds_dwordx4 v251, s[90:91]
	s_add_i32 m0, s3, 0x2000
	s_add_u32 s24, s90, 0x40080
	s_addc_u32 s25, s91, 0
	s_add_i32 s3, s12, s4
	global_load_lds_dwordx4 v252, s[90:91]
	s_mov_b32 m0, s3
	s_nop 0
	global_load_lds_dwordx4 v134, s[24:25]
	s_add_i32 m0, s3, 0x2000
	s_nop 0
	global_load_lds_dwordx4 v130, s[24:25]
	s_mov_b32 m0, s48
	s_nop 0
	global_load_lds_dwordx4 v253, s[92:93]
	s_mov_b32 m0, s49
	s_nop 0
	global_load_lds_dwordx4 v254, s[92:93]
	s_waitcnt vmcnt(8)
	s_waitcnt lgkmcnt(0)
	s_barrier
	s_setprio 1
	s_waitcnt lgkmcnt(0)
	v_mfma_f32_16x16x32_bf16 v[62:65], v[152:155], v[184:187], v[62:65]
	v_mfma_f32_16x16x32_bf16 v[58:61], v[160:163], v[184:187], v[58:61]
	v_mfma_f32_16x16x32_bf16 v[54:57], v[152:155], v[192:195], v[54:57]
	v_mfma_f32_16x16x32_bf16 v[50:53], v[160:163], v[192:195], v[50:53]
	v_mfma_f32_16x16x32_bf16 v[42:45], v[152:155], v[200:203], v[42:45]
	v_mfma_f32_16x16x32_bf16 v[34:37], v[160:163], v[200:203], v[34:37]
	v_mfma_f32_16x16x32_bf16 v[26:29], v[152:155], v[208:211], v[26:29]
	v_mfma_f32_16x16x32_bf16 v[18:21], v[160:163], v[208:211], v[18:21]
	v_mfma_f32_16x16x32_bf16 v[62:65], v[156:159], v[188:191], v[62:65]
	v_mfma_f32_16x16x32_bf16 v[58:61], v[164:167], v[188:191], v[58:61]
	v_mfma_f32_16x16x32_bf16 v[54:57], v[156:159], v[196:199], v[54:57]
	v_mfma_f32_16x16x32_bf16 v[50:53], v[164:167], v[196:199], v[50:53]
	v_mfma_f32_16x16x32_bf16 v[42:45], v[156:159], v[204:207], v[42:45]
	v_mfma_f32_16x16x32_bf16 v[34:37], v[164:167], v[204:207], v[34:37]
	v_mfma_f32_16x16x32_bf16 v[26:29], v[156:159], v[212:215], v[26:29]
	v_mfma_f32_16x16x32_bf16 v[18:21], v[164:167], v[212:215], v[18:21]
	s_setprio 0
	s_setprio 1
	v_mfma_f32_16x16x32_bf16 v[46:49], v[168:171], v[184:187], v[46:49]
	v_mfma_f32_16x16x32_bf16 v[38:41], v[176:179], v[184:187], v[38:41]
	v_mfma_f32_16x16x32_bf16 v[30:33], v[168:171], v[192:195], v[30:33]
	v_mfma_f32_16x16x32_bf16 v[22:25], v[176:179], v[192:195], v[22:25]
	v_mfma_f32_16x16x32_bf16 v[14:17], v[168:171], v[200:203], v[14:17]
	v_mfma_f32_16x16x32_bf16 v[10:13], v[176:179], v[200:203], v[10:13]
	v_mfma_f32_16x16x32_bf16 v[6:9], v[168:171], v[208:211], v[6:9]
	v_mfma_f32_16x16x32_bf16 v[2:5], v[176:179], v[208:211], v[2:5]
	v_mfma_f32_16x16x32_bf16 v[46:49], v[172:175], v[188:191], v[46:49]
	v_mfma_f32_16x16x32_bf16 v[38:41], v[180:183], v[188:191], v[38:41]
	v_mfma_f32_16x16x32_bf16 v[30:33], v[172:175], v[196:199], v[30:33]
	v_mfma_f32_16x16x32_bf16 v[22:25], v[180:183], v[196:199], v[22:25]
	v_mfma_f32_16x16x32_bf16 v[14:17], v[172:175], v[204:207], v[14:17]
	v_mfma_f32_16x16x32_bf16 v[10:13], v[180:183], v[204:207], v[10:13]
	v_mfma_f32_16x16x32_bf16 v[6:9], v[172:175], v[212:215], v[6:9]
	v_mfma_f32_16x16x32_bf16 v[2:5], v[180:183], v[212:215], v[2:5]
	s_setprio 0
	s_barrier
	s_add_u32 s88, s88, 0x100
	s_addc_u32 s89, s89, 0
	s_add_u32 s83, s83, 0x100
	s_addc_u32 vcc_lo, vcc_lo, 0
	s_cmp_ge_i32 s13, s87
	s_mov_b32 s12, s13
	s_cbranch_scc0 .LBB0_633
	s_and_b64 vcc, exec, s[76:77]
	s_cbranch_vccz .LBB0_636
	s_barrier

.LBB0_663:
	ds_read_b128 v[98:101], v222
	ds_read_b128 v[102:105], v222 offset:1024
	ds_read_b128 v[154:157], v222 offset:2048
	ds_read_b128 v[158:161], v222 offset:3072
	ds_read_b128 v[162:165], v223
	ds_read_b128 v[166:169], v223 offset:1024
	ds_read_b128 v[170:173], v223 offset:2048
	ds_read_b128 v[174:177], v223 offset:3072
	s_add_u32 s3, s82, 0xfffc0080
	s_addc_u32 s13, s83, -1
	s_cmp_eq_u32 s12, 12
	s_cselect_b32 s87, s37, s13
	s_cselect_b32 s86, s49, s3
	s_cselect_b32 s85, s71, vcc_lo
	s_cselect_b32 s84, s73, s79
	s_add_i32 m0, s22, 0xc000
	ds_read_b128 v[178:181], v224
	ds_read_b128 v[182:185], v224 offset:1024
	ds_read_b128 v[186:189], v224 offset:2048
	ds_read_b128 v[190:193], v224 offset:3072
	ds_read_b128 v[194:197], v224 offset:4096
	ds_read_b128 v[198:201], v224 offset:5120
	ds_read_b128 v[202:205], v224 offset:6144
	ds_read_b128 v[206:209], v224 offset:7168
	global_load_lds_dwordx4 v146, s[82:83]
	s_add_i32 m0, s22, 0xe000
	s_nop 0
	global_load_lds_dwordx4 v148, s[82:83]
	s_waitcnt vmcnt(8)
	s_waitcnt lgkmcnt(0)
	s_barrier
	s_setprio 1
	s_waitcnt lgkmcnt(0)
	v_mfma_f32_16x16x32_bf16 v[134:137], v[98:101], v[178:181], v[134:137]
	v_mfma_f32_16x16x32_bf16 v[130:133], v[154:157], v[178:181], v[130:133]
	v_mfma_f32_16x16x32_bf16 v[126:129], v[98:101], v[186:189], v[126:129]
	v_mfma_f32_16x16x32_bf16 v[122:125], v[154:157], v[186:189], v[122:125]
	v_mfma_f32_16x16x32_bf16 v[118:121], v[98:101], v[194:197], v[118:121]
	v_mfma_f32_16x16x32_bf16 v[114:117], v[154:157], v[194:197], v[114:117]
	v_mfma_f32_16x16x32_bf16 v[110:113], v[98:101], v[202:205], v[110:113]
	v_mfma_f32_16x16x32_bf16 v[106:109], v[154:157], v[202:205], v[106:109]
	v_mfma_f32_16x16x32_bf16 v[134:137], v[102:105], v[182:185], v[134:137]
	v_mfma_f32_16x16x32_bf16 v[130:133], v[158:161], v[182:185], v[130:133]
	v_mfma_f32_16x16x32_bf16 v[126:129], v[102:105], v[190:193], v[126:129]
	v_mfma_f32_16x16x32_bf16 v[122:125], v[158:161], v[190:193], v[122:125]
	v_mfma_f32_16x16x32_bf16 v[118:121], v[102:105], v[198:201], v[118:121]
	v_mfma_f32_16x16x32_bf16 v[114:117], v[158:161], v[198:201], v[114:117]
	v_mfma_f32_16x16x32_bf16 v[110:113], v[102:105], v[206:209], v[110:113]
	v_mfma_f32_16x16x32_bf16 v[106:109], v[158:161], v[206:209], v[106:109]
	s_setprio 0
	s_setprio 1
	v_mfma_f32_16x16x32_bf16 v[62:65], v[162:165], v[178:181], v[62:65]
	v_mfma_f32_16x16x32_bf16 v[58:61], v[170:173], v[178:181], v[58:61]
	v_mfma_f32_16x16x32_bf16 v[54:57], v[162:165], v[186:189], v[54:57]
	v_mfma_f32_16x16x32_bf16 v[50:53], v[170:173], v[186:189], v[50:53]
	v_mfma_f32_16x16x32_bf16 v[46:49], v[162:165], v[194:197], v[46:49]
	v_mfma_f32_16x16x32_bf16 v[42:45], v[170:173], v[194:197], v[42:45]
	v_mfma_f32_16x16x32_bf16 v[38:41], v[162:165], v[202:205], v[38:41]
	v_mfma_f32_16x16x32_bf16 v[34:37], v[170:173], v[202:205], v[34:37]
	v_mfma_f32_16x16x32_bf16 v[62:65], v[166:169], v[182:185], v[62:65]
	v_mfma_f32_16x16x32_bf16 v[58:61], v[174:177], v[182:185], v[58:61]
	v_mfma_f32_16x16x32_bf16 v[54:57], v[166:169], v[190:193], v[54:57]
	v_mfma_f32_16x16x32_bf16 v[50:53], v[174:177], v[190:193], v[50:53]
	v_mfma_f32_16x16x32_bf16 v[46:49], v[166:169], v[198:201], v[46:49]
	v_mfma_f32_16x16x32_bf16 v[42:45], v[174:177], v[198:201], v[42:45]
	v_mfma_f32_16x16x32_bf16 v[38:41], v[166:169], v[206:209], v[38:41]
	v_mfma_f32_16x16x32_bf16 v[34:37], v[174:177], v[206:209], v[34:37]
	s_setprio 0
	s_barrier
	s_add_i32 s3, s93, s5
	s_mov_b32 m0, s3
	ds_read_b128 v[178:181], v224 offset:16384
	ds_read_b128 v[182:185], v224 offset:17408
	ds_read_b128 v[186:189], v224 offset:18432
	ds_read_b128 v[190:193], v224 offset:19456
	ds_read_b128 v[194:197], v224 offset:20480
	ds_read_b128 v[198:201], v224 offset:21504
	ds_read_b128 v[202:205], v224 offset:22528
	ds_read_b128 v[206:209], v224 offset:23552
	global_load_lds_dwordx4 v140, s[84:85]
	s_add_i32 m0, s3, 0x2000
	s_add_u32 s24, s84, 0x40000
	s_addc_u32 s25, s85, 0
	s_add_i32 s3, s48, s5
	global_load_lds_dwordx4 v144, s[84:85]
	s_mov_b32 m0, s3
	s_nop 0
	global_load_lds_dwordx4 v140, s[24:25]
	s_add_i32 m0, s3, 0x2000
	s_nop 0
	global_load_lds_dwordx4 v144, s[24:25]
	s_mov_b32 m0, s22
	s_nop 0
	global_load_lds_dwordx4 v138, s[86:87]
	s_mov_b32 m0, s23
	s_nop 0
	global_load_lds_dwordx4 v142, s[86:87]
	s_waitcnt vmcnt(8)
	s_waitcnt lgkmcnt(0)
	s_barrier
	s_setprio 1
	s_waitcnt lgkmcnt(0)
	v_mfma_f32_16x16x32_bf16 v[94:97], v[98:101], v[178:181], v[94:97]
	v_mfma_f32_16x16x32_bf16 v[90:93], v[154:157], v[178:181], v[90:93]
	v_mfma_f32_16x16x32_bf16 v[86:89], v[98:101], v[186:189], v[86:89]
	v_mfma_f32_16x16x32_bf16 v[82:85], v[154:157], v[186:189], v[82:85]
	v_mfma_f32_16x16x32_bf16 v[78:81], v[98:101], v[194:197], v[78:81]
	v_mfma_f32_16x16x32_bf16 v[74:77], v[154:157], v[194:197], v[74:77]
	v_mfma_f32_16x16x32_bf16 v[70:73], v[98:101], v[202:205], v[70:73]
	v_mfma_f32_16x16x32_bf16 v[66:69], v[154:157], v[202:205], v[66:69]
	v_mfma_f32_16x16x32_bf16 v[94:97], v[102:105], v[182:185], v[94:97]
	v_mfma_f32_16x16x32_bf16 v[90:93], v[158:161], v[182:185], v[90:93]
	v_mfma_f32_16x16x32_bf16 v[86:89], v[102:105], v[190:193], v[86:89]
	v_mfma_f32_16x16x32_bf16 v[82:85], v[158:161], v[190:193], v[82:85]
	v_mfma_f32_16x16x32_bf16 v[78:81], v[102:105], v[198:201], v[78:81]
	v_mfma_f32_16x16x32_bf16 v[74:77], v[158:161], v[198:201], v[74:77]
	v_mfma_f32_16x16x32_bf16 v[70:73], v[102:105], v[206:209], v[70:73]
	v_mfma_f32_16x16x32_bf16 v[66:69], v[158:161], v[206:209], v[66:69]
	s_setprio 0
	s_setprio 1
	v_mfma_f32_16x16x32_bf16 v[30:33], v[162:165], v[178:181], v[30:33]
	v_mfma_f32_16x16x32_bf16 v[26:29], v[170:173], v[178:181], v[26:29]
	v_mfma_f32_16x16x32_bf16 v[22:25], v[162:165], v[186:189], v[22:25]
	v_mfma_f32_16x16x32_bf16 v[18:21], v[170:173], v[186:189], v[18:21]
	v_mfma_f32_16x16x32_bf16 v[14:17], v[162:165], v[194:197], v[14:17]
	v_mfma_f32_16x16x32_bf16 v[10:13], v[170:173], v[194:197], v[10:13]
	v_mfma_f32_16x16x32_bf16 v[6:9], v[162:165], v[202:205], v[6:9]
	v_mfma_f32_16x16x32_bf16 v[2:5], v[170:173], v[202:205], v[2:5]
	v_mfma_f32_16x16x32_bf16 v[30:33], v[166:169], v[182:185], v[30:33]
	v_mfma_f32_16x16x32_bf16 v[26:29], v[174:177], v[182:185], v[26:29]
	v_mfma_f32_16x16x32_bf16 v[22:25], v[166:169], v[190:193], v[22:25]
	v_mfma_f32_16x16x32_bf16 v[18:21], v[174:177], v[190:193], v[18:21]
	v_mfma_f32_16x16x32_bf16 v[14:17], v[166:169], v[198:201], v[14:17]
	v_mfma_f32_16x16x32_bf16 v[10:13], v[174:177], v[198:201], v[10:13]
	v_mfma_f32_16x16x32_bf16 v[6:9], v[166:169], v[206:209], v[6:9]
	v_mfma_f32_16x16x32_bf16 v[2:5], v[174:177], v[206:209], v[2:5]
	s_setprio 0
	s_barrier
	s_add_i32 s3, 0, 0x18000
	s_add_i32 s13, 0, 0x1c000
	v_add_u32_e32 v158, s3, v220
	v_add_u32_e32 v174, s13, v220
	ds_read_b128 v[98:101], v158
	ds_read_b128 v[102:105], v158 offset:1024
	ds_read_b128 v[154:157], v158 offset:2048
	ds_read_b128 v[158:161], v158 offset:3072
	ds_read_b128 v[162:165], v174
	ds_read_b128 v[166:169], v174 offset:1024
	ds_read_b128 v[170:173], v174 offset:2048
	ds_read_b128 v[174:177], v174 offset:3072
	s_add_u32 s24, s86, 0x40000
	s_addc_u32 s25, s87, 0
	s_mov_b32 m0, s33
	ds_read_b128 v[178:181], v224 offset:32768
	ds_read_b128 v[182:185], v224 offset:33792
	ds_read_b128 v[186:189], v224 offset:34816
	ds_read_b128 v[190:193], v224 offset:35840
	ds_read_b128 v[194:197], v224 offset:36864
	ds_read_b128 v[198:201], v224 offset:37888
	ds_read_b128 v[202:205], v224 offset:38912
	ds_read_b128 v[206:209], v224 offset:39936
	global_load_lds_dwordx4 v138, s[24:25]
	s_mov_b32 m0, s44
	s_nop 0
	global_load_lds_dwordx4 v142, s[24:25]
	s_waitcnt vmcnt(8)
	s_waitcnt lgkmcnt(0)
	s_barrier
	s_setprio 1
	s_waitcnt lgkmcnt(0)
	v_mfma_f32_16x16x32_bf16 v[134:137], v[98:101], v[178:181], v[134:137]
	v_mfma_f32_16x16x32_bf16 v[130:133], v[154:157], v[178:181], v[130:133]
	v_mfma_f32_16x16x32_bf16 v[126:129], v[98:101], v[186:189], v[126:129]
	v_mfma_f32_16x16x32_bf16 v[122:125], v[154:157], v[186:189], v[122:125]
	v_mfma_f32_16x16x32_bf16 v[118:121], v[98:101], v[194:197], v[118:121]
	v_mfma_f32_16x16x32_bf16 v[114:117], v[154:157], v[194:197], v[114:117]
	v_mfma_f32_16x16x32_bf16 v[110:113], v[98:101], v[202:205], v[110:113]
	v_mfma_f32_16x16x32_bf16 v[106:109], v[154:157], v[202:205], v[106:109]
	v_mfma_f32_16x16x32_bf16 v[134:137], v[102:105], v[182:185], v[134:137]
	v_mfma_f32_16x16x32_bf16 v[130:133], v[158:161], v[182:185], v[130:133]
	v_mfma_f32_16x16x32_bf16 v[126:129], v[102:105], v[190:193], v[126:129]
	v_mfma_f32_16x16x32_bf16 v[122:125], v[158:161], v[190:193], v[122:125]
	v_mfma_f32_16x16x32_bf16 v[118:121], v[102:105], v[198:201], v[118:121]
	v_mfma_f32_16x16x32_bf16 v[114:117], v[158:161], v[198:201], v[114:117]
	v_mfma_f32_16x16x32_bf16 v[110:113], v[102:105], v[206:209], v[110:113]
	v_mfma_f32_16x16x32_bf16 v[106:109], v[158:161], v[206:209], v[106:109]
	s_setprio 0
	s_setprio 1
	v_mfma_f32_16x16x32_bf16 v[62:65], v[162:165], v[178:181], v[62:65]
	v_mfma_f32_16x16x32_bf16 v[58:61], v[170:173], v[178:181], v[58:61]
	v_mfma_f32_16x16x32_bf16 v[54:57], v[162:165], v[186:189], v[54:57]
	v_mfma_f32_16x16x32_bf16 v[50:53], v[170:173], v[186:189], v[50:53]
	v_mfma_f32_16x16x32_bf16 v[46:49], v[162:165], v[194:197], v[46:49]
	v_mfma_f32_16x16x32_bf16 v[42:45], v[170:173], v[194:197], v[42:45]
	v_mfma_f32_16x16x32_bf16 v[38:41], v[162:165], v[202:205], v[38:41]
	v_mfma_f32_16x16x32_bf16 v[34:37], v[170:173], v[202:205], v[34:37]
	v_mfma_f32_16x16x32_bf16 v[62:65], v[166:169], v[182:185], v[62:65]
	v_mfma_f32_16x16x32_bf16 v[58:61], v[174:177], v[182:185], v[58:61]
	v_mfma_f32_16x16x32_bf16 v[54:57], v[166:169], v[190:193], v[54:57]
	v_mfma_f32_16x16x32_bf16 v[50:53], v[174:177], v[190:193], v[50:53]
	v_mfma_f32_16x16x32_bf16 v[46:49], v[166:169], v[198:201], v[46:49]
	v_mfma_f32_16x16x32_bf16 v[42:45], v[174:177], v[198:201], v[42:45]
	v_mfma_f32_16x16x32_bf16 v[38:41], v[166:169], v[206:209], v[38:41]
	v_mfma_f32_16x16x32_bf16 v[34:37], v[174:177], v[206:209], v[34:37]
	s_setprio 0
	s_barrier
	s_add_i32 s3, s3, s5
	s_mov_b32 m0, s3
	ds_read_b128 v[178:181], v224 offset:49152
	ds_read_b128 v[182:185], v224 offset:50176
	ds_read_b128 v[186:189], v224 offset:51200
	ds_read_b128 v[190:193], v224 offset:52224
	ds_read_b128 v[194:197], v224 offset:53248
	ds_read_b128 v[198:201], v224 offset:54272
	ds_read_b128 v[202:205], v224 offset:55296
	ds_read_b128 v[206:209], v224 offset:56320
	global_load_lds_dwordx4 v251, s[84:85]
	s_add_i32 m0, s3, 0x2000
	s_add_u32 s24, s84, 0x40080
	s_addc_u32 s25, s85, 0
	s_add_i32 s3, s13, s5
	global_load_lds_dwordx4 v252, s[84:85]
	s_mov_b32 m0, s3
	s_nop 0
	global_load_lds_dwordx4 v140, s[24:25]
	s_add_i32 m0, s3, 0x2000
	s_nop 0
	global_load_lds_dwordx4 v144, s[24:25]
	s_mov_b32 m0, s90
	s_nop 0
	global_load_lds_dwordx4 v253, s[86:87]
	s_mov_b32 m0, s91
	s_nop 0
	global_load_lds_dwordx4 v254, s[86:87]
	s_waitcnt vmcnt(8)
	s_waitcnt lgkmcnt(0)
	s_barrier
	s_setprio 1
	s_waitcnt lgkmcnt(0)
	v_mfma_f32_16x16x32_bf16 v[94:97], v[98:101], v[178:181], v[94:97]
	v_mfma_f32_16x16x32_bf16 v[90:93], v[154:157], v[178:181], v[90:93]
	v_mfma_f32_16x16x32_bf16 v[86:89], v[98:101], v[186:189], v[86:89]
	v_mfma_f32_16x16x32_bf16 v[82:85], v[154:157], v[186:189], v[82:85]
	v_mfma_f32_16x16x32_bf16 v[78:81], v[98:101], v[194:197], v[78:81]
	v_mfma_f32_16x16x32_bf16 v[74:77], v[154:157], v[194:197], v[74:77]
	v_mfma_f32_16x16x32_bf16 v[70:73], v[98:101], v[202:205], v[70:73]
	v_mfma_f32_16x16x32_bf16 v[66:69], v[154:157], v[202:205], v[66:69]
	v_mfma_f32_16x16x32_bf16 v[94:97], v[102:105], v[182:185], v[94:97]
	v_mfma_f32_16x16x32_bf16 v[90:93], v[158:161], v[182:185], v[90:93]
	v_mfma_f32_16x16x32_bf16 v[86:89], v[102:105], v[190:193], v[86:89]
	v_mfma_f32_16x16x32_bf16 v[82:85], v[158:161], v[190:193], v[82:85]
	v_mfma_f32_16x16x32_bf16 v[78:81], v[102:105], v[198:201], v[78:81]
	v_mfma_f32_16x16x32_bf16 v[74:77], v[158:161], v[198:201], v[74:77]
	v_mfma_f32_16x16x32_bf16 v[70:73], v[102:105], v[206:209], v[70:73]
	v_mfma_f32_16x16x32_bf16 v[66:69], v[158:161], v[206:209], v[66:69]
	s_setprio 0
	s_setprio 1
	v_mfma_f32_16x16x32_bf16 v[30:33], v[162:165], v[178:181], v[30:33]
	v_mfma_f32_16x16x32_bf16 v[26:29], v[170:173], v[178:181], v[26:29]
	v_mfma_f32_16x16x32_bf16 v[22:25], v[162:165], v[186:189], v[22:25]
	v_mfma_f32_16x16x32_bf16 v[18:21], v[170:173], v[186:189], v[18:21]
	v_mfma_f32_16x16x32_bf16 v[14:17], v[162:165], v[194:197], v[14:17]
	v_mfma_f32_16x16x32_bf16 v[10:13], v[170:173], v[194:197], v[10:13]
	v_mfma_f32_16x16x32_bf16 v[6:9], v[162:165], v[202:205], v[6:9]
	v_mfma_f32_16x16x32_bf16 v[2:5], v[170:173], v[202:205], v[2:5]
	v_mfma_f32_16x16x32_bf16 v[30:33], v[166:169], v[182:185], v[30:33]
	v_mfma_f32_16x16x32_bf16 v[26:29], v[174:177], v[182:185], v[26:29]
	v_mfma_f32_16x16x32_bf16 v[22:25], v[166:169], v[190:193], v[22:25]
	v_mfma_f32_16x16x32_bf16 v[18:21], v[174:177], v[190:193], v[18:21]
	v_mfma_f32_16x16x32_bf16 v[14:17], v[166:169], v[198:201], v[14:17]
	v_mfma_f32_16x16x32_bf16 v[10:13], v[174:177], v[198:201], v[10:13]
	v_mfma_f32_16x16x32_bf16 v[6:9], v[166:169], v[206:209], v[6:9]
	v_mfma_f32_16x16x32_bf16 v[2:5], v[174:177], v[206:209], v[2:5]
	s_setprio 0
	s_barrier
	s_add_i32 s12, s12, 2
	s_add_u32 s82, s82, 0x100
	s_addc_u32 s83, s83, 0
	s_add_u32 s79, s79, 0x100
	s_addc_u32 vcc_lo, vcc_lo, 0
	s_cmp_gt_u32 s12, 13
	s_cbranch_scc0 .LBB0_663
	s_ashr_i32 s3, s78, 3
	s_ashr_i32 s79, s78, 31
	s_mul_hi_i32 s37, s3, 0x6000
	s_mulk_i32 s3, 0x6000
	s_add_u32 s12, s88, s3
	s_addc_u32 s13, s89, s37
	s_lshl_b64 s[24:25], s[78:79], 20
	s_add_u32 s24, s16, s24
	s_addc_u32 s25, s17, s25
	s_lshl_b64 s[82:83], s[78:79], 19
	s_add_u32 s82, s61, s82
	s_addc_u32 s83, s62, s83
	v_lshl_or_b32 v154, s80, 8, v221
	s_add_u32 s84, s63, s3
	v_ashrrev_i32_e32 v155, 31, v154
	v_mov_b32_e32 v98, v1
	s_addc_u32 s85, s81, s37
	v_lshlrev_b64 v[158:159], 2, v[154:155]
	v_lshl_add_u64 v[160:161], s[84:85], 0, v[158:159]
	v_lshl_add_u64 v[162:163], s[30:31], 0, v[158:159]
	v_lshl_add_u64 v[156:157], s[12:13], 0, v[158:159]
	v_add_u32_e32 v216, s60, v98
	global_load_dwordx4 v[98:101], v[160:161], off offset:16
	global_load_dwordx4 v[102:105], v[160:161], off
	global_load_dwordx4 v[164:167], v[162:163], off offset:16
	global_load_dwordx4 v[168:171], v[162:163], off
	global_load_dwordx4 v[172:175], v[156:157], off offset:16
	global_load_dwordx4 v[176:179], v[156:157], off
	v_ashrrev_i32_e32 v217, 31, v216
	v_lshl_add_u64 v[214:215], s[24:25], 0, v[158:159]
	v_lshlrev_b64 v[186:187], 1, v[154:155]
	v_lshlrev_b64 v[154:155], 12, v[216:217]
	v_lshl_add_u64 v[198:199], s[82:83], 0, v[186:187]
	s_lshl_b32 s49, s78, 8
	v_add_u32_e32 v218, 0x90, v216
	v_ashrrev_i32_e32 v219, 31, v218
	v_add_u32_e32 v204, 0xa0, v216
	v_ashrrev_i32_e32 v205, 31, v204
	s_waitcnt vmcnt(0)
	v_pk_add_f32 v[178:179], v[178:179], 1.0 op_sel_hi:[1,0]
	v_pk_add_f32 v[176:177], v[176:177], 1.0 op_sel_hi:[1,0]
	v_pk_mul_f32 v[188:189], v[170:171], v[178:179]
	v_pk_add_f32 v[170:171], v[172:173], 1.0 op_sel_hi:[1,0]
	v_pk_mul_f32 v[190:191], v[168:169], v[176:177]
	v_pk_add_f32 v[168:169], v[174:175], 1.0 op_sel_hi:[1,0]
	v_pk_mul_f32 v[194:195], v[164:165], v[170:171]
	v_lshl_add_u64 v[164:165], v[214:215], 0, v[154:155]
	v_pk_mul_f32 v[192:193], v[166:167], v[168:169]
	global_load_dwordx4 v[166:169], v[164:165], off offset:16 nt
	global_load_dwordx4 v[170:173], v[164:165], off nt
	v_add_u32_e32 v154, 16, v216
	v_ashrrev_i32_e32 v155, 31, v154
	v_lshlrev_b64 v[158:159], 12, v[154:155]
	v_lshl_add_u64 v[158:159], v[214:215], 0, v[158:159]
	global_load_dwordx4 v[174:177], v[158:159], off offset:16 nt
	global_load_dwordx4 v[178:181], v[158:159], off nt
	s_waitcnt vmcnt(3)
	v_pk_fma_f32 v[166:167], v[130:131], v[98:99], v[166:167]
	s_waitcnt vmcnt(2)
	v_pk_fma_f32 v[136:137], v[136:137], v[104:105], v[172:173]
	v_pk_fma_f32 v[134:135], v[134:135], v[102:103], v[170:171]
	v_pk_fma_f32 v[170:171], v[132:133], v[100:101], v[168:169]
	v_lshlrev_b64 v[168:169], 11, v[216:217]
	v_cvt_pk_f16_f32 v133, v170, v171
	v_cvt_pk_f16_f32 v131, v136, v137
	v_cvt_pk_f16_f32 v132, v166, v167
	v_cvt_pk_f16_f32 v130, v134, v135
	v_lshl_add_u64 v[168:169], v[198:199], 0, v[168:169]
	global_store_dwordx4 v[168:169], v[130:133], off
	s_waitcnt vmcnt(1)
	v_pk_fma_f32 v[128:129], v[128:129], v[104:105], v[180:181]
	v_pk_fma_f32 v[126:127], v[126:127], v[102:103], v[178:179]
	v_mul_f32_e32 v130, v135, v135
	v_mul_f32_e32 v131, v137, v137
	v_fmac_f32_e32 v130, v134, v134
	v_fmac_f32_e32 v131, v136, v136
	v_add_f32_e32 v130, v130, v131
	v_mul_f32_e32 v131, v167, v167
	v_mul_f32_e32 v132, v171, v171
	v_fmac_f32_e32 v131, v166, v166
	v_fmac_f32_e32 v132, v170, v170
	v_add_f32_e32 v131, v131, v132
	v_add_f32_e32 v226, v130, v131
	v_pk_mul_f32 v[130:131], v[188:189], v[136:137]
	v_pk_mul_f32 v[132:133], v[190:191], v[134:135]
	v_pk_mul_f32 v[136:137], v[192:193], v[170:171]
	v_cvt_pk_bf16_f32 v132, v132, v133
	v_cvt_pk_bf16_f32 v133, v130, v131
	v_add_u32_e32 v130, s49, v216
	v_pk_mul_f32 v[134:135], v[194:195], v[166:167]
	v_ashrrev_i32_e32 v131, 31, v130
	v_cvt_pk_bf16_f32 v134, v134, v135
	v_cvt_pk_bf16_f32 v135, v136, v137
	v_lshlrev_b64 v[136:137], 11, v[130:131]
	v_lshl_add_u64 v[136:137], s[0:1], 0, v[136:137]
	v_lshl_add_u64 v[170:171], v[136:137], 0, v[186:187]
	v_pk_fma_f32 v[124:125], v[124:125], v[100:101], v[176:177]
	v_pk_fma_f32 v[122:123], v[122:123], v[98:99], v[174:175]
	v_lshlrev_b64 v[136:137], 11, v[154:155]
	global_store_dwordx4 v[170:171], v[132:135], off
	v_lshl_add_u64 v[172:173], v[198:199], 0, v[136:137]
	v_pk_mul_f32 v[136:137], v[192:193], v[124:125]
	v_cvt_pk_f16_f32 v135, v124, v125
	v_cvt_pk_f16_f32 v133, v128, v129
	v_cvt_pk_f16_f32 v134, v122, v123
	v_cvt_pk_f16_f32 v132, v126, v127
	global_store_dwordx4 v[172:173], v[132:135], off
	v_pk_mul_f32 v[166:167], v[194:195], v[122:123]
	s_nop 0
	v_pk_mul_f32 v[134:135], v[188:189], v[128:129]
	v_pk_mul_f32 v[132:133], v[190:191], v[126:127]
	s_nop 0
	v_cvt_pk_bf16_f32 v132, v132, v133
	v_cvt_pk_bf16_f32 v133, v134, v135
	v_cvt_pk_bf16_f32 v134, v166, v167
	v_cvt_pk_bf16_f32 v135, v136, v137
	v_add_u32_e32 v136, s49, v154
	v_ashrrev_i32_e32 v137, 31, v136
	v_lshlrev_b64 v[136:137], 11, v[136:137]
	v_lshl_add_u64 v[136:137], s[0:1], 0, v[136:137]
	v_lshl_add_u64 v[178:179], v[136:137], 0, v[186:187]
	v_add_u32_e32 v136, 32, v216
	v_ashrrev_i32_e32 v137, 31, v136
	global_store_dwordx4 v[178:179], v[132:135], off
	v_add_u32_e32 v154, 48, v216
	v_ashrrev_i32_e32 v155, 31, v154
	v_lshlrev_b64 v[132:133], 12, v[136:137]
	v_lshl_add_u64 v[180:181], v[214:215], 0, v[132:133]
	global_load_dwordx4 v[132:135], v[180:181], off offset:16 nt
	global_load_dwordx4 v[174:177], v[180:181], off nt
	v_lshlrev_b64 v[166:167], 12, v[154:155]
	v_lshl_add_u64 v[182:183], v[214:215], 0, v[166:167]
	global_load_dwordx4 v[200:203], v[182:183], off offset:16 nt
	global_load_dwordx4 v[206:209], v[182:183], off nt
	v_lshlrev_b64 v[166:167], 11, v[136:137]
	v_add_u32_e32 v136, s49, v136
	v_ashrrev_i32_e32 v137, 31, v136
	v_lshlrev_b64 v[136:137], 11, v[136:137]
	v_lshl_add_u64 v[136:137], s[0:1], 0, v[136:137]
	v_lshl_add_u64 v[184:185], v[136:137], 0, v[186:187]
	v_lshlrev_b64 v[136:137], 11, v[154:155]
	s_waitcnt vmcnt(3)
	v_pk_fma_f32 v[116:117], v[116:117], v[100:101], v[134:135]
	s_waitcnt vmcnt(2)
	v_pk_fma_f32 v[120:121], v[120:121], v[104:105], v[176:177]
	v_pk_fma_f32 v[118:119], v[118:119], v[102:103], v[174:175]
	v_pk_fma_f32 v[114:115], v[114:115], v[98:99], v[132:133]
	v_cvt_pk_f16_f32 v135, v116, v117
	v_cvt_pk_f16_f32 v133, v120, v121
	v_cvt_pk_f16_f32 v134, v114, v115
	v_cvt_pk_f16_f32 v132, v118, v119
	v_lshl_add_u64 v[176:177], v[198:199], 0, v[166:167]
	global_store_dwordx4 v[176:177], v[132:135], off
	v_pk_mul_f32 v[166:167], v[192:193], v[116:117]
	v_pk_mul_f32 v[174:175], v[194:195], v[114:115]
	v_pk_mul_f32 v[134:135], v[188:189], v[120:121]
	v_pk_mul_f32 v[132:133], v[190:191], v[118:119]
	s_waitcnt vmcnt(1)
	v_pk_fma_f32 v[112:113], v[112:113], v[104:105], v[208:209]
	v_cvt_pk_bf16_f32 v132, v132, v133
	v_cvt_pk_bf16_f32 v133, v134, v135
	v_cvt_pk_bf16_f32 v134, v174, v175
	v_cvt_pk_bf16_f32 v135, v166, v167
	v_pk_fma_f32 v[110:111], v[110:111], v[102:103], v[206:207]
	v_pk_fma_f32 v[108:109], v[108:109], v[100:101], v[202:203]
	v_pk_fma_f32 v[106:107], v[106:107], v[98:99], v[200:201]
	global_store_dwordx4 v[184:185], v[132:135], off
	v_lshl_add_u64 v[174:175], v[198:199], 0, v[136:137]
	v_pk_mul_f32 v[136:137], v[192:193], v[108:109]
	v_cvt_pk_f16_f32 v135, v108, v109
	v_cvt_pk_f16_f32 v133, v112, v113
	v_cvt_pk_f16_f32 v134, v106, v107
	v_cvt_pk_f16_f32 v132, v110, v111
	global_store_dwordx4 v[174:175], v[132:135], off
	v_pk_mul_f32 v[166:167], v[194:195], v[106:107]
	v_add_u32_e32 v206, 0x80, v216
	v_pk_mul_f32 v[134:135], v[188:189], v[112:113]
	v_pk_mul_f32 v[132:133], v[190:191], v[110:111]
	v_ashrrev_i32_e32 v207, 31, v206
	v_cvt_pk_bf16_f32 v132, v132, v133
	v_cvt_pk_bf16_f32 v133, v134, v135
	v_cvt_pk_bf16_f32 v134, v166, v167
	v_cvt_pk_bf16_f32 v135, v136, v137
	v_add_u32_e32 v136, s49, v154
	v_ashrrev_i32_e32 v137, 31, v136
	v_lshlrev_b64 v[136:137], 11, v[136:137]
	v_lshl_add_u64 v[136:137], s[0:1], 0, v[136:137]
	v_lshl_add_u64 v[166:167], v[136:137], 0, v[186:187]
	global_store_dwordx4 v[166:167], v[132:135], off
	v_lshlrev_b64 v[136:137], 12, v[218:219]
	v_lshl_add_u64 v[210:211], v[214:215], 0, v[136:137]
	v_lshlrev_b64 v[132:133], 12, v[206:207]
	v_lshl_add_u64 v[196:197], v[214:215], 0, v[132:133]
	global_load_dwordx4 v[200:203], v[196:197], off offset:16 nt
	global_load_dwordx4 v[132:135], v[196:197], off nt
	global_load_dwordx4 v[228:231], v[210:211], off offset:16 nt
	global_load_dwordx4 v[232:235], v[210:211], off nt
	s_waitcnt vmcnt(2)
	v_pk_fma_f32 v[136:137], v[96:97], v[104:105], v[134:135]
	v_pk_fma_f32 v[154:155], v[94:95], v[102:103], v[132:133]
	v_pk_fma_f32 v[132:133], v[92:93], v[100:101], v[202:203]
	v_pk_fma_f32 v[134:135], v[90:91], v[98:99], v[200:201]
	v_lshlrev_b64 v[94:95], 11, v[206:207]
	v_cvt_pk_f16_f32 v93, v132, v133
	v_cvt_pk_f16_f32 v91, v136, v137
	v_cvt_pk_f16_f32 v92, v134, v135
	v_cvt_pk_f16_f32 v90, v154, v155
	v_lshl_add_u64 v[208:209], v[198:199], 0, v[94:95]
	global_store_dwordx4 v[208:209], v[90:93], off
	v_pk_mul_f32 v[94:95], v[192:193], v[132:133]
	v_pk_mul_f32 v[96:97], v[194:195], v[134:135]
	v_pk_mul_f32 v[92:93], v[188:189], v[136:137]
	v_pk_mul_f32 v[90:91], v[190:191], v[154:155]
	s_nop 0
	v_cvt_pk_bf16_f32 v90, v90, v91
	v_cvt_pk_bf16_f32 v91, v92, v93
	v_cvt_pk_bf16_f32 v92, v96, v97
	v_cvt_pk_bf16_f32 v93, v94, v95
	v_add_u32_e32 v94, s49, v206
	v_ashrrev_i32_e32 v95, 31, v94
	v_lshlrev_b64 v[94:95], 11, v[94:95]
	v_lshl_add_u64 v[94:95], s[0:1], 0, v[94:95]
	v_lshl_add_u64 v[212:213], v[94:95], 0, v[186:187]
	global_store_dwordx4 v[212:213], v[90:93], off
	s_waitcnt vmcnt(2)
	v_pk_fma_f32 v[94:95], v[88:89], v[104:105], v[234:235]
	v_pk_fma_f32 v[96:97], v[86:87], v[102:103], v[232:233]
	v_pk_fma_f32 v[90:91], v[84:85], v[100:101], v[230:231]
	v_pk_fma_f32 v[92:93], v[82:83], v[98:99], v[228:229]
	v_lshlrev_b64 v[86:87], 11, v[218:219]
	v_cvt_pk_f16_f32 v85, v90, v91
	v_cvt_pk_f16_f32 v83, v94, v95
	v_cvt_pk_f16_f32 v84, v92, v93
	v_cvt_pk_f16_f32 v82, v96, v97
	v_lshl_add_u64 v[206:207], v[198:199], 0, v[86:87]
	global_store_dwordx4 v[206:207], v[82:85], off
	v_pk_mul_f32 v[86:87], v[192:193], v[90:91]
	v_pk_mul_f32 v[88:89], v[194:195], v[92:93]
	v_pk_mul_f32 v[84:85], v[188:189], v[94:95]
	v_pk_mul_f32 v[82:83], v[190:191], v[96:97]
	s_nop 0
	v_cvt_pk_bf16_f32 v82, v82, v83
	v_cvt_pk_bf16_f32 v83, v84, v85
	v_cvt_pk_bf16_f32 v84, v88, v89
	v_cvt_pk_bf16_f32 v85, v86, v87
	v_add_u32_e32 v86, s49, v218
	v_ashrrev_i32_e32 v87, 31, v86
	v_lshlrev_b64 v[86:87], 11, v[86:87]
	v_lshl_add_u64 v[86:87], s[0:1], 0, v[86:87]
	v_lshl_add_u64 v[202:203], v[86:87], 0, v[186:187]
	global_store_dwordx4 v[202:203], v[82:85], off
	v_add_u32_e32 v218, 0xb0, v216
	v_ashrrev_i32_e32 v219, 31, v218
	v_lshlrev_b64 v[82:83], 12, v[204:205]
	v_lshl_add_u64 v[200:201], v[214:215], 0, v[82:83]
	global_load_dwordx4 v[82:85], v[200:201], off offset:16 nt
	global_load_dwordx4 v[86:89], v[200:201], off nt
	v_lshlrev_b64 v[216:217], 12, v[218:219]
	v_lshl_add_u64 v[214:215], v[214:215], 0, v[216:217]
	global_load_dwordx4 v[228:231], v[214:215], off offset:16 nt
	global_load_dwordx4 v[232:235], v[214:215], off nt
	s_waitcnt vmcnt(3)
	v_pk_fma_f32 v[76:77], v[76:77], v[100:101], v[84:85]
	s_waitcnt vmcnt(2)
	v_pk_fma_f32 v[80:81], v[80:81], v[104:105], v[88:89]
	v_pk_fma_f32 v[78:79], v[78:79], v[102:103], v[86:87]
	v_pk_fma_f32 v[74:75], v[74:75], v[98:99], v[82:83]
	v_lshlrev_b64 v[86:87], 11, v[204:205]
	v_cvt_pk_f16_f32 v85, v76, v77
	v_cvt_pk_f16_f32 v83, v80, v81
	v_cvt_pk_f16_f32 v84, v74, v75
	v_cvt_pk_f16_f32 v82, v78, v79
	v_lshl_add_u64 v[216:217], v[198:199], 0, v[86:87]
	global_store_dwordx4 v[216:217], v[82:85], off
	v_pk_mul_f32 v[86:87], v[192:193], v[76:77]
	v_pk_mul_f32 v[88:89], v[194:195], v[74:75]
	v_pk_mul_f32 v[84:85], v[188:189], v[80:81]
	v_pk_mul_f32 v[82:83], v[190:191], v[78:79]
	s_nop 0
	v_cvt_pk_bf16_f32 v82, v82, v83
	v_cvt_pk_bf16_f32 v83, v84, v85
	v_cvt_pk_bf16_f32 v84, v88, v89
	v_cvt_pk_bf16_f32 v85, v86, v87
	v_add_u32_e32 v86, s49, v204
	v_ashrrev_i32_e32 v87, 31, v86
	v_lshlrev_b64 v[86:87], 11, v[86:87]
	v_lshl_add_u64 v[86:87], s[0:1], 0, v[86:87]
	v_lshl_add_u64 v[204:205], v[86:87], 0, v[186:187]
	global_store_dwordx4 v[204:205], v[82:85], off
	s_waitcnt vmcnt(2)
	v_pk_fma_f32 v[86:87], v[72:73], v[104:105], v[234:235]
	v_pk_fma_f32 v[88:89], v[70:71], v[102:103], v[232:233]
	v_pk_fma_f32 v[82:83], v[68:69], v[100:101], v[230:231]
	v_pk_fma_f32 v[84:85], v[66:67], v[98:99], v[228:229]
	v_lshlrev_b64 v[70:71], 11, v[218:219]
	v_cvt_pk_f16_f32 v69, v82, v83
	v_cvt_pk_f16_f32 v67, v86, v87
	v_cvt_pk_f16_f32 v68, v84, v85
	v_cvt_pk_f16_f32 v66, v88, v89
	v_lshl_add_u64 v[98:99], v[198:199], 0, v[70:71]
	global_store_dwordx4 v[98:99], v[66:69], off
	v_pk_mul_f32 v[70:71], v[192:193], v[82:83]
	v_pk_mul_f32 v[72:73], v[194:195], v[84:85]
	v_pk_mul_f32 v[68:69], v[188:189], v[86:87]
	v_pk_mul_f32 v[66:67], v[190:191], v[88:89]
	s_nop 0
	v_cvt_pk_bf16_f32 v66, v66, v67
	v_cvt_pk_bf16_f32 v67, v68, v69
	v_cvt_pk_bf16_f32 v68, v72, v73
	v_cvt_pk_bf16_f32 v69, v70, v71
	v_add_u32_e32 v70, s49, v218
	v_ashrrev_i32_e32 v71, 31, v70
	v_lshlrev_b64 v[70:71], 11, v[70:71]
	v_lshl_add_u64 v[70:71], s[0:1], 0, v[70:71]
	v_lshl_add_u64 v[100:101], v[70:71], 0, v[186:187]
	global_store_dwordx4 v[100:101], v[66:69], off
	global_load_dwordx4 v[66:69], v[160:161], off offset:528
	s_nop 0
	global_load_dwordx4 v[70:73], v[160:161], off offset:512
	global_load_dwordx4 v[186:189], v[162:163], off offset:528
	s_nop 0
	global_load_dwordx4 v[160:163], v[162:163], off offset:512
	s_nop 0
	global_load_dwordx4 v[190:193], v[156:157], off offset:528
	global_load_dwordx4 v[102:105], v[156:157], off offset:512
	s_waitcnt vmcnt(0)
	v_pk_add_f32 v[104:105], v[104:105], 1.0 op_sel_hi:[1,0]
	v_pk_add_f32 v[156:157], v[102:103], 1.0 op_sel_hi:[1,0]
	v_pk_mul_f32 v[102:103], v[162:163], v[104:105]
	v_pk_mul_f32 v[104:105], v[160:161], v[156:157]
	v_pk_add_f32 v[156:157], v[192:193], 1.0 op_sel_hi:[1,0]
	v_pk_add_f32 v[160:161], v[190:191], 1.0 op_sel_hi:[1,0]
	v_pk_mul_f32 v[156:157], v[188:189], v[156:157]
	v_pk_mul_f32 v[160:161], v[186:187], v[160:161]
	global_load_dwordx4 v[186:189], v[164:165], off offset:528 nt
	s_nop 0
	global_load_dwordx4 v[162:165], v[164:165], off offset:512 nt
	s_nop 0
	global_load_dwordx4 v[190:193], v[158:159], off offset:528 nt
	global_load_dwordx4 v[228:231], v[158:159], off offset:512 nt
	s_waitcnt vmcnt(3)
	v_pk_fma_f32 v[158:159], v[60:61], v[68:69], v[188:189]
	s_waitcnt vmcnt(2)
	v_pk_fma_f32 v[64:65], v[64:65], v[72:73], v[164:165]
	v_pk_fma_f32 v[62:63], v[62:63], v[70:71], v[162:163]
	v_pk_fma_f32 v[162:163], v[58:59], v[66:67], v[186:187]
	v_cvt_pk_f16_f32 v61, v158, v159
	v_cvt_pk_f16_f32 v59, v64, v65
	v_cvt_pk_f16_f32 v60, v162, v163
	v_cvt_pk_f16_f32 v58, v62, v63
	global_store_dwordx4 v[168:169], v[58:61], off offset:256
	s_waitcnt vmcnt(1)
	v_pk_fma_f32 v[56:57], v[56:57], v[72:73], v[230:231]
	v_pk_fma_f32 v[54:55], v[54:55], v[70:71], v[228:229]
	v_mul_f32_e32 v58, v63, v63
	v_mul_f32_e32 v59, v65, v65
	v_fmac_f32_e32 v58, v62, v62
	v_fmac_f32_e32 v59, v64, v64
	v_add_f32_e32 v58, v58, v59
	v_mul_f32_e32 v59, v163, v163
	v_mul_f32_e32 v60, v159, v159
	v_fmac_f32_e32 v59, v162, v162
	v_fmac_f32_e32 v60, v158, v158
	v_add_f32_e32 v59, v59, v60
	v_pk_mul_f32 v[60:61], v[104:105], v[62:63]
	v_pk_mul_f32 v[62:63], v[160:161], v[162:163]
	v_pk_mul_f32 v[64:65], v[102:103], v[64:65]
	v_pk_mul_f32 v[158:159], v[156:157], v[158:159]
	v_cvt_pk_bf16_f32 v60, v60, v61
	v_cvt_pk_bf16_f32 v61, v64, v65
	v_cvt_pk_bf16_f32 v62, v62, v63
	v_pk_fma_f32 v[52:53], v[52:53], v[68:69], v[192:193]
	v_cvt_pk_bf16_f32 v63, v158, v159
	v_pk_fma_f32 v[50:51], v[50:51], v[66:67], v[190:191]
	global_store_dwordx4 v[170:171], v[60:63], off offset:256
	v_pk_mul_f32 v[64:65], v[156:157], v[52:53]
	v_pk_mul_f32 v[158:159], v[160:161], v[50:51]
	v_cvt_pk_f16_f32 v63, v52, v53
	v_cvt_pk_f16_f32 v61, v56, v57
	v_cvt_pk_f16_f32 v62, v50, v51
	v_cvt_pk_f16_f32 v60, v54, v55
	global_store_dwordx4 v[172:173], v[60:63], off offset:256
	v_add_f32_e32 v58, v58, v59
	v_xor_b32_e32 v59, 16, v225
	v_pk_mul_f32 v[62:63], v[102:103], v[56:57]
	v_pk_mul_f32 v[60:61], v[104:105], v[54:55]
	v_add_f32_e32 v58, v226, v58
	v_cvt_pk_bf16_f32 v60, v60, v61
	v_cvt_pk_bf16_f32 v61, v62, v63
	v_cvt_pk_bf16_f32 v62, v158, v159
	v_cvt_pk_bf16_f32 v63, v64, v65
	global_store_dwordx4 v[178:179], v[60:63], off offset:256
	global_load_dwordx4 v[60:63], v[180:181], off offset:528 nt
	s_nop 0
	global_load_dwordx4 v[162:165], v[180:181], off offset:512 nt
	global_load_dwordx4 v[168:171], v[182:183], off offset:528 nt
	s_nop 0
	global_load_dwordx4 v[178:181], v[182:183], off offset:512 nt
	s_waitcnt vmcnt(3)
	v_pk_fma_f32 v[44:45], v[44:45], v[68:69], v[62:63]
	s_waitcnt vmcnt(2)
	v_pk_fma_f32 v[48:49], v[48:49], v[72:73], v[164:165]
	v_pk_fma_f32 v[46:47], v[46:47], v[70:71], v[162:163]
	v_pk_fma_f32 v[42:43], v[42:43], v[66:67], v[60:61]
	v_cvt_pk_f16_f32 v63, v44, v45
	v_cvt_pk_f16_f32 v61, v48, v49
	v_cvt_pk_f16_f32 v62, v42, v43
	v_cvt_pk_f16_f32 v60, v46, v47
	global_store_dwordx4 v[176:177], v[60:63], off offset:256
	v_pk_mul_f32 v[64:65], v[156:157], v[44:45]
	v_pk_mul_f32 v[158:159], v[160:161], v[42:43]
	v_pk_mul_f32 v[62:63], v[102:103], v[48:49]
	v_pk_mul_f32 v[60:61], v[104:105], v[46:47]
	s_waitcnt vmcnt(1)
	v_pk_fma_f32 v[40:41], v[40:41], v[72:73], v[180:181]
	v_cvt_pk_bf16_f32 v60, v60, v61
	v_cvt_pk_bf16_f32 v61, v62, v63
	v_cvt_pk_bf16_f32 v62, v158, v159
	v_cvt_pk_bf16_f32 v63, v64, v65
	v_pk_fma_f32 v[38:39], v[38:39], v[70:71], v[178:179]
	v_pk_fma_f32 v[36:37], v[36:37], v[68:69], v[170:171]
	v_pk_fma_f32 v[34:35], v[34:35], v[66:67], v[168:169]
	global_store_dwordx4 v[184:185], v[60:63], off offset:256
	v_pk_mul_f32 v[64:65], v[156:157], v[36:37]
	v_pk_mul_f32 v[158:159], v[160:161], v[34:35]
	v_cvt_pk_f16_f32 v63, v36, v37
	v_cvt_pk_f16_f32 v61, v40, v41
	v_cvt_pk_f16_f32 v62, v34, v35
	v_cvt_pk_f16_f32 v60, v38, v39
	global_store_dwordx4 v[174:175], v[60:63], off offset:256
	s_nop 1
	v_pk_mul_f32 v[62:63], v[102:103], v[40:41]
	v_pk_mul_f32 v[60:61], v[104:105], v[38:39]
	s_nop 0
	v_cvt_pk_bf16_f32 v60, v60, v61
	v_cvt_pk_bf16_f32 v61, v62, v63
	v_cvt_pk_bf16_f32 v62, v158, v159
	v_cvt_pk_bf16_f32 v63, v64, v65
	global_store_dwordx4 v[166:167], v[60:63], off offset:256
	global_load_dwordx4 v[60:63], v[196:197], off offset:528 nt
	s_nop 0
	global_load_dwordx4 v[162:165], v[196:197], off offset:512 nt
	global_load_dwordx4 v[166:169], v[210:211], off offset:528 nt
	global_load_dwordx4 v[170:173], v[210:211], off offset:512 nt
	s_waitcnt vmcnt(3)
	v_pk_fma_f32 v[28:29], v[28:29], v[68:69], v[62:63]
	s_waitcnt vmcnt(2)
	v_pk_fma_f32 v[32:33], v[32:33], v[72:73], v[164:165]
	v_pk_fma_f32 v[30:31], v[30:31], v[70:71], v[162:163]
	v_pk_fma_f32 v[26:27], v[26:27], v[66:67], v[60:61]
	v_cvt_pk_f16_f32 v63, v28, v29
	v_cvt_pk_f16_f32 v61, v32, v33
	v_cvt_pk_f16_f32 v62, v26, v27
	v_cvt_pk_f16_f32 v60, v30, v31
	global_store_dwordx4 v[208:209], v[60:63], off offset:256
	v_pk_mul_f32 v[64:65], v[156:157], v[28:29]
	v_pk_mul_f32 v[158:159], v[160:161], v[26:27]
	v_pk_mul_f32 v[62:63], v[102:103], v[32:33]
	v_pk_mul_f32 v[60:61], v[104:105], v[30:31]
	s_waitcnt vmcnt(1)
	v_pk_fma_f32 v[24:25], v[24:25], v[72:73], v[172:173]
	v_cvt_pk_bf16_f32 v60, v60, v61
	v_cvt_pk_bf16_f32 v61, v62, v63
	v_cvt_pk_bf16_f32 v62, v158, v159
	v_cvt_pk_bf16_f32 v63, v64, v65
	v_pk_fma_f32 v[22:23], v[22:23], v[70:71], v[170:171]
	v_pk_fma_f32 v[20:21], v[20:21], v[68:69], v[168:169]
	v_pk_fma_f32 v[18:19], v[18:19], v[66:67], v[166:167]
	global_store_dwordx4 v[212:213], v[60:63], off offset:256
	v_pk_mul_f32 v[64:65], v[156:157], v[20:21]
	v_pk_mul_f32 v[158:159], v[160:161], v[18:19]
	v_cvt_pk_f16_f32 v63, v20, v21
	v_cvt_pk_f16_f32 v61, v24, v25
	v_cvt_pk_f16_f32 v62, v18, v19
	v_cvt_pk_f16_f32 v60, v22, v23
	global_store_dwordx4 v[206:207], v[60:63], off offset:256
	s_nop 1
	v_pk_mul_f32 v[62:63], v[102:103], v[24:25]
	v_pk_mul_f32 v[60:61], v[104:105], v[22:23]
	s_nop 0
	v_cvt_pk_bf16_f32 v60, v60, v61
	v_cvt_pk_bf16_f32 v61, v62, v63
	v_cvt_pk_bf16_f32 v62, v158, v159
	v_cvt_pk_bf16_f32 v63, v64, v65
	global_store_dwordx4 v[202:203], v[60:63], off offset:256
	global_load_dwordx4 v[60:63], v[200:201], off offset:528 nt
	s_nop 0
	global_load_dwordx4 v[162:165], v[200:201], off offset:512 nt
	global_load_dwordx4 v[166:169], v[214:215], off offset:528 nt
	global_load_dwordx4 v[170:173], v[214:215], off offset:512 nt
	s_waitcnt vmcnt(3)
	v_pk_fma_f32 v[12:13], v[12:13], v[68:69], v[62:63]
	s_waitcnt vmcnt(2)
	v_pk_fma_f32 v[16:17], v[16:17], v[72:73], v[164:165]
	v_pk_fma_f32 v[14:15], v[14:15], v[70:71], v[162:163]
	v_pk_fma_f32 v[10:11], v[10:11], v[66:67], v[60:61]
	v_cvt_pk_f16_f32 v63, v12, v13
	v_cvt_pk_f16_f32 v61, v16, v17
	v_cvt_pk_f16_f32 v62, v10, v11
	v_cvt_pk_f16_f32 v60, v14, v15
	global_store_dwordx4 v[216:217], v[60:63], off offset:256
	v_pk_mul_f32 v[64:65], v[156:157], v[12:13]
	v_pk_mul_f32 v[158:159], v[160:161], v[10:11]
	v_pk_mul_f32 v[62:63], v[102:103], v[16:17]
	v_pk_mul_f32 v[60:61], v[104:105], v[14:15]
	s_waitcnt vmcnt(1)
	v_pk_fma_f32 v[8:9], v[8:9], v[72:73], v[172:173]
	v_cvt_pk_bf16_f32 v60, v60, v61
	v_cvt_pk_bf16_f32 v61, v62, v63
	v_cvt_pk_bf16_f32 v62, v158, v159
	v_cvt_pk_bf16_f32 v63, v64, v65
	v_pk_fma_f32 v[6:7], v[6:7], v[70:71], v[170:171]
	v_pk_fma_f32 v[4:5], v[4:5], v[68:69], v[168:169]
	v_pk_fma_f32 v[2:3], v[2:3], v[66:67], v[166:167]
	global_store_dwordx4 v[204:205], v[60:63], off offset:256
	v_pk_mul_f32 v[64:65], v[156:157], v[4:5]
	v_pk_mul_f32 v[66:67], v[160:161], v[2:3]
	v_cvt_pk_f16_f32 v63, v4, v5
	v_cvt_pk_f16_f32 v61, v8, v9
	v_cvt_pk_f16_f32 v62, v2, v3
	v_cvt_pk_f16_f32 v60, v6, v7
	global_store_dwordx4 v[98:99], v[60:63], off offset:256
	s_nop 1
	v_pk_mul_f32 v[60:61], v[104:105], v[6:7]
	v_pk_mul_f32 v[62:63], v[102:103], v[8:9]
	v_cvt_pk_bf16_f32 v60, v60, v61
	s_nop 0
	v_cvt_pk_bf16_f32 v61, v62, v63
	v_cvt_pk_bf16_f32 v62, v66, v67
	v_cvt_pk_bf16_f32 v63, v64, v65
	global_store_dwordx4 v[100:101], v[60:63], off offset:256
	s_nop 1
	v_and_b32_e32 v60, 64, v225
	v_add_u32_e32 v60, 64, v60
	v_cmp_lt_i32_e32 vcc, v59, v60
	v_xor_b32_e32 v61, 32, v225
	s_nop 0
	v_cndmask_b32_e32 v59, v225, v59, vcc
	v_lshlrev_b32_e32 v59, 2, v59
	v_cmp_lt_i32_e32 vcc, v61, v60
	s_nop 1
	v_cndmask_b32_e32 v60, v225, v61, vcc
	ds_bpermute_b32 v61, v59, v58
	v_lshlrev_b32_e32 v60, 2, v60
	s_waitcnt lgkmcnt(0)
	v_add_f32_e32 v58, v58, v61
	ds_bpermute_b32 v61, v60, v58
	s_and_saveexec_b64 s[78:79], s[6:7]
	s_cbranch_execz .LBB0_666
	v_lshl_add_u64 v[62:63], v[130:131], 2, s[52:53]
	s_waitcnt lgkmcnt(0)
	v_add_f32_e32 v58, v58, v61
	global_atomic_add_f32 v[62:63], v58, off

.LBB0_777:
	ds_read_b128 v[50:53], v182
	ds_read_b128 v[54:57], v182 offset:1024
	ds_read_b128 v[58:61], v182 offset:2048
	ds_read_b128 v[62:65], v182 offset:3072
	ds_read_b128 v[166:169], v183
	ds_read_b128 v[188:191], v183 offset:1024
	ds_read_b128 v[192:195], v183 offset:2048
	ds_read_b128 v[196:199], v183 offset:3072
	s_add_u32 s3, s84, 0xfffc0080
	s_addc_u32 s13, s85, -1
	s_cmp_eq_u32 s12, 12
	s_cselect_b32 s89, s11, s13
	s_cselect_b32 s88, s37, s3
	s_cselect_b32 s87, s75, s93
	s_cselect_b32 s86, s77, s92
	s_add_i32 m0, s33, 0xc000
	ds_read_b128 v[200:203], v184
	ds_read_b128 v[204:207], v184 offset:1024
	ds_read_b128 v[208:211], v184 offset:2048
	ds_read_b128 v[212:215], v184 offset:3072
	ds_read_b128 v[216:219], v184 offset:4096
	ds_read_b128 v[220:223], v184 offset:5120
	ds_read_b128 v[224:227], v184 offset:6144
	ds_read_b128 v[228:231], v184 offset:7168
	global_load_lds_dwordx4 v158, s[84:85]
	s_add_i32 m0, s33, 0xe000
	s_nop 0
	global_load_lds_dwordx4 v160, s[84:85]
	s_waitcnt vmcnt(8)
	s_waitcnt lgkmcnt(0)
	s_barrier
	s_setprio 1
	s_waitcnt lgkmcnt(0)
	v_mfma_f32_16x16x32_bf16 v[142:145], v[50:53], v[200:203], v[142:145]
	v_mfma_f32_16x16x32_bf16 v[138:141], v[58:61], v[200:203], v[138:141]
	v_mfma_f32_16x16x32_bf16 v[126:129], v[50:53], v[208:211], v[126:129]
	v_mfma_f32_16x16x32_bf16 v[122:125], v[58:61], v[208:211], v[122:125]
	v_mfma_f32_16x16x32_bf16 v[110:113], v[50:53], v[216:219], v[110:113]
	v_mfma_f32_16x16x32_bf16 v[106:109], v[58:61], v[216:219], v[106:109]
	v_mfma_f32_16x16x32_bf16 v[94:97], v[50:53], v[224:227], v[94:97]
	v_mfma_f32_16x16x32_bf16 v[90:93], v[58:61], v[224:227], v[90:93]
	v_mfma_f32_16x16x32_bf16 v[142:145], v[54:57], v[204:207], v[142:145]
	v_mfma_f32_16x16x32_bf16 v[138:141], v[62:65], v[204:207], v[138:141]
	v_mfma_f32_16x16x32_bf16 v[126:129], v[54:57], v[212:215], v[126:129]
	v_mfma_f32_16x16x32_bf16 v[122:125], v[62:65], v[212:215], v[122:125]
	v_mfma_f32_16x16x32_bf16 v[110:113], v[54:57], v[220:223], v[110:113]
	v_mfma_f32_16x16x32_bf16 v[106:109], v[62:65], v[220:223], v[106:109]
	v_mfma_f32_16x16x32_bf16 v[94:97], v[54:57], v[228:231], v[94:97]
	v_mfma_f32_16x16x32_bf16 v[90:93], v[62:65], v[228:231], v[90:93]
	s_setprio 0
	s_setprio 1
	v_mfma_f32_16x16x32_bf16 v[134:137], v[166:169], v[200:203], v[134:137]
	v_mfma_f32_16x16x32_bf16 v[130:133], v[192:195], v[200:203], v[130:133]
	v_mfma_f32_16x16x32_bf16 v[118:121], v[166:169], v[208:211], v[118:121]
	v_mfma_f32_16x16x32_bf16 v[114:117], v[192:195], v[208:211], v[114:117]
	v_mfma_f32_16x16x32_bf16 v[102:105], v[166:169], v[216:219], v[102:105]
	v_mfma_f32_16x16x32_bf16 v[98:101], v[192:195], v[216:219], v[98:101]
	v_mfma_f32_16x16x32_bf16 v[86:89], v[166:169], v[224:227], v[86:89]
	v_mfma_f32_16x16x32_bf16 v[82:85], v[192:195], v[224:227], v[82:85]
	v_mfma_f32_16x16x32_bf16 v[134:137], v[188:191], v[204:207], v[134:137]
	v_mfma_f32_16x16x32_bf16 v[130:133], v[196:199], v[204:207], v[130:133]
	v_mfma_f32_16x16x32_bf16 v[118:121], v[188:191], v[212:215], v[118:121]
	v_mfma_f32_16x16x32_bf16 v[114:117], v[196:199], v[212:215], v[114:117]
	v_mfma_f32_16x16x32_bf16 v[102:105], v[188:191], v[220:223], v[102:105]
	v_mfma_f32_16x16x32_bf16 v[98:101], v[196:199], v[220:223], v[98:101]
	v_mfma_f32_16x16x32_bf16 v[86:89], v[188:191], v[228:231], v[86:89]
	v_mfma_f32_16x16x32_bf16 v[82:85], v[196:199], v[228:231], v[82:85]
	s_setprio 0
	s_barrier
	s_add_i32 s3, s66, s23
	s_mov_b32 m0, s3
	ds_read_b128 v[200:203], v184 offset:16384
	ds_read_b128 v[204:207], v184 offset:17408
	ds_read_b128 v[208:211], v184 offset:18432
	ds_read_b128 v[212:215], v184 offset:19456
	ds_read_b128 v[216:219], v184 offset:20480
	ds_read_b128 v[220:223], v184 offset:21504
	ds_read_b128 v[224:227], v184 offset:22528
	ds_read_b128 v[228:231], v184 offset:23552
	global_load_lds_dwordx4 v150, s[86:87]
	s_add_i32 m0, s3, 0x2000
	s_add_u32 s24, s86, 0x40000
	s_addc_u32 s25, s87, 0
	s_add_i32 s3, s67, s23
	global_load_lds_dwordx4 v154, s[86:87]
	s_mov_b32 m0, s3
	s_nop 0
	global_load_lds_dwordx4 v150, s[24:25]
	s_add_i32 m0, s3, 0x2000
	s_nop 0
	global_load_lds_dwordx4 v154, s[24:25]
	s_mov_b32 m0, s33
	s_nop 0
	global_load_lds_dwordx4 v148, s[88:89]
	s_mov_b32 m0, s44
	s_nop 0
	global_load_lds_dwordx4 v152, s[88:89]
	s_waitcnt vmcnt(8)
	s_waitcnt lgkmcnt(0)
	s_barrier
	s_setprio 1
	s_waitcnt lgkmcnt(0)
	v_mfma_f32_16x16x32_bf16 v[78:81], v[50:53], v[200:203], v[78:81]
	v_mfma_f32_16x16x32_bf16 v[74:77], v[58:61], v[200:203], v[74:77]
	v_mfma_f32_16x16x32_bf16 v[46:49], v[50:53], v[208:211], v[46:49]
	v_mfma_f32_16x16x32_bf16 v[42:45], v[58:61], v[208:211], v[42:45]
	v_mfma_f32_16x16x32_bf16 v[30:33], v[50:53], v[216:219], v[30:33]
	v_mfma_f32_16x16x32_bf16 v[26:29], v[58:61], v[216:219], v[26:29]
	v_mfma_f32_16x16x32_bf16 v[14:17], v[50:53], v[224:227], v[14:17]
	v_mfma_f32_16x16x32_bf16 v[10:13], v[58:61], v[224:227], v[10:13]
	v_mfma_f32_16x16x32_bf16 v[78:81], v[54:57], v[204:207], v[78:81]
	v_mfma_f32_16x16x32_bf16 v[74:77], v[62:65], v[204:207], v[74:77]
	v_mfma_f32_16x16x32_bf16 v[46:49], v[54:57], v[212:215], v[46:49]
	v_mfma_f32_16x16x32_bf16 v[42:45], v[62:65], v[212:215], v[42:45]
	v_mfma_f32_16x16x32_bf16 v[30:33], v[54:57], v[220:223], v[30:33]
	v_mfma_f32_16x16x32_bf16 v[26:29], v[62:65], v[220:223], v[26:29]
	v_mfma_f32_16x16x32_bf16 v[14:17], v[54:57], v[228:231], v[14:17]
	v_mfma_f32_16x16x32_bf16 v[10:13], v[62:65], v[228:231], v[10:13]
	s_setprio 0
	s_setprio 1
	v_mfma_f32_16x16x32_bf16 v[38:41], v[166:169], v[208:211], v[38:41]
	v_mfma_f32_16x16x32_bf16 v[34:37], v[192:195], v[208:211], v[34:37]
	v_mfma_f32_16x16x32_bf16 v[22:25], v[166:169], v[216:219], v[22:25]
	v_mfma_f32_16x16x32_bf16 v[18:21], v[192:195], v[216:219], v[18:21]
	v_mfma_f32_16x16x32_bf16 v[6:9], v[166:169], v[224:227], v[6:9]
	v_mfma_f32_16x16x32_bf16 v[2:5], v[192:195], v[224:227], v[2:5]
	v_mfma_f32_16x16x32_bf16 v[50:53], v[166:169], v[200:203], v[70:73]
	v_mfma_f32_16x16x32_bf16 v[54:57], v[192:195], v[200:203], v[66:69]
	v_mfma_f32_16x16x32_bf16 v[38:41], v[188:191], v[212:215], v[38:41]
	v_mfma_f32_16x16x32_bf16 v[34:37], v[196:199], v[212:215], v[34:37]
	v_mfma_f32_16x16x32_bf16 v[22:25], v[188:191], v[220:223], v[22:25]
	v_mfma_f32_16x16x32_bf16 v[18:21], v[196:199], v[220:223], v[18:21]
	v_mfma_f32_16x16x32_bf16 v[6:9], v[188:191], v[228:231], v[6:9]
	v_mfma_f32_16x16x32_bf16 v[2:5], v[196:199], v[228:231], v[2:5]
	v_mfma_f32_16x16x32_bf16 v[50:53], v[188:191], v[204:207], v[50:53]
	v_mfma_f32_16x16x32_bf16 v[54:57], v[196:199], v[204:207], v[54:57]
	s_setprio 0
	s_barrier
	s_add_i32 s3, 0, 0x18000
	s_add_i32 s13, 0, 0x1c000
	v_add_u32_e32 v70, s3, v173
	v_add_u32_e32 v187, s13, v173
	ds_read_b128 v[58:61], v70
	ds_read_b128 v[62:65], v70 offset:1024
	ds_read_b128 v[66:69], v70 offset:2048
	ds_read_b128 v[70:73], v70 offset:3072
	ds_read_b128 v[166:169], v187
	ds_read_b128 v[188:191], v187 offset:1024
	ds_read_b128 v[192:195], v187 offset:2048
	ds_read_b128 v[196:199], v187 offset:3072
	s_add_u32 s24, s88, 0x40000
	s_addc_u32 s25, s89, 0
	s_mov_b32 m0, s45
	ds_read_b128 v[200:203], v184 offset:32768
	ds_read_b128 v[204:207], v184 offset:33792
	ds_read_b128 v[208:211], v184 offset:34816
	ds_read_b128 v[212:215], v184 offset:35840
	ds_read_b128 v[216:219], v184 offset:36864
	ds_read_b128 v[220:223], v184 offset:37888
	ds_read_b128 v[224:227], v184 offset:38912
	ds_read_b128 v[228:231], v184 offset:39936
	global_load_lds_dwordx4 v148, s[24:25]
	s_mov_b32 m0, s48
	s_nop 0
	global_load_lds_dwordx4 v152, s[24:25]
	s_waitcnt vmcnt(8)
	s_waitcnt lgkmcnt(0)
	s_barrier
	s_setprio 1
	s_waitcnt lgkmcnt(0)
	v_mfma_f32_16x16x32_bf16 v[142:145], v[58:61], v[200:203], v[142:145]
	v_mfma_f32_16x16x32_bf16 v[138:141], v[66:69], v[200:203], v[138:141]
	v_mfma_f32_16x16x32_bf16 v[126:129], v[58:61], v[208:211], v[126:129]
	v_mfma_f32_16x16x32_bf16 v[122:125], v[66:69], v[208:211], v[122:125]
	v_mfma_f32_16x16x32_bf16 v[110:113], v[58:61], v[216:219], v[110:113]
	v_mfma_f32_16x16x32_bf16 v[106:109], v[66:69], v[216:219], v[106:109]
	v_mfma_f32_16x16x32_bf16 v[94:97], v[58:61], v[224:227], v[94:97]
	v_mfma_f32_16x16x32_bf16 v[90:93], v[66:69], v[224:227], v[90:93]
	v_mfma_f32_16x16x32_bf16 v[142:145], v[62:65], v[204:207], v[142:145]
	v_mfma_f32_16x16x32_bf16 v[138:141], v[70:73], v[204:207], v[138:141]
	v_mfma_f32_16x16x32_bf16 v[126:129], v[62:65], v[212:215], v[126:129]
	v_mfma_f32_16x16x32_bf16 v[122:125], v[70:73], v[212:215], v[122:125]
	v_mfma_f32_16x16x32_bf16 v[110:113], v[62:65], v[220:223], v[110:113]
	v_mfma_f32_16x16x32_bf16 v[106:109], v[70:73], v[220:223], v[106:109]
	v_mfma_f32_16x16x32_bf16 v[94:97], v[62:65], v[228:231], v[94:97]
	v_mfma_f32_16x16x32_bf16 v[90:93], v[70:73], v[228:231], v[90:93]
	s_setprio 0
	s_setprio 1
	v_mfma_f32_16x16x32_bf16 v[134:137], v[166:169], v[200:203], v[134:137]
	v_mfma_f32_16x16x32_bf16 v[130:133], v[192:195], v[200:203], v[130:133]
	v_mfma_f32_16x16x32_bf16 v[118:121], v[166:169], v[208:211], v[118:121]
	v_mfma_f32_16x16x32_bf16 v[114:117], v[192:195], v[208:211], v[114:117]
	v_mfma_f32_16x16x32_bf16 v[102:105], v[166:169], v[216:219], v[102:105]
	v_mfma_f32_16x16x32_bf16 v[98:101], v[192:195], v[216:219], v[98:101]
	v_mfma_f32_16x16x32_bf16 v[86:89], v[166:169], v[224:227], v[86:89]
	v_mfma_f32_16x16x32_bf16 v[82:85], v[192:195], v[224:227], v[82:85]
	v_mfma_f32_16x16x32_bf16 v[134:137], v[188:191], v[204:207], v[134:137]
	v_mfma_f32_16x16x32_bf16 v[130:133], v[196:199], v[204:207], v[130:133]
	v_mfma_f32_16x16x32_bf16 v[118:121], v[188:191], v[212:215], v[118:121]
	v_mfma_f32_16x16x32_bf16 v[114:117], v[196:199], v[212:215], v[114:117]
	v_mfma_f32_16x16x32_bf16 v[102:105], v[188:191], v[220:223], v[102:105]
	v_mfma_f32_16x16x32_bf16 v[98:101], v[196:199], v[220:223], v[98:101]
	v_mfma_f32_16x16x32_bf16 v[86:89], v[188:191], v[228:231], v[86:89]
	v_mfma_f32_16x16x32_bf16 v[82:85], v[196:199], v[228:231], v[82:85]
	s_setprio 0
	s_barrier
	s_add_i32 s3, s3, s23
	s_mov_b32 m0, s3
	ds_read_b128 v[200:203], v184 offset:49152
	ds_read_b128 v[204:207], v184 offset:50176
	ds_read_b128 v[208:211], v184 offset:51200
	ds_read_b128 v[212:215], v184 offset:52224
	ds_read_b128 v[216:219], v184 offset:53248
	ds_read_b128 v[220:223], v184 offset:54272
	ds_read_b128 v[224:227], v184 offset:55296
	ds_read_b128 v[228:231], v184 offset:56320
	global_load_lds_dwordx4 v251, s[86:87]
	s_add_i32 m0, s3, 0x2000
	s_add_u32 s24, s86, 0x40080
	s_addc_u32 s25, s87, 0
	s_add_i32 s3, s13, s23
	global_load_lds_dwordx4 v252, s[86:87]
	s_mov_b32 m0, s3
	s_nop 0
	global_load_lds_dwordx4 v150, s[24:25]
	s_add_i32 m0, s3, 0x2000
	s_nop 0
	global_load_lds_dwordx4 v154, s[24:25]
	s_mov_b32 m0, s60
	s_nop 0
	global_load_lds_dwordx4 v253, s[88:89]
	s_mov_b32 m0, s61
	s_nop 0
	global_load_lds_dwordx4 v254, s[88:89]
	s_waitcnt vmcnt(8)
	s_waitcnt lgkmcnt(0)
	s_barrier
	s_setprio 1
	s_waitcnt lgkmcnt(0)
	v_mfma_f32_16x16x32_bf16 v[78:81], v[58:61], v[200:203], v[78:81]
	v_mfma_f32_16x16x32_bf16 v[74:77], v[66:69], v[200:203], v[74:77]
	v_mfma_f32_16x16x32_bf16 v[46:49], v[58:61], v[208:211], v[46:49]
	v_mfma_f32_16x16x32_bf16 v[42:45], v[66:69], v[208:211], v[42:45]
	v_mfma_f32_16x16x32_bf16 v[30:33], v[58:61], v[216:219], v[30:33]
	v_mfma_f32_16x16x32_bf16 v[26:29], v[66:69], v[216:219], v[26:29]
	v_mfma_f32_16x16x32_bf16 v[14:17], v[58:61], v[224:227], v[14:17]
	v_mfma_f32_16x16x32_bf16 v[10:13], v[66:69], v[224:227], v[10:13]
	v_mfma_f32_16x16x32_bf16 v[78:81], v[62:65], v[204:207], v[78:81]
	v_mfma_f32_16x16x32_bf16 v[74:77], v[70:73], v[204:207], v[74:77]
	v_mfma_f32_16x16x32_bf16 v[46:49], v[62:65], v[212:215], v[46:49]
	v_mfma_f32_16x16x32_bf16 v[42:45], v[70:73], v[212:215], v[42:45]
	v_mfma_f32_16x16x32_bf16 v[30:33], v[62:65], v[220:223], v[30:33]
	v_mfma_f32_16x16x32_bf16 v[26:29], v[70:73], v[220:223], v[26:29]
	v_mfma_f32_16x16x32_bf16 v[14:17], v[62:65], v[228:231], v[14:17]
	v_mfma_f32_16x16x32_bf16 v[10:13], v[70:73], v[228:231], v[10:13]
	s_setprio 0
	s_setprio 1
	v_mfma_f32_16x16x32_bf16 v[50:53], v[166:169], v[200:203], v[50:53]
	v_mfma_f32_16x16x32_bf16 v[70:73], v[188:191], v[204:207], v[50:53]
	v_mfma_f32_16x16x32_bf16 v[50:53], v[192:195], v[200:203], v[54:57]
	v_mfma_f32_16x16x32_bf16 v[38:41], v[166:169], v[208:211], v[38:41]
	v_mfma_f32_16x16x32_bf16 v[34:37], v[192:195], v[208:211], v[34:37]
	v_mfma_f32_16x16x32_bf16 v[22:25], v[166:169], v[216:219], v[22:25]
	v_mfma_f32_16x16x32_bf16 v[18:21], v[192:195], v[216:219], v[18:21]
	v_mfma_f32_16x16x32_bf16 v[6:9], v[166:169], v[224:227], v[6:9]
	v_mfma_f32_16x16x32_bf16 v[2:5], v[192:195], v[224:227], v[2:5]
	v_mfma_f32_16x16x32_bf16 v[66:69], v[196:199], v[204:207], v[50:53]
	v_mfma_f32_16x16x32_bf16 v[38:41], v[188:191], v[212:215], v[38:41]
	v_mfma_f32_16x16x32_bf16 v[34:37], v[196:199], v[212:215], v[34:37]
	v_mfma_f32_16x16x32_bf16 v[22:25], v[188:191], v[220:223], v[22:25]
	v_mfma_f32_16x16x32_bf16 v[18:21], v[196:199], v[220:223], v[18:21]
	v_mfma_f32_16x16x32_bf16 v[6:9], v[188:191], v[228:231], v[6:9]
	v_mfma_f32_16x16x32_bf16 v[2:5], v[196:199], v[228:231], v[2:5]
	s_setprio 0
	s_barrier
	s_add_i32 s12, s12, 2
	s_add_u32 s84, s84, 0x100
	s_addc_u32 s85, s85, 0
	s_add_u32 s92, s92, 0x100
	s_addc_u32 s93, s93, 0
	s_cmp_gt_u32 s12, 13
	s_cbranch_scc0 .LBB0_777
	s_and_b64 vcc, exec, s[70:71]
	s_cbranch_vccz .LBB0_780
	s_barrier

.LBB0_818:
	ds_read_b128 v[152:155], v148
	ds_read_b128 v[156:159], v148 offset:1024
	ds_read_b128 v[160:163], v148 offset:2048
	ds_read_b128 v[164:167], v148 offset:3072
	ds_read_b128 v[168:171], v149
	ds_read_b128 v[172:175], v149 offset:1024
	ds_read_b128 v[176:179], v149 offset:2048
	ds_read_b128 v[180:183], v149 offset:3072
	s_add_i32 s13, s12, 2
	s_add_u32 s70, s68, 0x100
	s_addc_u32 s71, s69, 0
	s_cmp_eq_u32 s80, s12
	s_cselect_b32 s75, s7, s71
	s_cselect_b32 s74, s6, s70
	s_cselect_b32 s73, s53, s82
	s_cselect_b32 s72, s52, s81
	v_lshl_add_u64 v[216:217], s[68:69], 0, v[140:141]
	s_add_i32 m0, s36, 0xc000
	ds_read_b128 v[184:187], v150
	ds_read_b128 v[188:191], v150 offset:1024
	ds_read_b128 v[192:195], v150 offset:2048
	ds_read_b128 v[196:199], v150 offset:3072
	ds_read_b128 v[200:203], v150 offset:4096
	ds_read_b128 v[204:207], v150 offset:5120
	ds_read_b128 v[208:211], v150 offset:6144
	ds_read_b128 v[212:215], v150 offset:7168
	global_load_lds_dwordx4 v[216:217], off
	v_lshl_add_u64 v[216:217], s[68:69], 0, v[142:143]
	s_add_i32 m0, s36, 0xe000
	s_nop 0
	global_load_lds_dwordx4 v[216:217], off
	s_waitcnt vmcnt(8)
	s_waitcnt lgkmcnt(0)
	s_barrier
	s_setprio 1
	s_waitcnt lgkmcnt(0)
	v_mfma_f32_16x16x32_bf16 v[126:129], v[152:155], v[184:187], v[126:129]
	v_mfma_f32_16x16x32_bf16 v[122:125], v[160:163], v[184:187], v[122:125]
	v_mfma_f32_16x16x32_bf16 v[118:121], v[152:155], v[192:195], v[118:121]
	v_mfma_f32_16x16x32_bf16 v[114:117], v[160:163], v[192:195], v[114:117]
	v_mfma_f32_16x16x32_bf16 v[110:113], v[152:155], v[200:203], v[110:113]
	v_mfma_f32_16x16x32_bf16 v[102:105], v[160:163], v[200:203], v[102:105]
	v_mfma_f32_16x16x32_bf16 v[94:97], v[152:155], v[208:211], v[94:97]
	v_mfma_f32_16x16x32_bf16 v[86:89], v[160:163], v[208:211], v[86:89]
	v_mfma_f32_16x16x32_bf16 v[126:129], v[156:159], v[188:191], v[126:129]
	v_mfma_f32_16x16x32_bf16 v[122:125], v[164:167], v[188:191], v[122:125]
	v_mfma_f32_16x16x32_bf16 v[118:121], v[156:159], v[196:199], v[118:121]
	v_mfma_f32_16x16x32_bf16 v[114:117], v[164:167], v[196:199], v[114:117]
	v_mfma_f32_16x16x32_bf16 v[110:113], v[156:159], v[204:207], v[110:113]
	v_mfma_f32_16x16x32_bf16 v[102:105], v[164:167], v[204:207], v[102:105]
	v_mfma_f32_16x16x32_bf16 v[94:97], v[156:159], v[212:215], v[94:97]
	v_mfma_f32_16x16x32_bf16 v[86:89], v[164:167], v[212:215], v[86:89]
	s_setprio 0
	s_setprio 1
	v_mfma_f32_16x16x32_bf16 v[106:109], v[168:171], v[184:187], v[106:109]
	v_mfma_f32_16x16x32_bf16 v[98:101], v[176:179], v[184:187], v[98:101]
	v_mfma_f32_16x16x32_bf16 v[90:93], v[168:171], v[192:195], v[90:93]
	v_mfma_f32_16x16x32_bf16 v[82:85], v[176:179], v[192:195], v[82:85]
	v_mfma_f32_16x16x32_bf16 v[78:81], v[168:171], v[200:203], v[78:81]
	v_mfma_f32_16x16x32_bf16 v[74:77], v[176:179], v[200:203], v[74:77]
	v_mfma_f32_16x16x32_bf16 v[70:73], v[168:171], v[208:211], v[70:73]
	v_mfma_f32_16x16x32_bf16 v[66:69], v[176:179], v[208:211], v[66:69]
	v_mfma_f32_16x16x32_bf16 v[106:109], v[172:175], v[188:191], v[106:109]
	v_mfma_f32_16x16x32_bf16 v[98:101], v[180:183], v[188:191], v[98:101]
	v_mfma_f32_16x16x32_bf16 v[90:93], v[172:175], v[196:199], v[90:93]
	v_mfma_f32_16x16x32_bf16 v[82:85], v[180:183], v[196:199], v[82:85]
	v_mfma_f32_16x16x32_bf16 v[78:81], v[172:175], v[204:207], v[78:81]
	v_mfma_f32_16x16x32_bf16 v[74:77], v[180:183], v[204:207], v[74:77]
	v_mfma_f32_16x16x32_bf16 v[70:73], v[172:175], v[212:215], v[70:73]
	v_mfma_f32_16x16x32_bf16 v[66:69], v[180:183], v[212:215], v[66:69]
	s_setprio 0
	s_barrier
	s_add_i32 s3, s63, s27
	s_mov_b32 m0, s3
	ds_read_b128 v[184:187], v150 offset:16384
	ds_read_b128 v[188:191], v150 offset:17408
	ds_read_b128 v[192:195], v150 offset:18432
	ds_read_b128 v[196:199], v150 offset:19456
	ds_read_b128 v[200:203], v150 offset:20480
	ds_read_b128 v[204:207], v150 offset:21504
	ds_read_b128 v[208:211], v150 offset:22528
	ds_read_b128 v[212:215], v150 offset:23552
	global_load_lds_dwordx4 v134, s[72:73]
	s_add_i32 m0, s3, 0x2000
	s_add_u32 s24, s72, 0xb0000
	s_addc_u32 s25, s73, 0
	s_add_i32 s3, s66, s27
	global_load_lds_dwordx4 v130, s[72:73]
	s_mov_b32 m0, s3
	s_nop 0
	global_load_lds_dwordx4 v134, s[24:25]
	s_add_i32 m0, s3, 0x2000
	s_nop 0
	global_load_lds_dwordx4 v130, s[24:25]
	s_mov_b32 m0, s36
	s_nop 0
	global_load_lds_dwordx4 v136, s[74:75]
	s_mov_b32 m0, s37
	s_nop 0
	global_load_lds_dwordx4 v132, s[74:75]
	s_waitcnt vmcnt(8)
	s_waitcnt lgkmcnt(0)
	s_barrier
	s_setprio 1
	s_waitcnt lgkmcnt(0)
	v_mfma_f32_16x16x32_bf16 v[62:65], v[152:155], v[184:187], v[62:65]
	v_mfma_f32_16x16x32_bf16 v[58:61], v[160:163], v[184:187], v[58:61]
	v_mfma_f32_16x16x32_bf16 v[54:57], v[152:155], v[192:195], v[54:57]
	v_mfma_f32_16x16x32_bf16 v[50:53], v[160:163], v[192:195], v[50:53]
	v_mfma_f32_16x16x32_bf16 v[46:49], v[152:155], v[200:203], v[46:49]
	v_mfma_f32_16x16x32_bf16 v[38:41], v[160:163], v[200:203], v[38:41]
	v_mfma_f32_16x16x32_bf16 v[30:33], v[152:155], v[208:211], v[30:33]
	v_mfma_f32_16x16x32_bf16 v[22:25], v[160:163], v[208:211], v[22:25]
	v_mfma_f32_16x16x32_bf16 v[62:65], v[156:159], v[188:191], v[62:65]
	v_mfma_f32_16x16x32_bf16 v[58:61], v[164:167], v[188:191], v[58:61]
	v_mfma_f32_16x16x32_bf16 v[54:57], v[156:159], v[196:199], v[54:57]
	v_mfma_f32_16x16x32_bf16 v[50:53], v[164:167], v[196:199], v[50:53]
	v_mfma_f32_16x16x32_bf16 v[46:49], v[156:159], v[204:207], v[46:49]
	v_mfma_f32_16x16x32_bf16 v[38:41], v[164:167], v[204:207], v[38:41]
	v_mfma_f32_16x16x32_bf16 v[30:33], v[156:159], v[212:215], v[30:33]
	v_mfma_f32_16x16x32_bf16 v[22:25], v[164:167], v[212:215], v[22:25]
	s_setprio 0
	s_setprio 1
	v_mfma_f32_16x16x32_bf16 v[42:45], v[168:171], v[184:187], v[42:45]
	v_mfma_f32_16x16x32_bf16 v[34:37], v[176:179], v[184:187], v[34:37]
	v_mfma_f32_16x16x32_bf16 v[26:29], v[168:171], v[192:195], v[26:29]
	v_mfma_f32_16x16x32_bf16 v[18:21], v[176:179], v[192:195], v[18:21]
	v_mfma_f32_16x16x32_bf16 v[14:17], v[168:171], v[200:203], v[14:17]
	v_mfma_f32_16x16x32_bf16 v[10:13], v[176:179], v[200:203], v[10:13]
	v_mfma_f32_16x16x32_bf16 v[6:9], v[168:171], v[208:211], v[6:9]
	v_mfma_f32_16x16x32_bf16 v[2:5], v[176:179], v[208:211], v[2:5]
	v_mfma_f32_16x16x32_bf16 v[42:45], v[172:175], v[188:191], v[42:45]
	v_mfma_f32_16x16x32_bf16 v[34:37], v[180:183], v[188:191], v[34:37]
	v_mfma_f32_16x16x32_bf16 v[26:29], v[172:175], v[196:199], v[26:29]
	v_mfma_f32_16x16x32_bf16 v[18:21], v[180:183], v[196:199], v[18:21]
	v_mfma_f32_16x16x32_bf16 v[14:17], v[172:175], v[204:207], v[14:17]
	v_mfma_f32_16x16x32_bf16 v[10:13], v[180:183], v[204:207], v[10:13]
	v_mfma_f32_16x16x32_bf16 v[6:9], v[172:175], v[212:215], v[6:9]
	v_mfma_f32_16x16x32_bf16 v[2:5], v[180:183], v[212:215], v[2:5]
	s_setprio 0
	s_barrier
	s_add_i32 s3, 0, 0x18000
	v_add_u32_e32 v151, s3, v1
	s_add_i32 s12, 0, 0x1c000
	ds_read_b128 v[152:155], v151
	ds_read_b128 v[156:159], v151 offset:1024
	ds_read_b128 v[160:163], v151 offset:2048
	ds_read_b128 v[164:167], v151 offset:3072
	v_add_u32_e32 v151, s12, v1
	ds_read_b128 v[168:171], v151
	ds_read_b128 v[172:175], v151 offset:1024
	ds_read_b128 v[176:179], v151 offset:2048
	ds_read_b128 v[180:183], v151 offset:3072
	s_add_u32 s24, s74, 0xb0000
	s_addc_u32 s25, s75, 0
	s_mov_b32 m0, s44
	ds_read_b128 v[184:187], v150 offset:32768
	ds_read_b128 v[188:191], v150 offset:33792
	ds_read_b128 v[192:195], v150 offset:34816
	ds_read_b128 v[196:199], v150 offset:35840
	ds_read_b128 v[200:203], v150 offset:36864
	ds_read_b128 v[204:207], v150 offset:37888
	ds_read_b128 v[208:211], v150 offset:38912
	ds_read_b128 v[212:215], v150 offset:39936
	global_load_lds_dwordx4 v136, s[24:25]
	s_mov_b32 m0, s45
	s_nop 0
	global_load_lds_dwordx4 v132, s[24:25]
	s_waitcnt vmcnt(8)
	s_waitcnt lgkmcnt(0)
	s_barrier
	s_setprio 1
	s_waitcnt lgkmcnt(0)
	v_mfma_f32_16x16x32_bf16 v[126:129], v[152:155], v[184:187], v[126:129]
	v_mfma_f32_16x16x32_bf16 v[122:125], v[160:163], v[184:187], v[122:125]
	v_mfma_f32_16x16x32_bf16 v[118:121], v[152:155], v[192:195], v[118:121]
	v_mfma_f32_16x16x32_bf16 v[114:117], v[160:163], v[192:195], v[114:117]
	v_mfma_f32_16x16x32_bf16 v[110:113], v[152:155], v[200:203], v[110:113]
	v_mfma_f32_16x16x32_bf16 v[102:105], v[160:163], v[200:203], v[102:105]
	v_mfma_f32_16x16x32_bf16 v[94:97], v[152:155], v[208:211], v[94:97]
	v_mfma_f32_16x16x32_bf16 v[86:89], v[160:163], v[208:211], v[86:89]
	v_mfma_f32_16x16x32_bf16 v[126:129], v[156:159], v[188:191], v[126:129]
	v_mfma_f32_16x16x32_bf16 v[122:125], v[164:167], v[188:191], v[122:125]
	v_mfma_f32_16x16x32_bf16 v[118:121], v[156:159], v[196:199], v[118:121]
	v_mfma_f32_16x16x32_bf16 v[114:117], v[164:167], v[196:199], v[114:117]
	v_mfma_f32_16x16x32_bf16 v[110:113], v[156:159], v[204:207], v[110:113]
	v_mfma_f32_16x16x32_bf16 v[102:105], v[164:167], v[204:207], v[102:105]
	v_mfma_f32_16x16x32_bf16 v[94:97], v[156:159], v[212:215], v[94:97]
	v_mfma_f32_16x16x32_bf16 v[86:89], v[164:167], v[212:215], v[86:89]
	s_setprio 0
	s_setprio 1
	v_mfma_f32_16x16x32_bf16 v[106:109], v[168:171], v[184:187], v[106:109]
	v_mfma_f32_16x16x32_bf16 v[98:101], v[176:179], v[184:187], v[98:101]
	v_mfma_f32_16x16x32_bf16 v[90:93], v[168:171], v[192:195], v[90:93]
	v_mfma_f32_16x16x32_bf16 v[82:85], v[176:179], v[192:195], v[82:85]
	v_mfma_f32_16x16x32_bf16 v[78:81], v[168:171], v[200:203], v[78:81]
	v_mfma_f32_16x16x32_bf16 v[74:77], v[176:179], v[200:203], v[74:77]
	v_mfma_f32_16x16x32_bf16 v[70:73], v[168:171], v[208:211], v[70:73]
	v_mfma_f32_16x16x32_bf16 v[66:69], v[176:179], v[208:211], v[66:69]
	v_mfma_f32_16x16x32_bf16 v[106:109], v[172:175], v[188:191], v[106:109]
	v_mfma_f32_16x16x32_bf16 v[98:101], v[180:183], v[188:191], v[98:101]
	v_mfma_f32_16x16x32_bf16 v[90:93], v[172:175], v[196:199], v[90:93]
	v_mfma_f32_16x16x32_bf16 v[82:85], v[180:183], v[196:199], v[82:85]
	v_mfma_f32_16x16x32_bf16 v[78:81], v[172:175], v[204:207], v[78:81]
	v_mfma_f32_16x16x32_bf16 v[74:77], v[180:183], v[204:207], v[74:77]
	v_mfma_f32_16x16x32_bf16 v[70:73], v[172:175], v[212:215], v[70:73]
	v_mfma_f32_16x16x32_bf16 v[66:69], v[180:183], v[212:215], v[66:69]
	s_setprio 0
	s_barrier
	s_add_i32 s3, s3, s27
	s_mov_b32 m0, s3
	ds_read_b128 v[184:187], v150 offset:49152
	ds_read_b128 v[188:191], v150 offset:50176
	ds_read_b128 v[192:195], v150 offset:51200
	ds_read_b128 v[196:199], v150 offset:52224
	ds_read_b128 v[200:203], v150 offset:53248
	ds_read_b128 v[204:207], v150 offset:54272
	ds_read_b128 v[208:211], v150 offset:55296
	ds_read_b128 v[212:215], v150 offset:56320
	global_load_lds_dwordx4 v251, s[72:73]
	s_add_i32 m0, s3, 0x2000
	s_add_u32 s24, s72, 0xb0080
	s_addc_u32 s25, s73, 0
	s_add_i32 s3, s12, s27
	global_load_lds_dwordx4 v252, s[72:73]
	s_mov_b32 m0, s3
	s_nop 0
	global_load_lds_dwordx4 v134, s[24:25]
	s_add_i32 m0, s3, 0x2000
	s_nop 0
	global_load_lds_dwordx4 v130, s[24:25]
	s_mov_b32 m0, s60
	s_nop 0
	global_load_lds_dwordx4 v253, s[74:75]
	s_mov_b32 m0, s61
	s_nop 0
	global_load_lds_dwordx4 v254, s[74:75]
	s_waitcnt vmcnt(8)
	s_waitcnt lgkmcnt(0)
	s_barrier
	s_setprio 1
	s_waitcnt lgkmcnt(0)
	v_mfma_f32_16x16x32_bf16 v[62:65], v[152:155], v[184:187], v[62:65]
	v_mfma_f32_16x16x32_bf16 v[58:61], v[160:163], v[184:187], v[58:61]
	v_mfma_f32_16x16x32_bf16 v[54:57], v[152:155], v[192:195], v[54:57]
	v_mfma_f32_16x16x32_bf16 v[50:53], v[160:163], v[192:195], v[50:53]
	v_mfma_f32_16x16x32_bf16 v[46:49], v[152:155], v[200:203], v[46:49]
	v_mfma_f32_16x16x32_bf16 v[38:41], v[160:163], v[200:203], v[38:41]
	v_mfma_f32_16x16x32_bf16 v[30:33], v[152:155], v[208:211], v[30:33]
	v_mfma_f32_16x16x32_bf16 v[22:25], v[160:163], v[208:211], v[22:25]
	v_mfma_f32_16x16x32_bf16 v[62:65], v[156:159], v[188:191], v[62:65]
	v_mfma_f32_16x16x32_bf16 v[58:61], v[164:167], v[188:191], v[58:61]
	v_mfma_f32_16x16x32_bf16 v[54:57], v[156:159], v[196:199], v[54:57]
	v_mfma_f32_16x16x32_bf16 v[50:53], v[164:167], v[196:199], v[50:53]
	v_mfma_f32_16x16x32_bf16 v[46:49], v[156:159], v[204:207], v[46:49]
	v_mfma_f32_16x16x32_bf16 v[38:41], v[164:167], v[204:207], v[38:41]
	v_mfma_f32_16x16x32_bf16 v[30:33], v[156:159], v[212:215], v[30:33]
	v_mfma_f32_16x16x32_bf16 v[22:25], v[164:167], v[212:215], v[22:25]
	s_setprio 0
	s_setprio 1
	v_mfma_f32_16x16x32_bf16 v[42:45], v[168:171], v[184:187], v[42:45]
	v_mfma_f32_16x16x32_bf16 v[34:37], v[176:179], v[184:187], v[34:37]
	v_mfma_f32_16x16x32_bf16 v[26:29], v[168:171], v[192:195], v[26:29]
	v_mfma_f32_16x16x32_bf16 v[18:21], v[176:179], v[192:195], v[18:21]
	v_mfma_f32_16x16x32_bf16 v[14:17], v[168:171], v[200:203], v[14:17]
	v_mfma_f32_16x16x32_bf16 v[10:13], v[176:179], v[200:203], v[10:13]
	v_mfma_f32_16x16x32_bf16 v[6:9], v[168:171], v[208:211], v[6:9]
	v_mfma_f32_16x16x32_bf16 v[2:5], v[176:179], v[208:211], v[2:5]
	v_mfma_f32_16x16x32_bf16 v[42:45], v[172:175], v[188:191], v[42:45]
	v_mfma_f32_16x16x32_bf16 v[34:37], v[180:183], v[188:191], v[34:37]
	v_mfma_f32_16x16x32_bf16 v[26:29], v[172:175], v[196:199], v[26:29]
	v_mfma_f32_16x16x32_bf16 v[18:21], v[180:183], v[196:199], v[18:21]
	v_mfma_f32_16x16x32_bf16 v[14:17], v[172:175], v[204:207], v[14:17]
	v_mfma_f32_16x16x32_bf16 v[10:13], v[180:183], v[204:207], v[10:13]
	v_mfma_f32_16x16x32_bf16 v[6:9], v[172:175], v[212:215], v[6:9]
	v_mfma_f32_16x16x32_bf16 v[2:5], v[180:183], v[212:215], v[2:5]
	s_setprio 0
	s_barrier
	s_add_u32 s81, s81, 0x100
	s_addc_u32 s82, s82, 0
	s_cmp_ge_i32 s13, s21
	s_mov_b64 s[68:69], s[70:71]
	s_mov_b32 s12, s13
	s_cbranch_scc0 .LBB0_818
	s_and_b64 vcc, exec, s[16:17]
	s_cbranch_vccz .LBB0_821
	s_barrier

.LBB0_904:
	ds_read_b128 v[130:133], v228
	ds_read_b128 v[134:137], v228 offset:1024
	ds_read_b128 v[154:157], v228 offset:2048
	ds_read_b128 v[158:161], v228 offset:3072
	ds_read_b128 v[162:165], v229
	ds_read_b128 v[166:169], v229 offset:1024
	ds_read_b128 v[170:173], v229 offset:2048
	ds_read_b128 v[174:177], v229 offset:3072
	s_add_u32 s72, s70, 0x100
	s_addc_u32 s73, s71, 0
	s_cmp_eq_u32 s12, 40
	s_cselect_b32 s77, s1, s73
	s_cselect_b32 s76, s0, s72
	s_cselect_b32 s75, s11, s87
	s_cselect_b32 s74, s10, s69
	v_lshl_add_u64 v[210:211], s[70:71], 0, v[146:147]
	s_add_i32 m0, s33, 0xc000
	ds_read_b128 v[178:181], v230
	ds_read_b128 v[182:185], v230 offset:1024
	ds_read_b128 v[186:189], v230 offset:2048
	ds_read_b128 v[190:193], v230 offset:3072
	ds_read_b128 v[194:197], v230 offset:4096
	ds_read_b128 v[198:201], v230 offset:5120
	ds_read_b128 v[202:205], v230 offset:6144
	ds_read_b128 v[206:209], v230 offset:7168
	global_load_lds_dwordx4 v[210:211], off
	v_lshl_add_u64 v[210:211], s[70:71], 0, v[148:149]
	s_add_i32 m0, s33, 0xe000
	s_nop 0
	global_load_lds_dwordx4 v[210:211], off
	s_waitcnt vmcnt(8)
	s_waitcnt lgkmcnt(0)
	s_barrier
	s_setprio 1
	s_waitcnt lgkmcnt(0)
	v_mfma_f32_16x16x32_bf16 v[126:129], v[130:133], v[178:181], v[126:129]
	v_mfma_f32_16x16x32_bf16 v[122:125], v[154:157], v[178:181], v[122:125]
	v_mfma_f32_16x16x32_bf16 v[118:121], v[130:133], v[186:189], v[118:121]
	v_mfma_f32_16x16x32_bf16 v[114:117], v[154:157], v[186:189], v[114:117]
	v_mfma_f32_16x16x32_bf16 v[110:113], v[130:133], v[194:197], v[110:113]
	v_mfma_f32_16x16x32_bf16 v[106:109], v[154:157], v[194:197], v[106:109]
	v_mfma_f32_16x16x32_bf16 v[102:105], v[130:133], v[202:205], v[102:105]
	v_mfma_f32_16x16x32_bf16 v[98:101], v[154:157], v[202:205], v[98:101]
	v_mfma_f32_16x16x32_bf16 v[126:129], v[134:137], v[182:185], v[126:129]
	v_mfma_f32_16x16x32_bf16 v[122:125], v[158:161], v[182:185], v[122:125]
	v_mfma_f32_16x16x32_bf16 v[118:121], v[134:137], v[190:193], v[118:121]
	v_mfma_f32_16x16x32_bf16 v[114:117], v[158:161], v[190:193], v[114:117]
	v_mfma_f32_16x16x32_bf16 v[110:113], v[134:137], v[198:201], v[110:113]
	v_mfma_f32_16x16x32_bf16 v[106:109], v[158:161], v[198:201], v[106:109]
	v_mfma_f32_16x16x32_bf16 v[102:105], v[134:137], v[206:209], v[102:105]
	v_mfma_f32_16x16x32_bf16 v[98:101], v[158:161], v[206:209], v[98:101]
	s_setprio 0
	s_setprio 1
	v_mfma_f32_16x16x32_bf16 v[62:65], v[162:165], v[178:181], v[62:65]
	v_mfma_f32_16x16x32_bf16 v[58:61], v[170:173], v[178:181], v[58:61]
	v_mfma_f32_16x16x32_bf16 v[54:57], v[162:165], v[186:189], v[54:57]
	v_mfma_f32_16x16x32_bf16 v[50:53], v[170:173], v[186:189], v[50:53]
	v_mfma_f32_16x16x32_bf16 v[46:49], v[162:165], v[194:197], v[46:49]
	v_mfma_f32_16x16x32_bf16 v[42:45], v[170:173], v[194:197], v[42:45]
	v_mfma_f32_16x16x32_bf16 v[38:41], v[162:165], v[202:205], v[38:41]
	v_mfma_f32_16x16x32_bf16 v[34:37], v[170:173], v[202:205], v[34:37]
	v_mfma_f32_16x16x32_bf16 v[62:65], v[166:169], v[182:185], v[62:65]
	v_mfma_f32_16x16x32_bf16 v[58:61], v[174:177], v[182:185], v[58:61]
	v_mfma_f32_16x16x32_bf16 v[54:57], v[166:169], v[190:193], v[54:57]
	v_mfma_f32_16x16x32_bf16 v[50:53], v[174:177], v[190:193], v[50:53]
	v_mfma_f32_16x16x32_bf16 v[46:49], v[166:169], v[198:201], v[46:49]
	v_mfma_f32_16x16x32_bf16 v[42:45], v[174:177], v[198:201], v[42:45]
	v_mfma_f32_16x16x32_bf16 v[38:41], v[166:169], v[206:209], v[38:41]
	v_mfma_f32_16x16x32_bf16 v[34:37], v[174:177], v[206:209], v[34:37]
	s_setprio 0
	s_barrier
	s_add_i32 s3, s82, s27
	s_mov_b32 m0, s3
	ds_read_b128 v[178:181], v230 offset:16384
	ds_read_b128 v[182:185], v230 offset:17408
	ds_read_b128 v[186:189], v230 offset:18432
	ds_read_b128 v[190:193], v230 offset:19456
	ds_read_b128 v[194:197], v230 offset:20480
	ds_read_b128 v[198:201], v230 offset:21504
	ds_read_b128 v[202:205], v230 offset:22528
	ds_read_b128 v[206:209], v230 offset:23552
	global_load_lds_dwordx4 v140, s[74:75]
	s_add_i32 m0, s3, 0x2000
	s_add_u32 s24, s74, 0xb0000
	s_addc_u32 s25, s75, 0
	s_add_i32 s3, s83, s27
	global_load_lds_dwordx4 v144, s[74:75]
	s_mov_b32 m0, s3
	s_nop 0
	global_load_lds_dwordx4 v140, s[24:25]
	s_add_i32 m0, s3, 0x2000
	s_nop 0
	global_load_lds_dwordx4 v144, s[24:25]
	s_mov_b32 m0, s33
	s_nop 0
	global_load_lds_dwordx4 v138, s[76:77]
	s_mov_b32 m0, s36
	s_nop 0
	global_load_lds_dwordx4 v142, s[76:77]
	s_waitcnt vmcnt(8)
	s_waitcnt lgkmcnt(0)
	s_barrier
	s_setprio 1
	s_waitcnt lgkmcnt(0)
	v_mfma_f32_16x16x32_bf16 v[94:97], v[130:133], v[178:181], v[94:97]
	v_mfma_f32_16x16x32_bf16 v[90:93], v[154:157], v[178:181], v[90:93]
	v_mfma_f32_16x16x32_bf16 v[86:89], v[130:133], v[186:189], v[86:89]
	v_mfma_f32_16x16x32_bf16 v[82:85], v[154:157], v[186:189], v[82:85]
	v_mfma_f32_16x16x32_bf16 v[78:81], v[130:133], v[194:197], v[78:81]
	v_mfma_f32_16x16x32_bf16 v[74:77], v[154:157], v[194:197], v[74:77]
	v_mfma_f32_16x16x32_bf16 v[70:73], v[130:133], v[202:205], v[70:73]
	v_mfma_f32_16x16x32_bf16 v[66:69], v[154:157], v[202:205], v[66:69]
	v_mfma_f32_16x16x32_bf16 v[94:97], v[134:137], v[182:185], v[94:97]
	v_mfma_f32_16x16x32_bf16 v[90:93], v[158:161], v[182:185], v[90:93]
	v_mfma_f32_16x16x32_bf16 v[86:89], v[134:137], v[190:193], v[86:89]
	v_mfma_f32_16x16x32_bf16 v[82:85], v[158:161], v[190:193], v[82:85]
	v_mfma_f32_16x16x32_bf16 v[78:81], v[134:137], v[198:201], v[78:81]
	v_mfma_f32_16x16x32_bf16 v[74:77], v[158:161], v[198:201], v[74:77]
	v_mfma_f32_16x16x32_bf16 v[70:73], v[134:137], v[206:209], v[70:73]
	v_mfma_f32_16x16x32_bf16 v[66:69], v[158:161], v[206:209], v[66:69]
	s_setprio 0
	s_setprio 1
	v_mfma_f32_16x16x32_bf16 v[30:33], v[162:165], v[178:181], v[30:33]
	v_mfma_f32_16x16x32_bf16 v[26:29], v[170:173], v[178:181], v[26:29]
	v_mfma_f32_16x16x32_bf16 v[22:25], v[162:165], v[186:189], v[22:25]
	v_mfma_f32_16x16x32_bf16 v[18:21], v[170:173], v[186:189], v[18:21]
	v_mfma_f32_16x16x32_bf16 v[14:17], v[162:165], v[194:197], v[14:17]
	v_mfma_f32_16x16x32_bf16 v[10:13], v[170:173], v[194:197], v[10:13]
	v_mfma_f32_16x16x32_bf16 v[6:9], v[162:165], v[202:205], v[6:9]
	v_mfma_f32_16x16x32_bf16 v[2:5], v[170:173], v[202:205], v[2:5]
	v_mfma_f32_16x16x32_bf16 v[30:33], v[166:169], v[182:185], v[30:33]
	v_mfma_f32_16x16x32_bf16 v[26:29], v[174:177], v[182:185], v[26:29]
	v_mfma_f32_16x16x32_bf16 v[22:25], v[166:169], v[190:193], v[22:25]
	v_mfma_f32_16x16x32_bf16 v[18:21], v[174:177], v[190:193], v[18:21]
	v_mfma_f32_16x16x32_bf16 v[14:17], v[166:169], v[198:201], v[14:17]
	v_mfma_f32_16x16x32_bf16 v[10:13], v[174:177], v[198:201], v[10:13]
	v_mfma_f32_16x16x32_bf16 v[6:9], v[166:169], v[206:209], v[6:9]
	v_mfma_f32_16x16x32_bf16 v[2:5], v[174:177], v[206:209], v[2:5]
	s_setprio 0
	s_barrier
	s_add_i32 s3, 0, 0x18000
	s_add_i32 s13, 0, 0x1c000
	v_add_u32_e32 v158, s3, v226
	v_add_u32_e32 v174, s13, v226
	ds_read_b128 v[130:133], v158
	ds_read_b128 v[134:137], v158 offset:1024
	ds_read_b128 v[154:157], v158 offset:2048
	ds_read_b128 v[158:161], v158 offset:3072
	ds_read_b128 v[162:165], v174
	ds_read_b128 v[166:169], v174 offset:1024
	ds_read_b128 v[170:173], v174 offset:2048
	ds_read_b128 v[174:177], v174 offset:3072
	s_add_u32 s24, s76, 0xb0000
	s_addc_u32 s25, s77, 0
	s_mov_b32 m0, s37
	ds_read_b128 v[178:181], v230 offset:32768
	ds_read_b128 v[182:185], v230 offset:33792
	ds_read_b128 v[186:189], v230 offset:34816
	ds_read_b128 v[190:193], v230 offset:35840
	ds_read_b128 v[194:197], v230 offset:36864
	ds_read_b128 v[198:201], v230 offset:37888
	ds_read_b128 v[202:205], v230 offset:38912
	ds_read_b128 v[206:209], v230 offset:39936
	global_load_lds_dwordx4 v138, s[24:25]
	s_mov_b32 m0, s44
	s_nop 0
	global_load_lds_dwordx4 v142, s[24:25]
	s_waitcnt vmcnt(8)
	s_waitcnt lgkmcnt(0)
	s_barrier
	s_setprio 1
	s_waitcnt lgkmcnt(0)
	v_mfma_f32_16x16x32_bf16 v[126:129], v[130:133], v[178:181], v[126:129]
	v_mfma_f32_16x16x32_bf16 v[122:125], v[154:157], v[178:181], v[122:125]
	v_mfma_f32_16x16x32_bf16 v[118:121], v[130:133], v[186:189], v[118:121]
	v_mfma_f32_16x16x32_bf16 v[114:117], v[154:157], v[186:189], v[114:117]
	v_mfma_f32_16x16x32_bf16 v[110:113], v[130:133], v[194:197], v[110:113]
	v_mfma_f32_16x16x32_bf16 v[106:109], v[154:157], v[194:197], v[106:109]
	v_mfma_f32_16x16x32_bf16 v[102:105], v[130:133], v[202:205], v[102:105]
	v_mfma_f32_16x16x32_bf16 v[98:101], v[154:157], v[202:205], v[98:101]
	v_mfma_f32_16x16x32_bf16 v[126:129], v[134:137], v[182:185], v[126:129]
	v_mfma_f32_16x16x32_bf16 v[122:125], v[158:161], v[182:185], v[122:125]
	v_mfma_f32_16x16x32_bf16 v[118:121], v[134:137], v[190:193], v[118:121]
	v_mfma_f32_16x16x32_bf16 v[114:117], v[158:161], v[190:193], v[114:117]
	v_mfma_f32_16x16x32_bf16 v[110:113], v[134:137], v[198:201], v[110:113]
	v_mfma_f32_16x16x32_bf16 v[106:109], v[158:161], v[198:201], v[106:109]
	v_mfma_f32_16x16x32_bf16 v[102:105], v[134:137], v[206:209], v[102:105]
	v_mfma_f32_16x16x32_bf16 v[98:101], v[158:161], v[206:209], v[98:101]
	s_setprio 0
	s_setprio 1
	v_mfma_f32_16x16x32_bf16 v[62:65], v[162:165], v[178:181], v[62:65]
	v_mfma_f32_16x16x32_bf16 v[58:61], v[170:173], v[178:181], v[58:61]
	v_mfma_f32_16x16x32_bf16 v[54:57], v[162:165], v[186:189], v[54:57]
	v_mfma_f32_16x16x32_bf16 v[50:53], v[170:173], v[186:189], v[50:53]
	v_mfma_f32_16x16x32_bf16 v[46:49], v[162:165], v[194:197], v[46:49]
	v_mfma_f32_16x16x32_bf16 v[42:45], v[170:173], v[194:197], v[42:45]
	v_mfma_f32_16x16x32_bf16 v[38:41], v[162:165], v[202:205], v[38:41]
	v_mfma_f32_16x16x32_bf16 v[34:37], v[170:173], v[202:205], v[34:37]
	v_mfma_f32_16x16x32_bf16 v[62:65], v[166:169], v[182:185], v[62:65]
	v_mfma_f32_16x16x32_bf16 v[58:61], v[174:177], v[182:185], v[58:61]
	v_mfma_f32_16x16x32_bf16 v[54:57], v[166:169], v[190:193], v[54:57]
	v_mfma_f32_16x16x32_bf16 v[50:53], v[174:177], v[190:193], v[50:53]
	v_mfma_f32_16x16x32_bf16 v[46:49], v[166:169], v[198:201], v[46:49]
	v_mfma_f32_16x16x32_bf16 v[42:45], v[174:177], v[198:201], v[42:45]
	v_mfma_f32_16x16x32_bf16 v[38:41], v[166:169], v[206:209], v[38:41]
	v_mfma_f32_16x16x32_bf16 v[34:37], v[174:177], v[206:209], v[34:37]
	s_setprio 0
	s_barrier
	s_add_i32 s3, s3, s27
	s_mov_b32 m0, s3
	ds_read_b128 v[178:181], v230 offset:49152
	ds_read_b128 v[182:185], v230 offset:50176
	ds_read_b128 v[186:189], v230 offset:51200
	ds_read_b128 v[190:193], v230 offset:52224
	ds_read_b128 v[194:197], v230 offset:53248
	ds_read_b128 v[198:201], v230 offset:54272
	ds_read_b128 v[202:205], v230 offset:55296
	ds_read_b128 v[206:209], v230 offset:56320
	global_load_lds_dwordx4 v251, s[74:75]
	s_add_i32 m0, s3, 0x2000
	s_add_u32 s24, s74, 0xb0080
	s_addc_u32 s25, s75, 0
	s_add_i32 s3, s13, s27
	global_load_lds_dwordx4 v252, s[74:75]
	s_mov_b32 m0, s3
	s_nop 0
	global_load_lds_dwordx4 v140, s[24:25]
	s_add_i32 m0, s3, 0x2000
	s_nop 0
	global_load_lds_dwordx4 v144, s[24:25]
	s_mov_b32 m0, s79
	s_nop 0
	global_load_lds_dwordx4 v253, s[76:77]
	s_mov_b32 m0, s80
	s_nop 0
	global_load_lds_dwordx4 v254, s[76:77]
	s_waitcnt vmcnt(8)
	s_waitcnt lgkmcnt(0)
	s_barrier
	s_setprio 1
	s_waitcnt lgkmcnt(0)
	v_mfma_f32_16x16x32_bf16 v[94:97], v[130:133], v[178:181], v[94:97]
	v_mfma_f32_16x16x32_bf16 v[90:93], v[154:157], v[178:181], v[90:93]
	v_mfma_f32_16x16x32_bf16 v[86:89], v[130:133], v[186:189], v[86:89]
	v_mfma_f32_16x16x32_bf16 v[82:85], v[154:157], v[186:189], v[82:85]
	v_mfma_f32_16x16x32_bf16 v[78:81], v[130:133], v[194:197], v[78:81]
	v_mfma_f32_16x16x32_bf16 v[74:77], v[154:157], v[194:197], v[74:77]
	v_mfma_f32_16x16x32_bf16 v[70:73], v[130:133], v[202:205], v[70:73]
	v_mfma_f32_16x16x32_bf16 v[66:69], v[154:157], v[202:205], v[66:69]
	v_mfma_f32_16x16x32_bf16 v[94:97], v[134:137], v[182:185], v[94:97]
	v_mfma_f32_16x16x32_bf16 v[90:93], v[158:161], v[182:185], v[90:93]
	v_mfma_f32_16x16x32_bf16 v[86:89], v[134:137], v[190:193], v[86:89]
	v_mfma_f32_16x16x32_bf16 v[82:85], v[158:161], v[190:193], v[82:85]
	v_mfma_f32_16x16x32_bf16 v[78:81], v[134:137], v[198:201], v[78:81]
	v_mfma_f32_16x16x32_bf16 v[74:77], v[158:161], v[198:201], v[74:77]
	v_mfma_f32_16x16x32_bf16 v[70:73], v[134:137], v[206:209], v[70:73]
	v_mfma_f32_16x16x32_bf16 v[66:69], v[158:161], v[206:209], v[66:69]
	s_setprio 0
	s_setprio 1
	v_mfma_f32_16x16x32_bf16 v[30:33], v[162:165], v[178:181], v[30:33]
	v_mfma_f32_16x16x32_bf16 v[26:29], v[170:173], v[178:181], v[26:29]
	v_mfma_f32_16x16x32_bf16 v[22:25], v[162:165], v[186:189], v[22:25]
	v_mfma_f32_16x16x32_bf16 v[18:21], v[170:173], v[186:189], v[18:21]
	v_mfma_f32_16x16x32_bf16 v[14:17], v[162:165], v[194:197], v[14:17]
	v_mfma_f32_16x16x32_bf16 v[10:13], v[170:173], v[194:197], v[10:13]
	v_mfma_f32_16x16x32_bf16 v[6:9], v[162:165], v[202:205], v[6:9]
	v_mfma_f32_16x16x32_bf16 v[2:5], v[170:173], v[202:205], v[2:5]
	v_mfma_f32_16x16x32_bf16 v[30:33], v[166:169], v[182:185], v[30:33]
	v_mfma_f32_16x16x32_bf16 v[26:29], v[174:177], v[182:185], v[26:29]
	v_mfma_f32_16x16x32_bf16 v[22:25], v[166:169], v[190:193], v[22:25]
	v_mfma_f32_16x16x32_bf16 v[18:21], v[174:177], v[190:193], v[18:21]
	v_mfma_f32_16x16x32_bf16 v[14:17], v[166:169], v[198:201], v[14:17]
	v_mfma_f32_16x16x32_bf16 v[10:13], v[174:177], v[198:201], v[10:13]
	v_mfma_f32_16x16x32_bf16 v[6:9], v[166:169], v[206:209], v[6:9]
	v_mfma_f32_16x16x32_bf16 v[2:5], v[174:177], v[206:209], v[2:5]
	s_setprio 0
	s_barrier
	s_add_i32 s12, s12, 2
	s_add_u32 s69, s69, 0x100
	s_addc_u32 s87, s87, 0
	s_cmp_gt_u32 s12, 41
	s_mov_b64 s[70:71], s[72:73]
	s_cbranch_scc0 .LBB0_904
	s_ashr_i32 s3, s68, 3
	s_ashr_i32 s69, s68, 31
	s_mul_hi_i32 s72, s3, 0x6000
	s_mulk_i32 s3, 0x6000
	s_add_u32 s12, s66, s3
	v_mov_b32_e32 v130, v1
	s_addc_u32 s13, s67, s72
	s_lshl_b64 s[24:25], s[68:69], 19
	v_lshl_or_b32 v166, s86, 8, v227
	s_add_u32 s70, s48, s24
	v_add_u32_e32 v160, s78, v130
	v_ashrrev_i32_e32 v167, 31, v166
	s_addc_u32 s71, s49, s25
	v_lshlrev_b64 v[156:157], 1, v[166:167]
	v_ashrrev_i32_e32 v161, 31, v160
	v_lshlrev_b64 v[130:131], 2, v[166:167]
	v_lshl_add_u64 v[162:163], s[70:71], 0, v[156:157]
	v_lshlrev_b64 v[154:155], 11, v[160:161]
	v_add_u32_e32 v170, 16, v160
	v_lshl_add_u64 v[172:173], s[12:13], 0, v[130:131]
	v_lshl_add_u64 v[174:175], v[162:163], 0, v[154:155]
	v_ashrrev_i32_e32 v171, 31, v170
	s_add_u32 s12, s60, s24
	v_lshl_add_u64 v[132:133], s[16:17], 0, v[130:131]
	global_load_dwordx4 v[180:183], v[172:173], off offset:16
	global_load_dwordx4 v[184:187], v[172:173], off
	global_load_dwordx4 v[188:191], v[132:133], off offset:16
	global_load_dwordx4 v[192:195], v[132:133], off
	global_load_dwordx4 v[196:199], v[174:175], off nt
	v_lshlrev_b64 v[204:205], 11, v[170:171]
	s_addc_u32 s13, s61, s25
	v_lshl_add_u64 v[178:179], v[162:163], 0, v[204:205]
	s_add_u32 s24, s62, s3
	global_load_dwordx4 v[200:203], v[178:179], off nt
	s_addc_u32 s25, s63, s72
	v_lshl_add_u64 v[176:177], s[24:25], 0, v[130:131]
	global_load_dwordx4 v[134:137], v[176:177], off
	global_load_dwordx4 v[130:133], v[176:177], off offset:16
	v_lshl_add_u64 v[158:159], s[12:13], 0, v[156:157]
	s_lshl_b32 s12, s68, 8
	v_lshl_add_u64 v[164:165], v[158:159], 0, v[154:155]
	v_add_u32_e32 v154, s12, v160
	v_ashrrev_i32_e32 v155, 31, v154
	v_lshlrev_b64 v[168:169], 11, v[154:155]
	v_lshl_add_u64 v[168:169], s[20:21], 0, v[168:169]
	v_add_u32_e32 v170, s12, v170
	v_lshl_add_u64 v[168:169], v[168:169], 0, v[156:157]
	v_ashrrev_i32_e32 v171, 31, v170
	v_lshlrev_b64 v[170:171], 11, v[170:171]
	v_lshl_add_u64 v[170:171], s[20:21], 0, v[170:171]
	s_waitcnt vmcnt(0)
	v_pk_add_f32 v[182:183], v[182:183], 1.0 op_sel_hi:[1,0]
	v_pk_add_f32 v[186:187], v[186:187], 1.0 op_sel_hi:[1,0]
	v_pk_add_f32 v[184:185], v[184:185], 1.0 op_sel_hi:[1,0]
	v_pk_add_f32 v[180:181], v[180:181], 1.0 op_sel_hi:[1,0]
	v_pk_mul_f32 v[216:217], v[194:195], v[186:187]
	v_pk_mul_f32 v[218:219], v[192:193], v[184:185]
	v_pk_mul_f32 v[220:221], v[190:191], v[182:183]
	v_pk_mul_f32 v[222:223], v[188:189], v[180:181]
	v_cvt_f32_f16_e32 v180, v198
	v_cvt_f32_f16_sdwa v181, v198 dst_sel:DWORD dst_unused:UNUSED_PAD src0_sel:WORD_1
	v_cvt_f32_f16_e32 v182, v199
	v_cvt_f32_f16_sdwa v183, v199 dst_sel:DWORD dst_unused:UNUSED_PAD src0_sel:WORD_1
	v_cvt_f32_f16_e32 v184, v196
	v_cvt_f32_f16_sdwa v185, v196 dst_sel:DWORD dst_unused:UNUSED_PAD src0_sel:WORD_1
	v_cvt_f32_f16_e32 v186, v197
	v_cvt_f32_f16_sdwa v187, v197 dst_sel:DWORD dst_unused:UNUSED_PAD src0_sel:WORD_1
	v_cvt_f32_f16_e32 v188, v202
	v_cvt_f32_f16_sdwa v189, v202 dst_sel:DWORD dst_unused:UNUSED_PAD src0_sel:WORD_1
	v_cvt_f32_f16_e32 v190, v203
	v_cvt_f32_f16_sdwa v191, v203 dst_sel:DWORD dst_unused:UNUSED_PAD src0_sel:WORD_1
	v_cvt_f32_f16_e32 v192, v200
	v_cvt_f32_f16_sdwa v193, v200 dst_sel:DWORD dst_unused:UNUSED_PAD src0_sel:WORD_1
	v_cvt_f32_f16_e32 v194, v201
	v_cvt_f32_f16_sdwa v195, v201 dst_sel:DWORD dst_unused:UNUSED_PAD src0_sel:WORD_1
	v_pk_fma_f32 v[128:129], v[128:129], v[136:137], v[186:187]
	v_pk_fma_f32 v[126:127], v[126:127], v[134:135], v[184:185]
	v_pk_fma_f32 v[124:125], v[124:125], v[132:133], v[182:183]
	v_pk_fma_f32 v[122:123], v[122:123], v[130:131], v[180:181]
	v_cvt_pk_f16_f32 v183, v124, v125
	v_cvt_pk_f16_f32 v181, v128, v129
	v_cvt_pk_f16_f32 v182, v122, v123
	v_cvt_pk_f16_f32 v180, v126, v127
	v_pk_fma_f32 v[120:121], v[120:121], v[136:137], v[194:195]
	v_pk_fma_f32 v[118:119], v[118:119], v[134:135], v[192:193]
	v_pk_fma_f32 v[116:117], v[116:117], v[132:133], v[190:191]
	v_pk_fma_f32 v[114:115], v[114:115], v[130:131], v[188:189]
	v_pk_mul_f32 v[188:189], v[216:217], v[128:129]
	v_pk_mul_f32 v[190:191], v[218:219], v[126:127]
	global_store_dwordx4 v[164:165], v[180:183], off
	v_pk_mul_f32 v[192:193], v[220:221], v[124:125]
	v_pk_mul_f32 v[194:195], v[222:223], v[122:123]
	v_cvt_pk_bf16_f32 v180, v190, v191
	v_cvt_pk_bf16_f32 v181, v188, v189
	v_cvt_pk_f16_f32 v187, v116, v117
	v_cvt_pk_f16_f32 v185, v120, v121
	v_cvt_pk_f16_f32 v186, v114, v115
	v_cvt_pk_bf16_f32 v182, v194, v195
	v_cvt_pk_bf16_f32 v183, v192, v193
	global_store_dwordx4 v[168:169], v[180:183], off
	v_cvt_pk_f16_f32 v184, v118, v119
	v_pk_mul_f32 v[188:189], v[222:223], v[114:115]
	v_lshl_add_u64 v[180:181], v[158:159], 0, v[204:205]
	global_store_dwordx4 v[180:181], v[184:187], off
	v_pk_mul_f32 v[182:183], v[218:219], v[118:119]
	v_add_u32_e32 v192, 48, v160
	v_pk_mul_f32 v[184:185], v[216:217], v[120:121]
	v_pk_mul_f32 v[186:187], v[220:221], v[116:117]
	v_cvt_pk_bf16_f32 v182, v182, v183
	v_cvt_pk_bf16_f32 v183, v184, v185
	v_cvt_pk_bf16_f32 v184, v188, v189
	v_ashrrev_i32_e32 v193, 31, v192
	v_cvt_pk_bf16_f32 v185, v186, v187
	v_lshl_add_u64 v[186:187], v[170:171], 0, v[156:157]
	global_store_dwordx4 v[186:187], v[182:185], off
	v_mul_f32_e32 v127, v127, v127
	v_mul_f32_e32 v129, v129, v129
	v_add_u32_e32 v182, 32, v160
	v_ashrrev_i32_e32 v183, 31, v182
	v_lshlrev_b64 v[170:171], 11, v[182:183]
	v_lshl_add_u64 v[188:189], v[162:163], 0, v[170:171]
	global_load_dwordx4 v[194:197], v[188:189], off nt
	v_lshlrev_b64 v[184:185], 11, v[192:193]
	v_lshl_add_u64 v[190:191], v[162:163], 0, v[184:185]
	global_load_dwordx4 v[198:201], v[190:191], off nt
	v_add_u32_e32 v182, s12, v182
	v_add_u32_e32 v192, s12, v192
	v_ashrrev_i32_e32 v183, 31, v182
	v_ashrrev_i32_e32 v193, 31, v192
	v_lshlrev_b64 v[182:183], 11, v[182:183]
	v_lshlrev_b64 v[192:193], 11, v[192:193]
	v_lshl_add_u64 v[182:183], s[20:21], 0, v[182:183]
	v_lshl_add_u64 v[202:203], s[20:21], 0, v[192:193]
	v_lshl_add_u64 v[192:193], v[182:183], 0, v[156:157]
	v_lshl_add_u64 v[170:171], v[158:159], 0, v[170:171]
	v_lshl_add_u64 v[184:185], v[158:159], 0, v[184:185]
	v_mul_f32_e32 v123, v123, v123
	v_mul_f32_e32 v125, v125, v125
	v_fmac_f32_e32 v127, v126, v126
	v_fmac_f32_e32 v129, v128, v128
	v_fmac_f32_e32 v123, v122, v122
	v_fmac_f32_e32 v125, v124, v124
	v_add_f32_e32 v122, v127, v129
	v_add_f32_e32 v123, v123, v125
	v_add_f32_e32 v122, v122, v123
	s_waitcnt vmcnt(1)
	v_cvt_f32_f16_e32 v182, v196
	v_cvt_f32_f16_sdwa v183, v196 dst_sel:DWORD dst_unused:UNUSED_PAD src0_sel:WORD_1
	v_cvt_f32_f16_e32 v196, v197
	v_cvt_f32_f16_sdwa v197, v197 dst_sel:DWORD dst_unused:UNUSED_PAD src0_sel:WORD_1
	v_cvt_f32_f16_e32 v204, v194
	v_cvt_f32_f16_sdwa v205, v194 dst_sel:DWORD dst_unused:UNUSED_PAD src0_sel:WORD_1
	v_cvt_f32_f16_e32 v194, v195
	v_cvt_f32_f16_sdwa v195, v195 dst_sel:DWORD dst_unused:UNUSED_PAD src0_sel:WORD_1
	s_waitcnt vmcnt(0)
	v_cvt_f32_f16_e32 v206, v200
	v_cvt_f32_f16_sdwa v207, v200 dst_sel:DWORD dst_unused:UNUSED_PAD src0_sel:WORD_1
	v_cvt_f32_f16_e32 v208, v198
	v_cvt_f32_f16_sdwa v209, v198 dst_sel:DWORD dst_unused:UNUSED_PAD src0_sel:WORD_1
	v_cvt_f32_f16_e32 v198, v199
	v_cvt_f32_f16_sdwa v199, v199 dst_sel:DWORD dst_unused:UNUSED_PAD src0_sel:WORD_1
	v_cvt_f32_f16_e32 v200, v201
	v_cvt_f32_f16_sdwa v201, v201 dst_sel:DWORD dst_unused:UNUSED_PAD src0_sel:WORD_1
	v_pk_fma_f32 v[112:113], v[112:113], v[136:137], v[194:195]
	v_pk_fma_f32 v[110:111], v[110:111], v[134:135], v[204:205]
	v_pk_fma_f32 v[108:109], v[108:109], v[132:133], v[196:197]
	v_pk_fma_f32 v[106:107], v[106:107], v[130:131], v[182:183]
	v_cvt_pk_f16_f32 v197, v108, v109
	v_cvt_pk_f16_f32 v195, v112, v113
	v_cvt_pk_f16_f32 v196, v106, v107
	v_cvt_pk_f16_f32 v194, v110, v111
	v_pk_mul_f32 v[182:183], v[216:217], v[112:113]
	v_pk_fma_f32 v[104:105], v[104:105], v[136:137], v[198:199]
	v_pk_fma_f32 v[102:103], v[102:103], v[134:135], v[208:209]
	v_pk_fma_f32 v[98:99], v[98:99], v[130:131], v[206:207]
	v_pk_mul_f32 v[204:205], v[218:219], v[110:111]
	v_pk_mul_f32 v[206:207], v[220:221], v[108:109]
	global_store_dwordx4 v[170:171], v[194:197], off
	v_pk_fma_f32 v[100:101], v[100:101], v[132:133], v[200:201]
	v_pk_mul_f32 v[208:209], v[222:223], v[106:107]
	v_cvt_pk_bf16_f32 v194, v204, v205
	v_cvt_pk_bf16_f32 v195, v182, v183
	v_add_u32_e32 v182, 0x80, v160
	v_cvt_pk_f16_f32 v199, v104, v105
	v_cvt_pk_f16_f32 v198, v102, v103
	v_cvt_pk_bf16_f32 v196, v208, v209
	v_cvt_pk_bf16_f32 v197, v206, v207
	v_ashrrev_i32_e32 v183, 31, v182
	v_add_u32_e32 v206, 0x90, v160
	v_cvt_pk_f16_f32 v201, v100, v101
	v_cvt_pk_f16_f32 v200, v98, v99
	v_pk_mul_f32 v[210:211], v[216:217], v[104:105]
	v_pk_mul_f32 v[212:213], v[218:219], v[102:103]
	global_store_dwordx4 v[192:193], v[194:197], off
	global_store_dwordx4 v[184:185], v[198:201], off
	v_ashrrev_i32_e32 v207, 31, v206
	v_lshl_add_u64 v[196:197], v[202:203], 0, v[156:157]
	v_cvt_pk_bf16_f32 v198, v212, v213
	v_cvt_pk_bf16_f32 v199, v210, v211
	v_lshlrev_b64 v[194:195], 11, v[182:183]
	v_pk_mul_f32 v[214:215], v[220:221], v[100:101]
	v_pk_mul_f32 v[224:225], v[222:223], v[98:99]
	v_lshlrev_b64 v[208:209], 11, v[206:207]
	v_cvt_pk_bf16_f32 v200, v224, v225
	v_cvt_pk_bf16_f32 v201, v214, v215
	global_store_dwordx4 v[196:197], v[198:201], off
	v_lshl_add_u64 v[204:205], v[162:163], 0, v[208:209]
	global_load_dwordx4 v[236:239], v[204:205], off nt
	v_lshl_add_u64 v[198:199], v[162:163], 0, v[194:195]
	global_load_dwordx4 v[232:235], v[198:199], off nt
	v_lshl_add_u64 v[212:213], v[158:159], 0, v[194:195]
	v_add_u32_e32 v182, s12, v182
	v_add_u32_e32 v194, s12, v206
	v_ashrrev_i32_e32 v183, 31, v182
	v_ashrrev_i32_e32 v195, 31, v194
	v_lshlrev_b64 v[182:183], 11, v[182:183]
	v_lshlrev_b64 v[194:195], 11, v[194:195]
	v_lshl_add_u64 v[182:183], s[20:21], 0, v[182:183]
	v_lshl_add_u64 v[194:195], s[20:21], 0, v[194:195]
	v_lshl_add_u64 v[210:211], v[158:159], 0, v[208:209]
	v_lshl_add_u64 v[214:215], v[182:183], 0, v[156:157]
	v_lshl_add_u64 v[208:209], v[194:195], 0, v[156:157]
	v_add_u32_e32 v200, 0xa0, v160
	v_ashrrev_i32_e32 v201, 31, v200
	v_lshlrev_b64 v[240:241], 11, v[200:201]
	v_lshl_add_u64 v[202:203], v[162:163], 0, v[240:241]
	s_waitcnt vmcnt(0)
	v_cvt_f32_f16_e32 v182, v234
	v_cvt_f32_f16_sdwa v183, v234 dst_sel:DWORD dst_unused:UNUSED_PAD src0_sel:WORD_1
	v_cvt_f32_f16_e32 v194, v235
	v_cvt_f32_f16_sdwa v195, v235 dst_sel:DWORD dst_unused:UNUSED_PAD src0_sel:WORD_1
	v_cvt_f32_f16_e32 v206, v232
	v_cvt_f32_f16_sdwa v207, v232 dst_sel:DWORD dst_unused:UNUSED_PAD src0_sel:WORD_1
	v_cvt_f32_f16_e32 v224, v233
	v_cvt_f32_f16_sdwa v225, v233 dst_sel:DWORD dst_unused:UNUSED_PAD src0_sel:WORD_1
	v_cvt_f32_f16_e32 v232, v238
	v_cvt_f32_f16_sdwa v233, v238 dst_sel:DWORD dst_unused:UNUSED_PAD src0_sel:WORD_1
	v_cvt_f32_f16_e32 v234, v239
	v_cvt_f32_f16_sdwa v235, v239 dst_sel:DWORD dst_unused:UNUSED_PAD src0_sel:WORD_1
	v_cvt_f32_f16_e32 v238, v236
	v_cvt_f32_f16_sdwa v239, v236 dst_sel:DWORD dst_unused:UNUSED_PAD src0_sel:WORD_1
	v_cvt_f32_f16_e32 v236, v237
	v_cvt_f32_f16_sdwa v237, v237 dst_sel:DWORD dst_unused:UNUSED_PAD src0_sel:WORD_1
	v_pk_fma_f32 v[96:97], v[96:97], v[136:137], v[224:225]
	v_pk_fma_f32 v[94:95], v[94:95], v[134:135], v[206:207]
	v_pk_fma_f32 v[92:93], v[92:93], v[132:133], v[194:195]
	v_pk_fma_f32 v[90:91], v[90:91], v[130:131], v[182:183]
	v_pk_fma_f32 v[84:85], v[84:85], v[132:133], v[234:235]
	v_pk_fma_f32 v[82:83], v[82:83], v[130:131], v[232:233]
	v_cvt_pk_f16_f32 v235, v92, v93
	v_cvt_pk_f16_f32 v233, v96, v97
	v_cvt_pk_f16_f32 v234, v90, v91
	v_cvt_pk_f16_f32 v232, v94, v95
	v_pk_mul_f32 v[206:207], v[220:221], v[92:93]
	v_pk_mul_f32 v[182:183], v[216:217], v[96:97]
	v_pk_mul_f32 v[194:195], v[218:219], v[94:95]
	v_pk_mul_f32 v[224:225], v[222:223], v[90:91]
	global_store_dwordx4 v[212:213], v[232:235], off
	v_pk_fma_f32 v[88:89], v[88:89], v[136:137], v[236:237]
	v_pk_fma_f32 v[86:87], v[86:87], v[134:135], v[238:239]
	v_cvt_pk_bf16_f32 v232, v194, v195
	v_cvt_pk_bf16_f32 v233, v182, v183
	v_cvt_pk_bf16_f32 v234, v224, v225
	v_cvt_pk_bf16_f32 v235, v206, v207
	v_add_u32_e32 v206, 0xb0, v160
	v_ashrrev_i32_e32 v207, 31, v206
	v_cvt_pk_f16_f32 v239, v84, v85
	v_cvt_pk_f16_f32 v237, v88, v89
	v_cvt_pk_f16_f32 v238, v82, v83
	v_cvt_pk_f16_f32 v236, v86, v87
	v_pk_mul_f32 v[242:243], v[216:217], v[88:89]
	v_pk_mul_f32 v[244:245], v[218:219], v[86:87]
	v_pk_mul_f32 v[246:247], v[220:221], v[84:85]
	v_pk_mul_f32 v[248:249], v[222:223], v[82:83]
	global_store_dwordx4 v[214:215], v[232:235], off
	global_store_dwordx4 v[210:211], v[236:239], off
	v_lshlrev_b64 v[194:195], 11, v[206:207]
	v_cvt_pk_bf16_f32 v232, v244, v245
	v_cvt_pk_bf16_f32 v233, v242, v243
	v_cvt_pk_bf16_f32 v234, v248, v249
	v_cvt_pk_bf16_f32 v235, v246, v247
	global_store_dwordx4 v[208:209], v[232:235], off
	global_load_dwordx4 v[232:235], v[202:203], off nt
	v_lshl_add_u64 v[224:225], v[162:163], 0, v[194:195]
	global_load_dwordx4 v[160:163], v[224:225], off nt
	v_lshl_add_u64 v[182:183], v[158:159], 0, v[240:241]
	v_lshl_add_u64 v[194:195], v[158:159], 0, v[194:195]
	v_add_u32_e32 v158, s12, v200
	v_add_u32_e32 v200, s12, v206
	v_ashrrev_i32_e32 v159, 31, v158
	v_ashrrev_i32_e32 v201, 31, v200
	v_lshlrev_b64 v[158:159], 11, v[158:159]
	v_lshlrev_b64 v[200:201], 11, v[200:201]
	v_lshl_add_u64 v[158:159], s[20:21], 0, v[158:159]
	v_lshl_add_u64 v[200:201], s[20:21], 0, v[200:201]
	v_lshl_add_u64 v[206:207], v[158:159], 0, v[156:157]
	v_lshl_add_u64 v[200:201], v[200:201], 0, v[156:157]
	s_waitcnt vmcnt(1)
	v_cvt_f32_f16_e32 v158, v234
	v_cvt_f32_f16_sdwa v159, v234 dst_sel:DWORD dst_unused:UNUSED_PAD src0_sel:WORD_1
	v_cvt_f32_f16_e32 v156, v235
	v_cvt_f32_f16_sdwa v157, v235 dst_sel:DWORD dst_unused:UNUSED_PAD src0_sel:WORD_1
	v_cvt_f32_f16_e32 v234, v232
	v_cvt_f32_f16_sdwa v235, v232 dst_sel:DWORD dst_unused:UNUSED_PAD src0_sel:WORD_1
	v_cvt_f32_f16_e32 v232, v233
	v_cvt_f32_f16_sdwa v233, v233 dst_sel:DWORD dst_unused:UNUSED_PAD src0_sel:WORD_1
	s_waitcnt vmcnt(0)
	v_cvt_f32_f16_e32 v236, v162
	v_cvt_f32_f16_sdwa v237, v162 dst_sel:DWORD dst_unused:UNUSED_PAD src0_sel:WORD_1
	v_cvt_f32_f16_e32 v238, v163
	v_cvt_f32_f16_sdwa v239, v163 dst_sel:DWORD dst_unused:UNUSED_PAD src0_sel:WORD_1
	v_cvt_f32_f16_e32 v240, v160
	v_cvt_f32_f16_sdwa v241, v160 dst_sel:DWORD dst_unused:UNUSED_PAD src0_sel:WORD_1
	v_cvt_f32_f16_e32 v242, v161
	v_cvt_f32_f16_sdwa v243, v161 dst_sel:DWORD dst_unused:UNUSED_PAD src0_sel:WORD_1
	v_pk_fma_f32 v[160:161], v[80:81], v[136:137], v[232:233]
	v_pk_fma_f32 v[162:163], v[78:79], v[134:135], v[234:235]
	v_pk_fma_f32 v[156:157], v[76:77], v[132:133], v[156:157]
	v_pk_fma_f32 v[158:159], v[74:75], v[130:131], v[158:159]
	v_pk_fma_f32 v[74:75], v[68:69], v[132:133], v[238:239]
	v_pk_fma_f32 v[76:77], v[66:67], v[130:131], v[236:237]
	v_cvt_pk_f16_f32 v69, v156, v157
	v_cvt_pk_f16_f32 v67, v160, v161
	v_cvt_pk_f16_f32 v68, v158, v159
	v_cvt_pk_f16_f32 v66, v162, v163
	v_pk_fma_f32 v[78:79], v[72:73], v[136:137], v[242:243]
	v_pk_fma_f32 v[80:81], v[70:71], v[134:135], v[240:241]
	v_pk_mul_f32 v[130:131], v[216:217], v[160:161]
	v_pk_mul_f32 v[132:133], v[218:219], v[162:163]
	v_pk_mul_f32 v[134:135], v[220:221], v[156:157]
	v_pk_mul_f32 v[136:137], v[222:223], v[158:159]
	global_store_dwordx4 v[182:183], v[66:69], off
	v_cvt_pk_f16_f32 v73, v74, v75
	v_cvt_pk_f16_f32 v71, v78, v79
	v_cvt_pk_bf16_f32 v66, v132, v133
	v_cvt_pk_bf16_f32 v67, v130, v131
	v_cvt_pk_bf16_f32 v68, v136, v137
	v_cvt_pk_bf16_f32 v69, v134, v135
	v_cvt_pk_f16_f32 v72, v76, v77
	v_cvt_pk_f16_f32 v70, v80, v81
	v_pk_mul_f32 v[216:217], v[216:217], v[78:79]
	v_pk_mul_f32 v[218:219], v[218:219], v[80:81]
	v_pk_mul_f32 v[220:221], v[220:221], v[74:75]
	v_pk_mul_f32 v[222:223], v[222:223], v[76:77]
	global_store_dwordx4 v[206:207], v[66:69], off
	global_store_dwordx4 v[194:195], v[70:73], off
	s_nop 0
	v_cvt_pk_bf16_f32 v66, v218, v219
	v_cvt_pk_bf16_f32 v67, v216, v217
	v_cvt_pk_bf16_f32 v68, v222, v223
	v_cvt_pk_bf16_f32 v69, v220, v221
	global_store_dwordx4 v[200:201], v[66:69], off
	global_load_dwordx4 v[130:133], v[172:173], off offset:512
	global_load_dwordx4 v[134:137], v[172:173], off offset:528
	s_nop 0
	global_load_dwordx4 v[172:175], v[174:175], off offset:256 nt
	s_nop 0
	global_load_dwordx4 v[216:219], v[178:179], off offset:256 nt
	v_or_b32_e32 v66, 0x80, v166
	v_ashrrev_i32_e32 v67, 31, v66
	v_lshl_add_u64 v[66:67], v[66:67], 2, s[16:17]
	global_load_dwordx4 v[220:223], v[66:67], off
	global_load_dwordx4 v[232:235], v[66:67], off offset:16
	global_load_dwordx4 v[70:73], v[176:177], off offset:512
	s_nop 0
	global_load_dwordx4 v[66:69], v[176:177], off offset:528
	s_waitcnt vmcnt(7)
	v_pk_add_f32 v[132:133], v[132:133], 1.0 op_sel_hi:[1,0]
	v_pk_add_f32 v[166:167], v[130:131], 1.0 op_sel_hi:[1,0]
	s_waitcnt vmcnt(5)
	v_cvt_f32_f16_e32 v178, v174
	v_cvt_f32_f16_sdwa v179, v174 dst_sel:DWORD dst_unused:UNUSED_PAD src0_sel:WORD_1
	v_cvt_f32_f16_e32 v174, v175
	v_cvt_f32_f16_sdwa v175, v175 dst_sel:DWORD dst_unused:UNUSED_PAD src0_sel:WORD_1
	v_cvt_f32_f16_e32 v236, v172
	v_cvt_f32_f16_sdwa v237, v172 dst_sel:DWORD dst_unused:UNUSED_PAD src0_sel:WORD_1
	v_cvt_f32_f16_e32 v172, v173
	v_cvt_f32_f16_sdwa v173, v173 dst_sel:DWORD dst_unused:UNUSED_PAD src0_sel:WORD_1
	s_waitcnt vmcnt(4)
	v_cvt_f32_f16_e32 v238, v218
	v_cvt_f32_f16_sdwa v239, v218 dst_sel:DWORD dst_unused:UNUSED_PAD src0_sel:WORD_1
	v_cvt_f32_f16_e32 v218, v219
	v_cvt_f32_f16_sdwa v219, v219 dst_sel:DWORD dst_unused:UNUSED_PAD src0_sel:WORD_1
	v_cvt_f32_f16_e32 v240, v216
	v_cvt_f32_f16_sdwa v241, v216 dst_sel:DWORD dst_unused:UNUSED_PAD src0_sel:WORD_1
	v_cvt_f32_f16_e32 v216, v217
	v_cvt_f32_f16_sdwa v217, v217 dst_sel:DWORD dst_unused:UNUSED_PAD src0_sel:WORD_1
	v_pk_add_f32 v[136:137], v[136:137], 1.0 op_sel_hi:[1,0]
	v_pk_add_f32 v[176:177], v[134:135], 1.0 op_sel_hi:[1,0]
	s_waitcnt vmcnt(3)
	v_pk_mul_f32 v[130:131], v[222:223], v[132:133]
	s_waitcnt vmcnt(1)
	v_pk_fma_f32 v[64:65], v[64:65], v[72:73], v[172:173]
	v_pk_fma_f32 v[62:63], v[62:63], v[70:71], v[236:237]
	s_waitcnt vmcnt(0)
	v_pk_fma_f32 v[60:61], v[60:61], v[68:69], v[174:175]
	v_pk_fma_f32 v[58:59], v[58:59], v[66:67], v[178:179]
	v_pk_mul_f32 v[132:133], v[220:221], v[166:167]
	v_pk_mul_f32 v[134:135], v[234:235], v[136:137]
	v_pk_mul_f32 v[136:137], v[232:233], v[176:177]
	v_cvt_pk_f16_f32 v175, v60, v61
	v_cvt_pk_f16_f32 v173, v64, v65
	v_cvt_pk_f16_f32 v174, v58, v59
	v_cvt_pk_f16_f32 v172, v62, v63
	v_pk_mul_f32 v[166:167], v[130:131], v[64:65]
	v_pk_fma_f32 v[56:57], v[56:57], v[72:73], v[216:217]
	v_pk_fma_f32 v[54:55], v[54:55], v[70:71], v[240:241]
	v_pk_fma_f32 v[52:53], v[52:53], v[68:69], v[218:219]
	v_pk_fma_f32 v[50:51], v[50:51], v[66:67], v[238:239]
	v_pk_mul_f32 v[216:217], v[132:133], v[62:63]
	v_pk_mul_f32 v[218:219], v[134:135], v[60:61]
	v_pk_mul_f32 v[220:221], v[136:137], v[58:59]
	global_store_dwordx4 v[164:165], v[172:175], off offset:256
	v_cvt_pk_bf16_f32 v164, v216, v217
	v_cvt_pk_bf16_f32 v165, v166, v167
	v_cvt_pk_bf16_f32 v166, v220, v221
	v_cvt_pk_bf16_f32 v167, v218, v219
	v_cvt_pk_f16_f32 v179, v52, v53
	v_cvt_pk_f16_f32 v177, v56, v57
	v_cvt_pk_f16_f32 v178, v50, v51
	v_cvt_pk_f16_f32 v176, v54, v55
	v_pk_mul_f32 v[222:223], v[130:131], v[56:57]
	v_pk_mul_f32 v[232:233], v[132:133], v[54:55]
	v_pk_mul_f32 v[234:235], v[134:135], v[52:53]
	v_pk_mul_f32 v[236:237], v[136:137], v[50:51]
	global_store_dwordx4 v[168:169], v[164:167], off offset:256
	global_store_dwordx4 v[180:181], v[176:179], off offset:256
	v_mul_f32_e32 v63, v63, v63
	v_cvt_pk_bf16_f32 v164, v232, v233
	v_cvt_pk_bf16_f32 v165, v222, v223
	v_cvt_pk_bf16_f32 v166, v236, v237
	v_cvt_pk_bf16_f32 v167, v234, v235
	global_store_dwordx4 v[186:187], v[164:167], off offset:256
	global_load_dwordx4 v[164:167], v[188:189], off offset:256 nt
	s_nop 0
	global_load_dwordx4 v[172:175], v[190:191], off offset:256 nt
	v_mul_f32_e32 v65, v65, v65
	v_mul_f32_e32 v59, v59, v59
	v_mul_f32_e32 v61, v61, v61
	v_fmac_f32_e32 v63, v62, v62
	v_fmac_f32_e32 v65, v64, v64
	v_fmac_f32_e32 v59, v58, v58
	v_fmac_f32_e32 v61, v60, v60
	v_add_f32_e32 v58, v63, v65
	v_add_f32_e32 v59, v59, v61
	v_add_f32_e32 v58, v58, v59
	v_add_f32_e32 v59, v122, v58
	v_xor_b32_e32 v58, 32, v231
	s_waitcnt vmcnt(1)
	v_cvt_f32_f16_e32 v168, v166
	v_cvt_f32_f16_sdwa v169, v166 dst_sel:DWORD dst_unused:UNUSED_PAD src0_sel:WORD_1
	v_cvt_f32_f16_e32 v166, v167
	v_cvt_f32_f16_sdwa v167, v167 dst_sel:DWORD dst_unused:UNUSED_PAD src0_sel:WORD_1
	v_cvt_f32_f16_e32 v176, v164
	v_cvt_f32_f16_sdwa v177, v164 dst_sel:DWORD dst_unused:UNUSED_PAD src0_sel:WORD_1
	v_cvt_f32_f16_e32 v164, v165
	v_cvt_f32_f16_sdwa v165, v165 dst_sel:DWORD dst_unused:UNUSED_PAD src0_sel:WORD_1
	s_waitcnt vmcnt(0)
	v_cvt_f32_f16_e32 v178, v174
	v_cvt_f32_f16_sdwa v179, v174 dst_sel:DWORD dst_unused:UNUSED_PAD src0_sel:WORD_1
	v_cvt_f32_f16_e32 v174, v175
	v_cvt_f32_f16_sdwa v175, v175 dst_sel:DWORD dst_unused:UNUSED_PAD src0_sel:WORD_1
	v_cvt_f32_f16_e32 v180, v172
	v_cvt_f32_f16_sdwa v181, v172 dst_sel:DWORD dst_unused:UNUSED_PAD src0_sel:WORD_1
	v_cvt_f32_f16_e32 v172, v173
	v_cvt_f32_f16_sdwa v173, v173 dst_sel:DWORD dst_unused:UNUSED_PAD src0_sel:WORD_1
	v_pk_fma_f32 v[48:49], v[48:49], v[72:73], v[164:165]
	v_pk_fma_f32 v[46:47], v[46:47], v[70:71], v[176:177]
	v_pk_fma_f32 v[44:45], v[44:45], v[68:69], v[166:167]
	v_pk_fma_f32 v[42:43], v[42:43], v[66:67], v[168:169]
	v_cvt_pk_f16_f32 v167, v44, v45
	v_cvt_pk_f16_f32 v165, v48, v49
	v_cvt_pk_f16_f32 v166, v42, v43
	v_cvt_pk_f16_f32 v164, v46, v47
	v_pk_fma_f32 v[40:41], v[40:41], v[72:73], v[172:173]
	v_pk_fma_f32 v[38:39], v[38:39], v[70:71], v[180:181]
	v_pk_fma_f32 v[36:37], v[36:37], v[68:69], v[174:175]
	v_pk_fma_f32 v[34:35], v[34:35], v[66:67], v[178:179]
	v_pk_mul_f32 v[168:169], v[130:131], v[48:49]
	v_pk_mul_f32 v[176:177], v[132:133], v[46:47]
	v_pk_mul_f32 v[178:179], v[134:135], v[44:45]
	v_pk_mul_f32 v[180:181], v[136:137], v[42:43]
	global_store_dwordx4 v[170:171], v[164:167], off offset:256
	v_cvt_pk_f16_f32 v175, v36, v37
	v_cvt_pk_f16_f32 v173, v40, v41
	v_cvt_pk_bf16_f32 v164, v176, v177
	v_cvt_pk_bf16_f32 v165, v168, v169
	v_cvt_pk_bf16_f32 v166, v180, v181
	v_cvt_pk_bf16_f32 v167, v178, v179
	v_cvt_pk_f16_f32 v174, v34, v35
	v_cvt_pk_f16_f32 v172, v38, v39
	v_pk_mul_f32 v[186:187], v[130:131], v[40:41]
	v_pk_mul_f32 v[188:189], v[132:133], v[38:39]
	v_pk_mul_f32 v[190:191], v[134:135], v[36:37]
	v_pk_mul_f32 v[216:217], v[136:137], v[34:35]
	global_store_dwordx4 v[192:193], v[164:167], off offset:256
	global_store_dwordx4 v[184:185], v[172:175], off offset:256
	s_nop 0
	v_cvt_pk_bf16_f32 v164, v188, v189
	v_cvt_pk_bf16_f32 v165, v186, v187
	v_cvt_pk_bf16_f32 v166, v216, v217
	v_cvt_pk_bf16_f32 v167, v190, v191
	global_store_dwordx4 v[196:197], v[164:167], off offset:256
	global_load_dwordx4 v[164:167], v[198:199], off offset:256 nt
	s_nop 0
	global_load_dwordx4 v[168:171], v[204:205], off offset:256 nt
	s_waitcnt vmcnt(1)
	v_cvt_f32_f16_e32 v172, v166
	v_cvt_f32_f16_sdwa v173, v166 dst_sel:DWORD dst_unused:UNUSED_PAD src0_sel:WORD_1
	v_cvt_f32_f16_e32 v166, v167
	v_cvt_f32_f16_sdwa v167, v167 dst_sel:DWORD dst_unused:UNUSED_PAD src0_sel:WORD_1
	v_cvt_f32_f16_e32 v174, v164
	v_cvt_f32_f16_sdwa v175, v164 dst_sel:DWORD dst_unused:UNUSED_PAD src0_sel:WORD_1
	v_cvt_f32_f16_e32 v164, v165
	v_cvt_f32_f16_sdwa v165, v165 dst_sel:DWORD dst_unused:UNUSED_PAD src0_sel:WORD_1
	s_waitcnt vmcnt(0)
	v_cvt_f32_f16_e32 v176, v170
	v_cvt_f32_f16_sdwa v177, v170 dst_sel:DWORD dst_unused:UNUSED_PAD src0_sel:WORD_1
	v_cvt_f32_f16_e32 v170, v171
	v_cvt_f32_f16_sdwa v171, v171 dst_sel:DWORD dst_unused:UNUSED_PAD src0_sel:WORD_1
	v_cvt_f32_f16_e32 v178, v168
	v_cvt_f32_f16_sdwa v179, v168 dst_sel:DWORD dst_unused:UNUSED_PAD src0_sel:WORD_1
	v_cvt_f32_f16_e32 v168, v169
	v_cvt_f32_f16_sdwa v169, v169 dst_sel:DWORD dst_unused:UNUSED_PAD src0_sel:WORD_1
	v_pk_fma_f32 v[32:33], v[32:33], v[72:73], v[164:165]
	v_pk_fma_f32 v[30:31], v[30:31], v[70:71], v[174:175]
	v_pk_fma_f32 v[28:29], v[28:29], v[68:69], v[166:167]
	v_pk_fma_f32 v[26:27], v[26:27], v[66:67], v[172:173]
	v_cvt_pk_f16_f32 v167, v28, v29
	v_cvt_pk_f16_f32 v165, v32, v33
	v_cvt_pk_f16_f32 v166, v26, v27
	v_cvt_pk_f16_f32 v164, v30, v31
	v_pk_fma_f32 v[24:25], v[24:25], v[72:73], v[168:169]
	v_pk_fma_f32 v[22:23], v[22:23], v[70:71], v[178:179]
	v_pk_fma_f32 v[20:21], v[20:21], v[68:69], v[170:171]
	v_pk_fma_f32 v[18:19], v[18:19], v[66:67], v[176:177]
	v_pk_mul_f32 v[172:173], v[130:131], v[32:33]
	v_pk_mul_f32 v[174:175], v[132:133], v[30:31]
	v_pk_mul_f32 v[176:177], v[134:135], v[28:29]
	v_pk_mul_f32 v[178:179], v[136:137], v[26:27]
	global_store_dwordx4 v[212:213], v[164:167], off offset:256
	v_cvt_pk_f16_f32 v171, v20, v21
	v_cvt_pk_f16_f32 v169, v24, v25
	v_cvt_pk_bf16_f32 v164, v174, v175
	v_cvt_pk_bf16_f32 v165, v172, v173
	v_cvt_pk_bf16_f32 v166, v178, v179
	v_cvt_pk_bf16_f32 v167, v176, v177
	v_cvt_pk_f16_f32 v170, v18, v19
	v_cvt_pk_f16_f32 v168, v22, v23
	v_pk_mul_f32 v[180:181], v[130:131], v[24:25]
	v_pk_mul_f32 v[184:185], v[132:133], v[22:23]
	v_pk_mul_f32 v[186:187], v[134:135], v[20:21]
	v_pk_mul_f32 v[188:189], v[136:137], v[18:19]
	global_store_dwordx4 v[214:215], v[164:167], off offset:256
	global_store_dwordx4 v[210:211], v[168:171], off offset:256
	s_nop 0
	v_cvt_pk_bf16_f32 v164, v184, v185
	v_cvt_pk_bf16_f32 v165, v180, v181
	v_cvt_pk_bf16_f32 v166, v188, v189
	v_cvt_pk_bf16_f32 v167, v186, v187
	global_store_dwordx4 v[208:209], v[164:167], off offset:256
	global_load_dwordx4 v[166:169], v[202:203], off offset:256 nt
	s_nop 0
	global_load_dwordx4 v[170:173], v[224:225], off offset:256 nt
	v_and_b32_e32 v165, 64, v231
	v_xor_b32_e32 v164, 16, v231
	v_add_u32_e32 v165, 64, v165
	v_cmp_lt_i32_e32 vcc, v164, v165
	s_waitcnt vmcnt(1)
	v_cvt_f32_f16_e32 v62, v168
	v_cndmask_b32_e32 v164, v231, v164, vcc
	v_lshlrev_b32_e32 v164, 2, v164
	ds_bpermute_b32 v60, v164, v59
	v_cmp_lt_i32_e32 vcc, v58, v165
	v_cvt_f32_f16_sdwa v63, v168 dst_sel:DWORD dst_unused:UNUSED_PAD src0_sel:WORD_1
	v_cvt_f32_f16_e32 v64, v169
	v_cndmask_b32_e32 v58, v231, v58, vcc
	v_cvt_f32_f16_sdwa v65, v169 dst_sel:DWORD dst_unused:UNUSED_PAD src0_sel:WORD_1
	v_cvt_f32_f16_e32 v122, v166
	v_cvt_f32_f16_sdwa v123, v166 dst_sel:DWORD dst_unused:UNUSED_PAD src0_sel:WORD_1
	v_cvt_f32_f16_e32 v124, v167
	v_cvt_f32_f16_sdwa v125, v167 dst_sel:DWORD dst_unused:UNUSED_PAD src0_sel:WORD_1
	v_lshlrev_b32_e32 v58, 2, v58
	s_waitcnt lgkmcnt(0)
	v_add_f32_e32 v59, v59, v60
	ds_bpermute_b32 v60, v58, v59
	s_waitcnt vmcnt(0)
	v_cvt_f32_f16_e32 v126, v172
	v_cvt_f32_f16_sdwa v127, v172 dst_sel:DWORD dst_unused:UNUSED_PAD src0_sel:WORD_1
	v_cvt_f32_f16_e32 v128, v173
	v_cvt_f32_f16_sdwa v129, v173 dst_sel:DWORD dst_unused:UNUSED_PAD src0_sel:WORD_1
	v_cvt_f32_f16_e32 v166, v170
	v_cvt_f32_f16_sdwa v167, v170 dst_sel:DWORD dst_unused:UNUSED_PAD src0_sel:WORD_1
	v_cvt_f32_f16_e32 v168, v171
	v_cvt_f32_f16_sdwa v169, v171 dst_sel:DWORD dst_unused:UNUSED_PAD src0_sel:WORD_1
	v_pk_fma_f32 v[16:17], v[16:17], v[72:73], v[124:125]
	v_pk_fma_f32 v[14:15], v[14:15], v[70:71], v[122:123]
	v_pk_fma_f32 v[12:13], v[12:13], v[68:69], v[64:65]
	v_pk_fma_f32 v[10:11], v[10:11], v[66:67], v[62:63]
	v_cvt_pk_f16_f32 v65, v12, v13
	v_cvt_pk_f16_f32 v63, v16, v17
	v_cvt_pk_f16_f32 v64, v10, v11
	v_cvt_pk_f16_f32 v62, v14, v15
	v_pk_fma_f32 v[8:9], v[8:9], v[72:73], v[168:169]
	v_pk_fma_f32 v[6:7], v[6:7], v[70:71], v[166:167]
	v_pk_fma_f32 v[4:5], v[4:5], v[68:69], v[128:129]
	v_pk_fma_f32 v[2:3], v[2:3], v[66:67], v[126:127]
	v_pk_mul_f32 v[70:71], v[130:131], v[16:17]
	v_pk_mul_f32 v[72:73], v[132:133], v[14:15]
	v_pk_mul_f32 v[122:123], v[134:135], v[12:13]
	v_pk_mul_f32 v[124:125], v[136:137], v[10:11]
	global_store_dwordx4 v[182:183], v[62:65], off offset:256
	v_cvt_pk_f16_f32 v69, v4, v5
	v_cvt_pk_f16_f32 v67, v8, v9
	v_cvt_pk_bf16_f32 v62, v72, v73
	v_cvt_pk_bf16_f32 v63, v70, v71
	v_cvt_pk_bf16_f32 v64, v124, v125
	v_cvt_pk_bf16_f32 v65, v122, v123
	v_cvt_pk_f16_f32 v68, v2, v3
	v_cvt_pk_f16_f32 v66, v6, v7
	v_pk_mul_f32 v[126:127], v[130:131], v[8:9]
	v_pk_mul_f32 v[128:129], v[132:133], v[6:7]
	v_pk_mul_f32 v[130:131], v[134:135], v[4:5]
	v_pk_mul_f32 v[132:133], v[136:137], v[2:3]
	global_store_dwordx4 v[206:207], v[62:65], off offset:256
	global_store_dwordx4 v[194:195], v[66:69], off offset:256
	s_nop 0
	v_cvt_pk_bf16_f32 v62, v128, v129
	v_cvt_pk_bf16_f32 v63, v126, v127
	v_cvt_pk_bf16_f32 v64, v132, v133
	v_cvt_pk_bf16_f32 v65, v130, v131
	global_store_dwordx4 v[200:201], v[62:65], off offset:256
	s_and_saveexec_b64 s[68:69], s[6:7]
	s_cbranch_execz .LBB0_907
	v_lshl_add_u64 v[62:63], v[154:155], 2, s[28:29]
	s_waitcnt lgkmcnt(0)
	v_add_f32_e32 v59, v59, v60
	global_atomic_add_f32 v[62:63], v59, off

.LBB0_991:
	ds_read_b128 v[34:37], v184
	ds_read_b128 v[38:41], v184 offset:1024
	ds_read_b128 v[42:45], v184 offset:2048
	ds_read_b128 v[46:49], v184 offset:3072
	ds_read_b128 v[166:169], v185
	ds_read_b128 v[170:173], v185 offset:1024
	ds_read_b128 v[190:193], v185 offset:2048
	ds_read_b128 v[194:197], v185 offset:3072
	s_add_u32 s3, s0, 0xfffc0080
	s_addc_u32 s13, s1, -1
	s_cmp_eq_u32 s12, 12
	s_cselect_b32 s87, s11, s13
	s_cselect_b32 s86, s23, s3
	s_cselect_b32 s85, s48, s77
	s_cselect_b32 s84, s49, s63
	s_add_i32 m0, s67, 0xc000
	ds_read_b128 v[198:201], v186
	ds_read_b128 v[202:205], v186 offset:1024
	ds_read_b128 v[206:209], v186 offset:2048
	ds_read_b128 v[210:213], v186 offset:3072
	ds_read_b128 v[214:217], v186 offset:4096
	ds_read_b128 v[218:221], v186 offset:5120
	ds_read_b128 v[222:225], v186 offset:6144
	ds_read_b128 v[226:229], v186 offset:7168
	global_load_lds_dwordx4 v158, s[0:1]
	s_add_i32 m0, s67, 0xe000
	s_nop 0
	global_load_lds_dwordx4 v160, s[0:1]
	s_waitcnt vmcnt(8)
	s_waitcnt lgkmcnt(0)
	s_barrier
	s_setprio 1
	s_waitcnt lgkmcnt(0)
	v_mfma_f32_16x16x32_bf16 v[142:145], v[34:37], v[198:201], v[142:145]
	v_mfma_f32_16x16x32_bf16 v[138:141], v[42:45], v[198:201], v[138:141]
	v_mfma_f32_16x16x32_bf16 v[126:129], v[34:37], v[206:209], v[126:129]
	v_mfma_f32_16x16x32_bf16 v[122:125], v[42:45], v[206:209], v[122:125]
	v_mfma_f32_16x16x32_bf16 v[110:113], v[34:37], v[214:217], v[110:113]
	v_mfma_f32_16x16x32_bf16 v[106:109], v[42:45], v[214:217], v[106:109]
	v_mfma_f32_16x16x32_bf16 v[94:97], v[34:37], v[222:225], v[94:97]
	v_mfma_f32_16x16x32_bf16 v[90:93], v[42:45], v[222:225], v[90:93]
	v_mfma_f32_16x16x32_bf16 v[142:145], v[38:41], v[202:205], v[142:145]
	v_mfma_f32_16x16x32_bf16 v[138:141], v[46:49], v[202:205], v[138:141]
	v_mfma_f32_16x16x32_bf16 v[126:129], v[38:41], v[210:213], v[126:129]
	v_mfma_f32_16x16x32_bf16 v[122:125], v[46:49], v[210:213], v[122:125]
	v_mfma_f32_16x16x32_bf16 v[110:113], v[38:41], v[218:221], v[110:113]
	v_mfma_f32_16x16x32_bf16 v[106:109], v[46:49], v[218:221], v[106:109]
	v_mfma_f32_16x16x32_bf16 v[94:97], v[38:41], v[226:229], v[94:97]
	v_mfma_f32_16x16x32_bf16 v[90:93], v[46:49], v[226:229], v[90:93]
	s_setprio 0
	s_setprio 1
	v_mfma_f32_16x16x32_bf16 v[134:137], v[166:169], v[198:201], v[134:137]
	v_mfma_f32_16x16x32_bf16 v[130:133], v[190:193], v[198:201], v[130:133]
	v_mfma_f32_16x16x32_bf16 v[118:121], v[166:169], v[206:209], v[118:121]
	v_mfma_f32_16x16x32_bf16 v[114:117], v[190:193], v[206:209], v[114:117]
	v_mfma_f32_16x16x32_bf16 v[102:105], v[166:169], v[214:217], v[102:105]
	v_mfma_f32_16x16x32_bf16 v[98:101], v[190:193], v[214:217], v[98:101]
	v_mfma_f32_16x16x32_bf16 v[86:89], v[166:169], v[222:225], v[86:89]
	v_mfma_f32_16x16x32_bf16 v[82:85], v[190:193], v[222:225], v[82:85]
	v_mfma_f32_16x16x32_bf16 v[134:137], v[170:173], v[202:205], v[134:137]
	v_mfma_f32_16x16x32_bf16 v[130:133], v[194:197], v[202:205], v[130:133]
	v_mfma_f32_16x16x32_bf16 v[118:121], v[170:173], v[210:213], v[118:121]
	v_mfma_f32_16x16x32_bf16 v[114:117], v[194:197], v[210:213], v[114:117]
	v_mfma_f32_16x16x32_bf16 v[102:105], v[170:173], v[218:221], v[102:105]
	v_mfma_f32_16x16x32_bf16 v[98:101], v[194:197], v[218:221], v[98:101]
	v_mfma_f32_16x16x32_bf16 v[86:89], v[170:173], v[226:229], v[86:89]
	v_mfma_f32_16x16x32_bf16 v[82:85], v[194:197], v[226:229], v[82:85]
	s_setprio 0
	s_barrier
	s_add_i32 s3, s61, s66
	s_mov_b32 m0, s3
	ds_read_b128 v[198:201], v186 offset:16384
	ds_read_b128 v[202:205], v186 offset:17408
	ds_read_b128 v[206:209], v186 offset:18432
	ds_read_b128 v[210:213], v186 offset:19456
	ds_read_b128 v[214:217], v186 offset:20480
	ds_read_b128 v[218:221], v186 offset:21504
	ds_read_b128 v[222:225], v186 offset:22528
	ds_read_b128 v[226:229], v186 offset:23552
	global_load_lds_dwordx4 v150, s[84:85]
	s_add_i32 m0, s3, 0x2000
	s_add_u32 s24, s84, 0x40000
	s_addc_u32 s25, s85, 0
	s_add_i32 s3, s62, s66
	global_load_lds_dwordx4 v154, s[84:85]
	s_mov_b32 m0, s3
	s_nop 0
	global_load_lds_dwordx4 v150, s[24:25]
	s_add_i32 m0, s3, 0x2000
	s_nop 0
	global_load_lds_dwordx4 v154, s[24:25]
	s_mov_b32 m0, s67
	s_nop 0
	global_load_lds_dwordx4 v148, s[86:87]
	s_mov_b32 m0, s88
	s_nop 0
	global_load_lds_dwordx4 v152, s[86:87]
	s_waitcnt vmcnt(8)
	s_waitcnt lgkmcnt(0)
	s_barrier
	s_setprio 1
	s_waitcnt lgkmcnt(0)
	v_mfma_f32_16x16x32_bf16 v[78:81], v[34:37], v[198:201], v[78:81]
	v_mfma_f32_16x16x32_bf16 v[74:77], v[42:45], v[198:201], v[74:77]
	v_mfma_f32_16x16x32_bf16 v[62:65], v[34:37], v[206:209], v[62:65]
	v_mfma_f32_16x16x32_bf16 v[58:61], v[42:45], v[206:209], v[58:61]
	v_mfma_f32_16x16x32_bf16 v[30:33], v[34:37], v[214:217], v[30:33]
	v_mfma_f32_16x16x32_bf16 v[26:29], v[42:45], v[214:217], v[26:29]
	v_mfma_f32_16x16x32_bf16 v[14:17], v[34:37], v[222:225], v[14:17]
	v_mfma_f32_16x16x32_bf16 v[10:13], v[42:45], v[222:225], v[10:13]
	v_mfma_f32_16x16x32_bf16 v[78:81], v[38:41], v[202:205], v[78:81]
	v_mfma_f32_16x16x32_bf16 v[74:77], v[46:49], v[202:205], v[74:77]
	v_mfma_f32_16x16x32_bf16 v[62:65], v[38:41], v[210:213], v[62:65]
	v_mfma_f32_16x16x32_bf16 v[58:61], v[46:49], v[210:213], v[58:61]
	v_mfma_f32_16x16x32_bf16 v[30:33], v[38:41], v[218:221], v[30:33]
	v_mfma_f32_16x16x32_bf16 v[26:29], v[46:49], v[218:221], v[26:29]
	v_mfma_f32_16x16x32_bf16 v[14:17], v[38:41], v[226:229], v[14:17]
	v_mfma_f32_16x16x32_bf16 v[10:13], v[46:49], v[226:229], v[10:13]
	s_setprio 0
	s_setprio 1
	v_mfma_f32_16x16x32_bf16 v[22:25], v[166:169], v[214:217], v[22:25]
	v_mfma_f32_16x16x32_bf16 v[18:21], v[190:193], v[214:217], v[18:21]
	v_mfma_f32_16x16x32_bf16 v[6:9], v[166:169], v[222:225], v[6:9]
	v_mfma_f32_16x16x32_bf16 v[2:5], v[190:193], v[222:225], v[2:5]
	v_mfma_f32_16x16x32_bf16 v[34:37], v[166:169], v[198:201], v[70:73]
	v_mfma_f32_16x16x32_bf16 v[38:41], v[190:193], v[198:201], v[66:69]
	v_mfma_f32_16x16x32_bf16 v[42:45], v[166:169], v[206:209], v[54:57]
	v_mfma_f32_16x16x32_bf16 v[46:49], v[190:193], v[206:209], v[50:53]
	v_mfma_f32_16x16x32_bf16 v[22:25], v[170:173], v[218:221], v[22:25]
	v_mfma_f32_16x16x32_bf16 v[18:21], v[194:197], v[218:221], v[18:21]
	v_mfma_f32_16x16x32_bf16 v[6:9], v[170:173], v[226:229], v[6:9]
	v_mfma_f32_16x16x32_bf16 v[2:5], v[194:197], v[226:229], v[2:5]
	v_mfma_f32_16x16x32_bf16 v[34:37], v[170:173], v[202:205], v[34:37]
	v_mfma_f32_16x16x32_bf16 v[38:41], v[194:197], v[202:205], v[38:41]
	v_mfma_f32_16x16x32_bf16 v[42:45], v[170:173], v[210:213], v[42:45]
	v_mfma_f32_16x16x32_bf16 v[46:49], v[194:197], v[210:213], v[46:49]
	s_setprio 0
	s_barrier
	s_add_i32 s3, 0, 0x18000
	s_add_i32 s13, 0, 0x1c000
	v_add_u32_e32 v70, s3, v175
	v_add_u32_e32 v194, s13, v175
	ds_read_b128 v[50:53], v70
	ds_read_b128 v[54:57], v70 offset:1024
	ds_read_b128 v[66:69], v70 offset:2048
	ds_read_b128 v[70:73], v70 offset:3072
	ds_read_b128 v[166:169], v194
	ds_read_b128 v[170:173], v194 offset:1024
	ds_read_b128 v[190:193], v194 offset:2048
	ds_read_b128 v[194:197], v194 offset:3072
	s_add_u32 s24, s86, 0x40000
	s_addc_u32 s25, s87, 0
	s_mov_b32 m0, s89
	ds_read_b128 v[198:201], v186 offset:32768
	ds_read_b128 v[202:205], v186 offset:33792
	ds_read_b128 v[206:209], v186 offset:34816
	ds_read_b128 v[210:213], v186 offset:35840
	ds_read_b128 v[214:217], v186 offset:36864
	ds_read_b128 v[218:221], v186 offset:37888
	ds_read_b128 v[222:225], v186 offset:38912
	ds_read_b128 v[226:229], v186 offset:39936
	global_load_lds_dwordx4 v148, s[24:25]
	s_mov_b32 m0, s90
	s_nop 0
	global_load_lds_dwordx4 v152, s[24:25]
	s_waitcnt vmcnt(8)
	s_waitcnt lgkmcnt(0)
	s_barrier
	s_setprio 1
	s_waitcnt lgkmcnt(0)
	v_mfma_f32_16x16x32_bf16 v[142:145], v[50:53], v[198:201], v[142:145]
	v_mfma_f32_16x16x32_bf16 v[138:141], v[66:69], v[198:201], v[138:141]
	v_mfma_f32_16x16x32_bf16 v[126:129], v[50:53], v[206:209], v[126:129]
	v_mfma_f32_16x16x32_bf16 v[122:125], v[66:69], v[206:209], v[122:125]
	v_mfma_f32_16x16x32_bf16 v[110:113], v[50:53], v[214:217], v[110:113]
	v_mfma_f32_16x16x32_bf16 v[106:109], v[66:69], v[214:217], v[106:109]
	v_mfma_f32_16x16x32_bf16 v[94:97], v[50:53], v[222:225], v[94:97]
	v_mfma_f32_16x16x32_bf16 v[90:93], v[66:69], v[222:225], v[90:93]
	v_mfma_f32_16x16x32_bf16 v[142:145], v[54:57], v[202:205], v[142:145]
	v_mfma_f32_16x16x32_bf16 v[138:141], v[70:73], v[202:205], v[138:141]
	v_mfma_f32_16x16x32_bf16 v[126:129], v[54:57], v[210:213], v[126:129]
	v_mfma_f32_16x16x32_bf16 v[122:125], v[70:73], v[210:213], v[122:125]
	v_mfma_f32_16x16x32_bf16 v[110:113], v[54:57], v[218:221], v[110:113]
	v_mfma_f32_16x16x32_bf16 v[106:109], v[70:73], v[218:221], v[106:109]
	v_mfma_f32_16x16x32_bf16 v[94:97], v[54:57], v[226:229], v[94:97]
	v_mfma_f32_16x16x32_bf16 v[90:93], v[70:73], v[226:229], v[90:93]
	s_setprio 0
	s_setprio 1
	v_mfma_f32_16x16x32_bf16 v[134:137], v[166:169], v[198:201], v[134:137]
	v_mfma_f32_16x16x32_bf16 v[130:133], v[190:193], v[198:201], v[130:133]
	v_mfma_f32_16x16x32_bf16 v[118:121], v[166:169], v[206:209], v[118:121]
	v_mfma_f32_16x16x32_bf16 v[114:117], v[190:193], v[206:209], v[114:117]
	v_mfma_f32_16x16x32_bf16 v[102:105], v[166:169], v[214:217], v[102:105]
	v_mfma_f32_16x16x32_bf16 v[98:101], v[190:193], v[214:217], v[98:101]
	v_mfma_f32_16x16x32_bf16 v[86:89], v[166:169], v[222:225], v[86:89]
	v_mfma_f32_16x16x32_bf16 v[82:85], v[190:193], v[222:225], v[82:85]
	v_mfma_f32_16x16x32_bf16 v[134:137], v[170:173], v[202:205], v[134:137]
	v_mfma_f32_16x16x32_bf16 v[130:133], v[194:197], v[202:205], v[130:133]
	v_mfma_f32_16x16x32_bf16 v[118:121], v[170:173], v[210:213], v[118:121]
	v_mfma_f32_16x16x32_bf16 v[114:117], v[194:197], v[210:213], v[114:117]
	v_mfma_f32_16x16x32_bf16 v[102:105], v[170:173], v[218:221], v[102:105]
	v_mfma_f32_16x16x32_bf16 v[98:101], v[194:197], v[218:221], v[98:101]
	v_mfma_f32_16x16x32_bf16 v[86:89], v[170:173], v[226:229], v[86:89]
	v_mfma_f32_16x16x32_bf16 v[82:85], v[194:197], v[226:229], v[82:85]
	s_setprio 0
	s_barrier
	s_add_i32 s3, s3, s66
	s_mov_b32 m0, s3
	ds_read_b128 v[198:201], v186 offset:49152
	ds_read_b128 v[202:205], v186 offset:50176
	ds_read_b128 v[206:209], v186 offset:51200
	ds_read_b128 v[210:213], v186 offset:52224
	ds_read_b128 v[214:217], v186 offset:53248
	ds_read_b128 v[218:221], v186 offset:54272
	ds_read_b128 v[222:225], v186 offset:55296
	ds_read_b128 v[226:229], v186 offset:56320
	global_load_lds_dwordx4 v251, s[84:85]
	s_add_i32 m0, s3, 0x2000
	s_add_u32 s24, s84, 0x40080
	s_addc_u32 s25, s85, 0
	s_add_i32 s3, s13, s66
	global_load_lds_dwordx4 v252, s[84:85]
	s_mov_b32 m0, s3
	s_nop 0
	global_load_lds_dwordx4 v150, s[24:25]
	s_add_i32 m0, s3, 0x2000
	s_nop 0
	global_load_lds_dwordx4 v154, s[24:25]
	s_mov_b32 m0, s93
	s_nop 0
	global_load_lds_dwordx4 v253, s[86:87]
	s_mov_b32 m0, s44
	s_nop 0
	global_load_lds_dwordx4 v254, s[86:87]
	s_waitcnt vmcnt(8)
	s_waitcnt lgkmcnt(0)
	s_barrier
	s_setprio 1
	s_waitcnt lgkmcnt(0)
	v_mfma_f32_16x16x32_bf16 v[78:81], v[50:53], v[198:201], v[78:81]
	v_mfma_f32_16x16x32_bf16 v[74:77], v[66:69], v[198:201], v[74:77]
	v_mfma_f32_16x16x32_bf16 v[62:65], v[50:53], v[206:209], v[62:65]
	v_mfma_f32_16x16x32_bf16 v[58:61], v[66:69], v[206:209], v[58:61]
	v_mfma_f32_16x16x32_bf16 v[30:33], v[50:53], v[214:217], v[30:33]
	v_mfma_f32_16x16x32_bf16 v[26:29], v[66:69], v[214:217], v[26:29]
	v_mfma_f32_16x16x32_bf16 v[14:17], v[50:53], v[222:225], v[14:17]
	v_mfma_f32_16x16x32_bf16 v[10:13], v[66:69], v[222:225], v[10:13]
	v_mfma_f32_16x16x32_bf16 v[78:81], v[54:57], v[202:205], v[78:81]
	v_mfma_f32_16x16x32_bf16 v[74:77], v[70:73], v[202:205], v[74:77]
	v_mfma_f32_16x16x32_bf16 v[62:65], v[54:57], v[210:213], v[62:65]
	v_mfma_f32_16x16x32_bf16 v[58:61], v[70:73], v[210:213], v[58:61]
	v_mfma_f32_16x16x32_bf16 v[30:33], v[54:57], v[218:221], v[30:33]
	v_mfma_f32_16x16x32_bf16 v[26:29], v[70:73], v[218:221], v[26:29]
	v_mfma_f32_16x16x32_bf16 v[14:17], v[54:57], v[226:229], v[14:17]
	v_mfma_f32_16x16x32_bf16 v[10:13], v[70:73], v[226:229], v[10:13]
	s_setprio 0
	s_setprio 1
	v_mfma_f32_16x16x32_bf16 v[34:37], v[166:169], v[198:201], v[34:37]
	v_mfma_f32_16x16x32_bf16 v[70:73], v[170:173], v[202:205], v[34:37]
	v_mfma_f32_16x16x32_bf16 v[34:37], v[190:193], v[198:201], v[38:41]
	v_mfma_f32_16x16x32_bf16 v[66:69], v[194:197], v[202:205], v[34:37]
	v_mfma_f32_16x16x32_bf16 v[34:37], v[166:169], v[206:209], v[42:45]
	v_mfma_f32_16x16x32_bf16 v[54:57], v[170:173], v[210:213], v[34:37]
	v_mfma_f32_16x16x32_bf16 v[34:37], v[190:193], v[206:209], v[46:49]
	v_mfma_f32_16x16x32_bf16 v[22:25], v[166:169], v[214:217], v[22:25]
	v_mfma_f32_16x16x32_bf16 v[18:21], v[190:193], v[214:217], v[18:21]
	v_mfma_f32_16x16x32_bf16 v[6:9], v[166:169], v[222:225], v[6:9]
	v_mfma_f32_16x16x32_bf16 v[2:5], v[190:193], v[222:225], v[2:5]
	v_mfma_f32_16x16x32_bf16 v[50:53], v[194:197], v[210:213], v[34:37]
	v_mfma_f32_16x16x32_bf16 v[22:25], v[170:173], v[218:221], v[22:25]
	v_mfma_f32_16x16x32_bf16 v[18:21], v[194:197], v[218:221], v[18:21]
	v_mfma_f32_16x16x32_bf16 v[6:9], v[170:173], v[226:229], v[6:9]
	v_mfma_f32_16x16x32_bf16 v[2:5], v[194:197], v[226:229], v[2:5]
	s_setprio 0
	s_barrier
	s_add_i32 s12, s12, 2
	s_add_u32 s0, s0, 0x100
	s_addc_u32 s1, s1, 0
	s_add_u32 s63, s63, 0x100
	s_addc_u32 s77, s77, 0
	s_cmp_gt_u32 s12, 13
	s_cbranch_scc0 .LBB0_991
	s_and_b64 vcc, exec, s[74:75]
	s_cbranch_vccz .LBB0_994
	s_barrier

.LBB0_1394:
	ds_read_b128 v[130:133], v228
	ds_read_b128 v[134:137], v228 offset:1024
	ds_read_b128 v[154:157], v228 offset:2048
	ds_read_b128 v[158:161], v228 offset:3072
	ds_read_b128 v[162:165], v229
	ds_read_b128 v[166:169], v229 offset:1024
	ds_read_b128 v[170:173], v229 offset:2048
	ds_read_b128 v[174:177], v229 offset:3072
	s_add_u32 s13, s30, 0xfffc0080
	s_addc_u32 s40, s31, -1
	s_cmp_eq_u32 s12, 12
	s_cselect_b32 s43, s25, s40
	s_cselect_b32 s42, s37, s13
	s_cselect_b32 s41, s23, s69
	s_cselect_b32 s40, s67, s68
	s_add_i32 m0, s39, 0xc000
	ds_read_b128 v[178:181], v230
	ds_read_b128 v[182:185], v230 offset:1024
	ds_read_b128 v[186:189], v230 offset:2048
	ds_read_b128 v[190:193], v230 offset:3072
	ds_read_b128 v[194:197], v230 offset:4096
	ds_read_b128 v[198:201], v230 offset:5120
	ds_read_b128 v[202:205], v230 offset:6144
	ds_read_b128 v[206:209], v230 offset:7168
	global_load_lds_dwordx4 v146, s[30:31]
	s_add_i32 m0, s39, 0xe000
	s_nop 0
	global_load_lds_dwordx4 v148, s[30:31]
	s_waitcnt vmcnt(8)
	s_waitcnt lgkmcnt(0)
	s_barrier
	s_setprio 1
	s_waitcnt lgkmcnt(0)
	v_mfma_f32_16x16x32_bf16 v[126:129], v[130:133], v[178:181], v[126:129]
	v_mfma_f32_16x16x32_bf16 v[122:125], v[154:157], v[178:181], v[122:125]
	v_mfma_f32_16x16x32_bf16 v[118:121], v[130:133], v[186:189], v[118:121]
	v_mfma_f32_16x16x32_bf16 v[114:117], v[154:157], v[186:189], v[114:117]
	v_mfma_f32_16x16x32_bf16 v[110:113], v[130:133], v[194:197], v[110:113]
	v_mfma_f32_16x16x32_bf16 v[106:109], v[154:157], v[194:197], v[106:109]
	v_mfma_f32_16x16x32_bf16 v[102:105], v[130:133], v[202:205], v[102:105]
	v_mfma_f32_16x16x32_bf16 v[98:101], v[154:157], v[202:205], v[98:101]
	v_mfma_f32_16x16x32_bf16 v[126:129], v[134:137], v[182:185], v[126:129]
	v_mfma_f32_16x16x32_bf16 v[122:125], v[158:161], v[182:185], v[122:125]
	v_mfma_f32_16x16x32_bf16 v[118:121], v[134:137], v[190:193], v[118:121]
	v_mfma_f32_16x16x32_bf16 v[114:117], v[158:161], v[190:193], v[114:117]
	v_mfma_f32_16x16x32_bf16 v[110:113], v[134:137], v[198:201], v[110:113]
	v_mfma_f32_16x16x32_bf16 v[106:109], v[158:161], v[198:201], v[106:109]
	v_mfma_f32_16x16x32_bf16 v[102:105], v[134:137], v[206:209], v[102:105]
	v_mfma_f32_16x16x32_bf16 v[98:101], v[158:161], v[206:209], v[98:101]
	s_setprio 0
	s_setprio 1
	v_mfma_f32_16x16x32_bf16 v[62:65], v[162:165], v[178:181], v[62:65]
	v_mfma_f32_16x16x32_bf16 v[58:61], v[170:173], v[178:181], v[58:61]
	v_mfma_f32_16x16x32_bf16 v[54:57], v[162:165], v[186:189], v[54:57]
	v_mfma_f32_16x16x32_bf16 v[50:53], v[170:173], v[186:189], v[50:53]
	v_mfma_f32_16x16x32_bf16 v[46:49], v[162:165], v[194:197], v[46:49]
	v_mfma_f32_16x16x32_bf16 v[42:45], v[170:173], v[194:197], v[42:45]
	v_mfma_f32_16x16x32_bf16 v[38:41], v[162:165], v[202:205], v[38:41]
	v_mfma_f32_16x16x32_bf16 v[34:37], v[170:173], v[202:205], v[34:37]
	v_mfma_f32_16x16x32_bf16 v[62:65], v[166:169], v[182:185], v[62:65]
	v_mfma_f32_16x16x32_bf16 v[58:61], v[174:177], v[182:185], v[58:61]
	v_mfma_f32_16x16x32_bf16 v[54:57], v[166:169], v[190:193], v[54:57]
	v_mfma_f32_16x16x32_bf16 v[50:53], v[174:177], v[190:193], v[50:53]
	v_mfma_f32_16x16x32_bf16 v[46:49], v[166:169], v[198:201], v[46:49]
	v_mfma_f32_16x16x32_bf16 v[42:45], v[174:177], v[198:201], v[42:45]
	v_mfma_f32_16x16x32_bf16 v[38:41], v[166:169], v[206:209], v[38:41]
	v_mfma_f32_16x16x32_bf16 v[34:37], v[174:177], v[206:209], v[34:37]
	s_setprio 0
	s_barrier
	s_add_i32 s13, s63, s46
	s_mov_b32 m0, s13
	ds_read_b128 v[178:181], v230 offset:16384
	ds_read_b128 v[182:185], v230 offset:17408
	ds_read_b128 v[186:189], v230 offset:18432
	ds_read_b128 v[190:193], v230 offset:19456
	ds_read_b128 v[194:197], v230 offset:20480
	ds_read_b128 v[198:201], v230 offset:21504
	ds_read_b128 v[202:205], v230 offset:22528
	ds_read_b128 v[206:209], v230 offset:23552
	global_load_lds_dwordx4 v140, s[40:41]
	s_add_i32 m0, s13, 0x2000
	s_add_u32 s70, s40, 0x40000
	v_lshl_add_u64 v[212:213], s[40:41], 0, v[144:145]
	s_addc_u32 s71, s41, 0
	s_add_i32 s13, s66, s46
	global_load_lds_dwordx4 v144, s[40:41]
	s_mov_b32 m0, s13
	v_lshl_add_u64 v[216:217], s[42:43], 0, v[142:143]
	global_load_lds_dwordx4 v140, s[70:71]
	s_add_i32 m0, s13, 0x2000
	s_nop 0
	global_load_lds_dwordx4 v144, s[70:71]
	v_lshl_add_u64 v[214:215], s[42:43], 0, v[138:139]
	s_mov_b32 m0, s39
	s_nop 0
	global_load_lds_dwordx4 v138, s[42:43]
	s_mov_b32 m0, s47
	s_nop 0
	global_load_lds_dwordx4 v142, s[42:43]
	s_waitcnt vmcnt(8)
	s_waitcnt lgkmcnt(0)
	s_barrier
	s_setprio 1
	s_waitcnt lgkmcnt(0)
	v_mfma_f32_16x16x32_bf16 v[94:97], v[130:133], v[178:181], v[94:97]
	v_mfma_f32_16x16x32_bf16 v[90:93], v[154:157], v[178:181], v[90:93]
	v_mfma_f32_16x16x32_bf16 v[86:89], v[130:133], v[186:189], v[86:89]
	v_mfma_f32_16x16x32_bf16 v[82:85], v[154:157], v[186:189], v[82:85]
	v_mfma_f32_16x16x32_bf16 v[78:81], v[130:133], v[194:197], v[78:81]
	v_mfma_f32_16x16x32_bf16 v[74:77], v[154:157], v[194:197], v[74:77]
	v_mfma_f32_16x16x32_bf16 v[70:73], v[130:133], v[202:205], v[70:73]
	v_mfma_f32_16x16x32_bf16 v[66:69], v[154:157], v[202:205], v[66:69]
	v_mfma_f32_16x16x32_bf16 v[94:97], v[134:137], v[182:185], v[94:97]
	v_mfma_f32_16x16x32_bf16 v[90:93], v[158:161], v[182:185], v[90:93]
	v_mfma_f32_16x16x32_bf16 v[86:89], v[134:137], v[190:193], v[86:89]
	v_mfma_f32_16x16x32_bf16 v[82:85], v[158:161], v[190:193], v[82:85]
	v_mfma_f32_16x16x32_bf16 v[78:81], v[134:137], v[198:201], v[78:81]
	v_mfma_f32_16x16x32_bf16 v[74:77], v[158:161], v[198:201], v[74:77]
	v_mfma_f32_16x16x32_bf16 v[70:73], v[134:137], v[206:209], v[70:73]
	v_mfma_f32_16x16x32_bf16 v[66:69], v[158:161], v[206:209], v[66:69]
	s_setprio 0
	s_setprio 1
	v_mfma_f32_16x16x32_bf16 v[30:33], v[162:165], v[178:181], v[30:33]
	v_mfma_f32_16x16x32_bf16 v[26:29], v[170:173], v[178:181], v[26:29]
	v_mfma_f32_16x16x32_bf16 v[22:25], v[162:165], v[186:189], v[22:25]
	v_mfma_f32_16x16x32_bf16 v[18:21], v[170:173], v[186:189], v[18:21]
	v_mfma_f32_16x16x32_bf16 v[14:17], v[162:165], v[194:197], v[14:17]
	v_mfma_f32_16x16x32_bf16 v[10:13], v[170:173], v[194:197], v[10:13]
	v_mfma_f32_16x16x32_bf16 v[6:9], v[162:165], v[202:205], v[6:9]
	v_mfma_f32_16x16x32_bf16 v[2:5], v[170:173], v[202:205], v[2:5]
	v_mfma_f32_16x16x32_bf16 v[30:33], v[166:169], v[182:185], v[30:33]
	v_mfma_f32_16x16x32_bf16 v[26:29], v[174:177], v[182:185], v[26:29]
	v_mfma_f32_16x16x32_bf16 v[22:25], v[166:169], v[190:193], v[22:25]
	v_mfma_f32_16x16x32_bf16 v[18:21], v[174:177], v[190:193], v[18:21]
	v_mfma_f32_16x16x32_bf16 v[14:17], v[166:169], v[198:201], v[14:17]
	v_mfma_f32_16x16x32_bf16 v[10:13], v[174:177], v[198:201], v[10:13]
	v_mfma_f32_16x16x32_bf16 v[6:9], v[166:169], v[206:209], v[6:9]
	v_mfma_f32_16x16x32_bf16 v[2:5], v[174:177], v[206:209], v[2:5]
	s_setprio 0
	s_barrier
	s_add_i32 s13, 0, 0x18000
	s_add_i32 s70, 0, 0x1c000
	v_add_u32_e32 v158, s13, v226
	v_add_u32_e32 v174, s70, v226
	ds_read_b128 v[130:133], v158
	ds_read_b128 v[134:137], v158 offset:1024
	ds_read_b128 v[154:157], v158 offset:2048
	ds_read_b128 v[158:161], v158 offset:3072
	ds_read_b128 v[162:165], v174
	ds_read_b128 v[166:169], v174 offset:1024
	ds_read_b128 v[170:173], v174 offset:2048
	ds_read_b128 v[174:177], v174 offset:3072
	s_add_u32 s42, s42, 0x40000
	s_addc_u32 s43, s43, 0
	s_mov_b32 m0, s48
	ds_read_b128 v[178:181], v230 offset:32768
	ds_read_b128 v[182:185], v230 offset:33792
	ds_read_b128 v[186:189], v230 offset:34816
	ds_read_b128 v[190:193], v230 offset:35840
	ds_read_b128 v[194:197], v230 offset:36864
	ds_read_b128 v[198:201], v230 offset:37888
	ds_read_b128 v[202:205], v230 offset:38912
	ds_read_b128 v[206:209], v230 offset:39936
	global_load_lds_dwordx4 v138, s[42:43]
	s_mov_b32 m0, s49
	s_nop 0
	global_load_lds_dwordx4 v142, s[42:43]
	s_waitcnt vmcnt(8)
	s_waitcnt lgkmcnt(0)
	s_barrier
	s_setprio 1
	s_waitcnt lgkmcnt(0)
	v_mfma_f32_16x16x32_bf16 v[126:129], v[130:133], v[178:181], v[126:129]
	v_mfma_f32_16x16x32_bf16 v[122:125], v[154:157], v[178:181], v[122:125]
	v_mfma_f32_16x16x32_bf16 v[118:121], v[130:133], v[186:189], v[118:121]
	v_mfma_f32_16x16x32_bf16 v[114:117], v[154:157], v[186:189], v[114:117]
	v_mfma_f32_16x16x32_bf16 v[110:113], v[130:133], v[194:197], v[110:113]
	v_mfma_f32_16x16x32_bf16 v[106:109], v[154:157], v[194:197], v[106:109]
	v_mfma_f32_16x16x32_bf16 v[102:105], v[130:133], v[202:205], v[102:105]
	v_mfma_f32_16x16x32_bf16 v[98:101], v[154:157], v[202:205], v[98:101]
	v_mfma_f32_16x16x32_bf16 v[126:129], v[134:137], v[182:185], v[126:129]
	v_mfma_f32_16x16x32_bf16 v[122:125], v[158:161], v[182:185], v[122:125]
	v_mfma_f32_16x16x32_bf16 v[118:121], v[134:137], v[190:193], v[118:121]
	v_mfma_f32_16x16x32_bf16 v[114:117], v[158:161], v[190:193], v[114:117]
	v_mfma_f32_16x16x32_bf16 v[110:113], v[134:137], v[198:201], v[110:113]
	v_mfma_f32_16x16x32_bf16 v[106:109], v[158:161], v[198:201], v[106:109]
	v_mfma_f32_16x16x32_bf16 v[102:105], v[134:137], v[206:209], v[102:105]
	v_mfma_f32_16x16x32_bf16 v[98:101], v[158:161], v[206:209], v[98:101]
	s_setprio 0
	s_setprio 1
	v_mfma_f32_16x16x32_bf16 v[62:65], v[162:165], v[178:181], v[62:65]
	v_mfma_f32_16x16x32_bf16 v[58:61], v[170:173], v[178:181], v[58:61]
	v_mfma_f32_16x16x32_bf16 v[54:57], v[162:165], v[186:189], v[54:57]
	v_mfma_f32_16x16x32_bf16 v[50:53], v[170:173], v[186:189], v[50:53]
	v_mfma_f32_16x16x32_bf16 v[46:49], v[162:165], v[194:197], v[46:49]
	v_mfma_f32_16x16x32_bf16 v[42:45], v[170:173], v[194:197], v[42:45]
	v_mfma_f32_16x16x32_bf16 v[38:41], v[162:165], v[202:205], v[38:41]
	v_mfma_f32_16x16x32_bf16 v[34:37], v[170:173], v[202:205], v[34:37]
	v_mfma_f32_16x16x32_bf16 v[62:65], v[166:169], v[182:185], v[62:65]
	v_mfma_f32_16x16x32_bf16 v[58:61], v[174:177], v[182:185], v[58:61]
	v_mfma_f32_16x16x32_bf16 v[54:57], v[166:169], v[190:193], v[54:57]
	v_mfma_f32_16x16x32_bf16 v[50:53], v[174:177], v[190:193], v[50:53]
	v_mfma_f32_16x16x32_bf16 v[46:49], v[166:169], v[198:201], v[46:49]
	v_mfma_f32_16x16x32_bf16 v[42:45], v[174:177], v[198:201], v[42:45]
	v_mfma_f32_16x16x32_bf16 v[38:41], v[166:169], v[206:209], v[38:41]
	v_mfma_f32_16x16x32_bf16 v[34:37], v[174:177], v[206:209], v[34:37]
	s_setprio 0
	s_barrier
	s_add_i32 s13, s13, s46
	s_mov_b32 m0, s13
	ds_read_b128 v[178:181], v230 offset:49152
	ds_read_b128 v[182:185], v230 offset:50176
	ds_read_b128 v[186:189], v230 offset:51200
	ds_read_b128 v[190:193], v230 offset:52224
	ds_read_b128 v[194:197], v230 offset:53248
	ds_read_b128 v[198:201], v230 offset:54272
	ds_read_b128 v[202:205], v230 offset:55296
	ds_read_b128 v[206:209], v230 offset:56320
	global_load_lds_dwordx4 v251, s[40:41]
	s_add_i32 m0, s13, 0x2000
	s_add_u32 s40, s40, 0x40080
	v_lshl_add_u64 v[210:211], v[212:213], 0, s[20:21]
	s_addc_u32 s41, s41, 0
	s_add_i32 s13, s70, s46
	global_load_lds_dwordx4 v[210:211], off
	s_mov_b32 m0, s13
	s_nop 0
	global_load_lds_dwordx4 v140, s[40:41]
	s_add_i32 m0, s13, 0x2000
	s_nop 0
	global_load_lds_dwordx4 v144, s[40:41]
	v_lshl_add_u64 v[210:211], v[214:215], 0, s[20:21]
	s_mov_b32 m0, s60
	s_nop 0
	global_load_lds_dwordx4 v[210:211], off
	v_lshl_add_u64 v[210:211], v[216:217], 0, s[20:21]
	s_mov_b32 m0, s61
	s_nop 0
	global_load_lds_dwordx4 v[210:211], off
	s_waitcnt vmcnt(8)
	s_waitcnt lgkmcnt(0)
	s_barrier
	s_setprio 1
	s_waitcnt lgkmcnt(0)
	v_mfma_f32_16x16x32_bf16 v[94:97], v[130:133], v[178:181], v[94:97]
	v_mfma_f32_16x16x32_bf16 v[90:93], v[154:157], v[178:181], v[90:93]
	v_mfma_f32_16x16x32_bf16 v[86:89], v[130:133], v[186:189], v[86:89]
	v_mfma_f32_16x16x32_bf16 v[82:85], v[154:157], v[186:189], v[82:85]
	v_mfma_f32_16x16x32_bf16 v[78:81], v[130:133], v[194:197], v[78:81]
	v_mfma_f32_16x16x32_bf16 v[74:77], v[154:157], v[194:197], v[74:77]
	v_mfma_f32_16x16x32_bf16 v[70:73], v[130:133], v[202:205], v[70:73]
	v_mfma_f32_16x16x32_bf16 v[66:69], v[154:157], v[202:205], v[66:69]
	v_mfma_f32_16x16x32_bf16 v[94:97], v[134:137], v[182:185], v[94:97]
	v_mfma_f32_16x16x32_bf16 v[90:93], v[158:161], v[182:185], v[90:93]
	v_mfma_f32_16x16x32_bf16 v[86:89], v[134:137], v[190:193], v[86:89]
	v_mfma_f32_16x16x32_bf16 v[82:85], v[158:161], v[190:193], v[82:85]
	v_mfma_f32_16x16x32_bf16 v[78:81], v[134:137], v[198:201], v[78:81]
	v_mfma_f32_16x16x32_bf16 v[74:77], v[158:161], v[198:201], v[74:77]
	v_mfma_f32_16x16x32_bf16 v[70:73], v[134:137], v[206:209], v[70:73]
	v_mfma_f32_16x16x32_bf16 v[66:69], v[158:161], v[206:209], v[66:69]
	s_setprio 0
	s_setprio 1
	v_mfma_f32_16x16x32_bf16 v[30:33], v[162:165], v[178:181], v[30:33]
	v_mfma_f32_16x16x32_bf16 v[26:29], v[170:173], v[178:181], v[26:29]
	v_mfma_f32_16x16x32_bf16 v[22:25], v[162:165], v[186:189], v[22:25]
	v_mfma_f32_16x16x32_bf16 v[18:21], v[170:173], v[186:189], v[18:21]
	v_mfma_f32_16x16x32_bf16 v[14:17], v[162:165], v[194:197], v[14:17]
	v_mfma_f32_16x16x32_bf16 v[10:13], v[170:173], v[194:197], v[10:13]
	v_mfma_f32_16x16x32_bf16 v[6:9], v[162:165], v[202:205], v[6:9]
	v_mfma_f32_16x16x32_bf16 v[2:5], v[170:173], v[202:205], v[2:5]
	v_mfma_f32_16x16x32_bf16 v[30:33], v[166:169], v[182:185], v[30:33]
	v_mfma_f32_16x16x32_bf16 v[26:29], v[174:177], v[182:185], v[26:29]
	v_mfma_f32_16x16x32_bf16 v[22:25], v[166:169], v[190:193], v[22:25]
	v_mfma_f32_16x16x32_bf16 v[18:21], v[174:177], v[190:193], v[18:21]
	v_mfma_f32_16x16x32_bf16 v[14:17], v[166:169], v[198:201], v[14:17]
	v_mfma_f32_16x16x32_bf16 v[10:13], v[174:177], v[198:201], v[10:13]
	v_mfma_f32_16x16x32_bf16 v[6:9], v[166:169], v[206:209], v[6:9]
	v_mfma_f32_16x16x32_bf16 v[2:5], v[174:177], v[206:209], v[2:5]
	s_setprio 0
	s_barrier
	s_add_i32 s12, s12, 2
	s_add_u32 s30, s30, 0x100
	s_addc_u32 s31, s31, 0
	s_add_u32 s68, s68, 0x100
	s_addc_u32 s69, s69, 0
	s_cmp_gt_u32 s12, 13
	s_cbranch_scc0 .LBB0_1394
	s_ashr_i32 s12, s36, 3
	s_ashr_i32 s37, s36, 31
	s_mul_i32 s25, s12, 0x6000
	s_mul_hi_i32 s23, s12, 0x6000
	s_add_u32 s12, s57, s25
	v_mov_b32_e32 v130, v1
	s_addc_u32 s13, s58, s23
	s_lshl_b64 s[30:31], s[36:37], 19
	v_lshl_or_b32 v166, s38, 8, v227
	s_add_u32 s40, s51, s30
	v_add_u32_e32 v160, s59, v130
	v_ashrrev_i32_e32 v167, 31, v166
	s_addc_u32 s41, s52, s31
	v_lshlrev_b64 v[156:157], 1, v[166:167]
	v_ashrrev_i32_e32 v161, 31, v160
	v_lshlrev_b64 v[130:131], 2, v[166:167]
	v_lshl_add_u64 v[162:163], s[40:41], 0, v[156:157]
	v_lshlrev_b64 v[154:155], 11, v[160:161]
	v_add_u32_e32 v170, 16, v160
	v_lshl_add_u64 v[172:173], s[12:13], 0, v[130:131]
	v_lshl_add_u64 v[174:175], v[162:163], 0, v[154:155]
	v_ashrrev_i32_e32 v171, 31, v170
	s_add_u32 s12, s53, s30
	v_lshl_add_u64 v[132:133], s[0:1], 0, v[130:131]
	global_load_dwordx4 v[180:183], v[172:173], off offset:16
	global_load_dwordx4 v[184:187], v[172:173], off
	global_load_dwordx4 v[188:191], v[132:133], off offset:16
	global_load_dwordx4 v[192:195], v[132:133], off
	global_load_dwordx4 v[196:199], v[174:175], off nt
	v_lshlrev_b64 v[204:205], 11, v[170:171]
	s_addc_u32 s13, s54, s31
	v_lshl_add_u64 v[178:179], v[162:163], 0, v[204:205]
	s_add_u32 s30, s55, s25
	global_load_dwordx4 v[200:203], v[178:179], off nt
	s_addc_u32 s31, s56, s23
	v_lshl_add_u64 v[176:177], s[30:31], 0, v[130:131]
	global_load_dwordx4 v[134:137], v[176:177], off
	global_load_dwordx4 v[130:133], v[176:177], off offset:16
	v_lshl_add_u64 v[158:159], s[12:13], 0, v[156:157]
	s_lshl_b32 s12, s36, 8
	v_lshl_add_u64 v[164:165], v[158:159], 0, v[154:155]
	v_add_u32_e32 v154, s12, v160
	v_ashrrev_i32_e32 v155, 31, v154
	v_lshlrev_b64 v[168:169], 11, v[154:155]
	v_lshl_add_u64 v[168:169], s[8:9], 0, v[168:169]
	v_add_u32_e32 v170, s12, v170
	v_lshl_add_u64 v[168:169], v[168:169], 0, v[156:157]
	v_ashrrev_i32_e32 v171, 31, v170
	v_lshlrev_b64 v[170:171], 11, v[170:171]
	v_lshl_add_u64 v[170:171], s[8:9], 0, v[170:171]
	s_waitcnt vmcnt(0)
	v_pk_add_f32 v[182:183], v[182:183], 1.0 op_sel_hi:[1,0]
	v_pk_add_f32 v[186:187], v[186:187], 1.0 op_sel_hi:[1,0]
	v_pk_add_f32 v[184:185], v[184:185], 1.0 op_sel_hi:[1,0]
	v_pk_add_f32 v[180:181], v[180:181], 1.0 op_sel_hi:[1,0]
	v_pk_mul_f32 v[216:217], v[194:195], v[186:187]
	v_pk_mul_f32 v[218:219], v[192:193], v[184:185]
	v_pk_mul_f32 v[220:221], v[190:191], v[182:183]
	v_pk_mul_f32 v[222:223], v[188:189], v[180:181]
	v_cvt_f32_f16_e32 v180, v198
	v_cvt_f32_f16_sdwa v181, v198 dst_sel:DWORD dst_unused:UNUSED_PAD src0_sel:WORD_1
	v_cvt_f32_f16_e32 v182, v199
	v_cvt_f32_f16_sdwa v183, v199 dst_sel:DWORD dst_unused:UNUSED_PAD src0_sel:WORD_1
	v_cvt_f32_f16_e32 v184, v196
	v_cvt_f32_f16_sdwa v185, v196 dst_sel:DWORD dst_unused:UNUSED_PAD src0_sel:WORD_1
	v_cvt_f32_f16_e32 v186, v197
	v_cvt_f32_f16_sdwa v187, v197 dst_sel:DWORD dst_unused:UNUSED_PAD src0_sel:WORD_1
	v_cvt_f32_f16_e32 v188, v202
	v_cvt_f32_f16_sdwa v189, v202 dst_sel:DWORD dst_unused:UNUSED_PAD src0_sel:WORD_1
	v_cvt_f32_f16_e32 v190, v203
	v_cvt_f32_f16_sdwa v191, v203 dst_sel:DWORD dst_unused:UNUSED_PAD src0_sel:WORD_1
	v_cvt_f32_f16_e32 v192, v200
	v_cvt_f32_f16_sdwa v193, v200 dst_sel:DWORD dst_unused:UNUSED_PAD src0_sel:WORD_1
	v_cvt_f32_f16_e32 v194, v201
	v_cvt_f32_f16_sdwa v195, v201 dst_sel:DWORD dst_unused:UNUSED_PAD src0_sel:WORD_1
	v_pk_fma_f32 v[128:129], v[128:129], v[136:137], v[186:187]
	v_pk_fma_f32 v[126:127], v[126:127], v[134:135], v[184:185]
	v_pk_fma_f32 v[124:125], v[124:125], v[132:133], v[182:183]
	v_pk_fma_f32 v[122:123], v[122:123], v[130:131], v[180:181]
	v_cvt_pk_f16_f32 v183, v124, v125
	v_cvt_pk_f16_f32 v181, v128, v129
	v_cvt_pk_f16_f32 v182, v122, v123
	v_cvt_pk_f16_f32 v180, v126, v127
	v_pk_fma_f32 v[120:121], v[120:121], v[136:137], v[194:195]
	v_pk_fma_f32 v[118:119], v[118:119], v[134:135], v[192:193]
	v_pk_fma_f32 v[116:117], v[116:117], v[132:133], v[190:191]
	v_pk_fma_f32 v[114:115], v[114:115], v[130:131], v[188:189]
	v_pk_mul_f32 v[188:189], v[216:217], v[128:129]
	v_pk_mul_f32 v[190:191], v[218:219], v[126:127]
	global_store_dwordx4 v[164:165], v[180:183], off
	v_pk_mul_f32 v[192:193], v[220:221], v[124:125]
	v_pk_mul_f32 v[194:195], v[222:223], v[122:123]
	v_cvt_pk_bf16_f32 v180, v190, v191
	v_cvt_pk_bf16_f32 v181, v188, v189
	v_cvt_pk_f16_f32 v187, v116, v117
	v_cvt_pk_f16_f32 v185, v120, v121
	v_cvt_pk_f16_f32 v186, v114, v115
	v_cvt_pk_bf16_f32 v182, v194, v195
	v_cvt_pk_bf16_f32 v183, v192, v193
	global_store_dwordx4 v[168:169], v[180:183], off
	v_cvt_pk_f16_f32 v184, v118, v119
	v_pk_mul_f32 v[188:189], v[222:223], v[114:115]
	v_lshl_add_u64 v[180:181], v[158:159], 0, v[204:205]
	global_store_dwordx4 v[180:181], v[184:187], off
	v_pk_mul_f32 v[182:183], v[218:219], v[118:119]
	v_add_u32_e32 v192, 48, v160
	v_pk_mul_f32 v[184:185], v[216:217], v[120:121]
	v_pk_mul_f32 v[186:187], v[220:221], v[116:117]
	v_cvt_pk_bf16_f32 v182, v182, v183
	v_cvt_pk_bf16_f32 v183, v184, v185
	v_cvt_pk_bf16_f32 v184, v188, v189
	v_ashrrev_i32_e32 v193, 31, v192
	v_cvt_pk_bf16_f32 v185, v186, v187
	v_lshl_add_u64 v[186:187], v[170:171], 0, v[156:157]
	global_store_dwordx4 v[186:187], v[182:185], off
	v_mul_f32_e32 v127, v127, v127
	v_mul_f32_e32 v129, v129, v129
	v_add_u32_e32 v182, 32, v160
	v_ashrrev_i32_e32 v183, 31, v182
	v_lshlrev_b64 v[170:171], 11, v[182:183]
	v_lshl_add_u64 v[188:189], v[162:163], 0, v[170:171]
	global_load_dwordx4 v[194:197], v[188:189], off nt
	v_lshlrev_b64 v[184:185], 11, v[192:193]
	v_lshl_add_u64 v[190:191], v[162:163], 0, v[184:185]
	global_load_dwordx4 v[198:201], v[190:191], off nt
	v_add_u32_e32 v182, s12, v182
	v_add_u32_e32 v192, s12, v192
	v_ashrrev_i32_e32 v183, 31, v182
	v_ashrrev_i32_e32 v193, 31, v192
	v_lshlrev_b64 v[182:183], 11, v[182:183]
	v_lshlrev_b64 v[192:193], 11, v[192:193]
	v_lshl_add_u64 v[182:183], s[8:9], 0, v[182:183]
	v_lshl_add_u64 v[202:203], s[8:9], 0, v[192:193]
	v_lshl_add_u64 v[192:193], v[182:183], 0, v[156:157]
	v_lshl_add_u64 v[170:171], v[158:159], 0, v[170:171]
	v_lshl_add_u64 v[184:185], v[158:159], 0, v[184:185]
	v_mul_f32_e32 v123, v123, v123
	v_mul_f32_e32 v125, v125, v125
	v_fmac_f32_e32 v127, v126, v126
	v_fmac_f32_e32 v129, v128, v128
	v_fmac_f32_e32 v123, v122, v122
	v_fmac_f32_e32 v125, v124, v124
	v_add_f32_e32 v122, v127, v129
	v_add_f32_e32 v123, v123, v125
	v_add_f32_e32 v122, v122, v123
	s_waitcnt vmcnt(1)
	v_cvt_f32_f16_e32 v182, v196
	v_cvt_f32_f16_sdwa v183, v196 dst_sel:DWORD dst_unused:UNUSED_PAD src0_sel:WORD_1
	v_cvt_f32_f16_e32 v196, v197
	v_cvt_f32_f16_sdwa v197, v197 dst_sel:DWORD dst_unused:UNUSED_PAD src0_sel:WORD_1
	v_cvt_f32_f16_e32 v204, v194
	v_cvt_f32_f16_sdwa v205, v194 dst_sel:DWORD dst_unused:UNUSED_PAD src0_sel:WORD_1
	v_cvt_f32_f16_e32 v194, v195
	v_cvt_f32_f16_sdwa v195, v195 dst_sel:DWORD dst_unused:UNUSED_PAD src0_sel:WORD_1
	s_waitcnt vmcnt(0)
	v_cvt_f32_f16_e32 v206, v200
	v_cvt_f32_f16_sdwa v207, v200 dst_sel:DWORD dst_unused:UNUSED_PAD src0_sel:WORD_1
	v_cvt_f32_f16_e32 v208, v198
	v_cvt_f32_f16_sdwa v209, v198 dst_sel:DWORD dst_unused:UNUSED_PAD src0_sel:WORD_1
	v_cvt_f32_f16_e32 v198, v199
	v_cvt_f32_f16_sdwa v199, v199 dst_sel:DWORD dst_unused:UNUSED_PAD src0_sel:WORD_1
	v_cvt_f32_f16_e32 v200, v201
	v_cvt_f32_f16_sdwa v201, v201 dst_sel:DWORD dst_unused:UNUSED_PAD src0_sel:WORD_1
	v_pk_fma_f32 v[112:113], v[112:113], v[136:137], v[194:195]
	v_pk_fma_f32 v[110:111], v[110:111], v[134:135], v[204:205]
	v_pk_fma_f32 v[108:109], v[108:109], v[132:133], v[196:197]
	v_pk_fma_f32 v[106:107], v[106:107], v[130:131], v[182:183]
	v_cvt_pk_f16_f32 v197, v108, v109
	v_cvt_pk_f16_f32 v195, v112, v113
	v_cvt_pk_f16_f32 v196, v106, v107
	v_cvt_pk_f16_f32 v194, v110, v111
	v_pk_mul_f32 v[182:183], v[216:217], v[112:113]
	v_pk_fma_f32 v[104:105], v[104:105], v[136:137], v[198:199]
	v_pk_fma_f32 v[102:103], v[102:103], v[134:135], v[208:209]
	v_pk_fma_f32 v[98:99], v[98:99], v[130:131], v[206:207]
	v_pk_mul_f32 v[204:205], v[218:219], v[110:111]
	v_pk_mul_f32 v[206:207], v[220:221], v[108:109]
	global_store_dwordx4 v[170:171], v[194:197], off
	v_pk_fma_f32 v[100:101], v[100:101], v[132:133], v[200:201]
	v_pk_mul_f32 v[208:209], v[222:223], v[106:107]
	v_cvt_pk_bf16_f32 v194, v204, v205
	v_cvt_pk_bf16_f32 v195, v182, v183
	v_add_u32_e32 v182, 0x80, v160
	v_cvt_pk_f16_f32 v199, v104, v105
	v_cvt_pk_f16_f32 v198, v102, v103
	v_cvt_pk_bf16_f32 v196, v208, v209
	v_cvt_pk_bf16_f32 v197, v206, v207
	v_ashrrev_i32_e32 v183, 31, v182
	v_add_u32_e32 v206, 0x90, v160
	v_cvt_pk_f16_f32 v201, v100, v101
	v_cvt_pk_f16_f32 v200, v98, v99
	v_pk_mul_f32 v[210:211], v[216:217], v[104:105]
	v_pk_mul_f32 v[212:213], v[218:219], v[102:103]
	global_store_dwordx4 v[192:193], v[194:197], off
	global_store_dwordx4 v[184:185], v[198:201], off
	v_ashrrev_i32_e32 v207, 31, v206
	v_lshl_add_u64 v[196:197], v[202:203], 0, v[156:157]
	v_cvt_pk_bf16_f32 v198, v212, v213
	v_cvt_pk_bf16_f32 v199, v210, v211
	v_lshlrev_b64 v[194:195], 11, v[182:183]
	v_pk_mul_f32 v[214:215], v[220:221], v[100:101]
	v_pk_mul_f32 v[224:225], v[222:223], v[98:99]
	v_lshlrev_b64 v[208:209], 11, v[206:207]
	v_cvt_pk_bf16_f32 v200, v224, v225
	v_cvt_pk_bf16_f32 v201, v214, v215
	global_store_dwordx4 v[196:197], v[198:201], off
	v_lshl_add_u64 v[204:205], v[162:163], 0, v[208:209]
	global_load_dwordx4 v[236:239], v[204:205], off nt
	v_lshl_add_u64 v[198:199], v[162:163], 0, v[194:195]
	global_load_dwordx4 v[232:235], v[198:199], off nt
	v_lshl_add_u64 v[212:213], v[158:159], 0, v[194:195]
	v_add_u32_e32 v182, s12, v182
	v_add_u32_e32 v194, s12, v206
	v_ashrrev_i32_e32 v183, 31, v182
	v_ashrrev_i32_e32 v195, 31, v194
	v_lshlrev_b64 v[182:183], 11, v[182:183]
	v_lshlrev_b64 v[194:195], 11, v[194:195]
	v_lshl_add_u64 v[182:183], s[8:9], 0, v[182:183]
	v_lshl_add_u64 v[194:195], s[8:9], 0, v[194:195]
	v_lshl_add_u64 v[210:211], v[158:159], 0, v[208:209]
	v_lshl_add_u64 v[214:215], v[182:183], 0, v[156:157]
	v_lshl_add_u64 v[208:209], v[194:195], 0, v[156:157]
	v_add_u32_e32 v200, 0xa0, v160
	v_ashrrev_i32_e32 v201, 31, v200
	v_lshlrev_b64 v[240:241], 11, v[200:201]
	v_lshl_add_u64 v[202:203], v[162:163], 0, v[240:241]
	s_waitcnt vmcnt(0)
	v_cvt_f32_f16_e32 v182, v234
	v_cvt_f32_f16_sdwa v183, v234 dst_sel:DWORD dst_unused:UNUSED_PAD src0_sel:WORD_1
	v_cvt_f32_f16_e32 v194, v235
	v_cvt_f32_f16_sdwa v195, v235 dst_sel:DWORD dst_unused:UNUSED_PAD src0_sel:WORD_1
	v_cvt_f32_f16_e32 v206, v232
	v_cvt_f32_f16_sdwa v207, v232 dst_sel:DWORD dst_unused:UNUSED_PAD src0_sel:WORD_1
	v_cvt_f32_f16_e32 v224, v233
	v_cvt_f32_f16_sdwa v225, v233 dst_sel:DWORD dst_unused:UNUSED_PAD src0_sel:WORD_1
	v_cvt_f32_f16_e32 v232, v238
	v_cvt_f32_f16_sdwa v233, v238 dst_sel:DWORD dst_unused:UNUSED_PAD src0_sel:WORD_1
	v_cvt_f32_f16_e32 v234, v239
	v_cvt_f32_f16_sdwa v235, v239 dst_sel:DWORD dst_unused:UNUSED_PAD src0_sel:WORD_1
	v_cvt_f32_f16_e32 v238, v236
	v_cvt_f32_f16_sdwa v239, v236 dst_sel:DWORD dst_unused:UNUSED_PAD src0_sel:WORD_1
	v_cvt_f32_f16_e32 v236, v237
	v_cvt_f32_f16_sdwa v237, v237 dst_sel:DWORD dst_unused:UNUSED_PAD src0_sel:WORD_1
	v_pk_fma_f32 v[96:97], v[96:97], v[136:137], v[224:225]
	v_pk_fma_f32 v[94:95], v[94:95], v[134:135], v[206:207]
	v_pk_fma_f32 v[92:93], v[92:93], v[132:133], v[194:195]
	v_pk_fma_f32 v[90:91], v[90:91], v[130:131], v[182:183]
	v_pk_fma_f32 v[84:85], v[84:85], v[132:133], v[234:235]
	v_pk_fma_f32 v[82:83], v[82:83], v[130:131], v[232:233]
	v_cvt_pk_f16_f32 v235, v92, v93
	v_cvt_pk_f16_f32 v233, v96, v97
	v_cvt_pk_f16_f32 v234, v90, v91
	v_cvt_pk_f16_f32 v232, v94, v95
	v_pk_mul_f32 v[206:207], v[220:221], v[92:93]
	v_pk_mul_f32 v[182:183], v[216:217], v[96:97]
	v_pk_mul_f32 v[194:195], v[218:219], v[94:95]
	v_pk_mul_f32 v[224:225], v[222:223], v[90:91]
	global_store_dwordx4 v[212:213], v[232:235], off
	v_pk_fma_f32 v[88:89], v[88:89], v[136:137], v[236:237]
	v_pk_fma_f32 v[86:87], v[86:87], v[134:135], v[238:239]
	v_cvt_pk_bf16_f32 v232, v194, v195
	v_cvt_pk_bf16_f32 v233, v182, v183
	v_cvt_pk_bf16_f32 v234, v224, v225
	v_cvt_pk_bf16_f32 v235, v206, v207
	v_add_u32_e32 v206, 0xb0, v160
	v_ashrrev_i32_e32 v207, 31, v206
	v_cvt_pk_f16_f32 v239, v84, v85
	v_cvt_pk_f16_f32 v237, v88, v89
	v_cvt_pk_f16_f32 v238, v82, v83
	v_cvt_pk_f16_f32 v236, v86, v87
	v_pk_mul_f32 v[242:243], v[216:217], v[88:89]
	v_pk_mul_f32 v[244:245], v[218:219], v[86:87]
	v_pk_mul_f32 v[246:247], v[220:221], v[84:85]
	v_pk_mul_f32 v[248:249], v[222:223], v[82:83]
	global_store_dwordx4 v[214:215], v[232:235], off
	global_store_dwordx4 v[210:211], v[236:239], off
	v_lshlrev_b64 v[194:195], 11, v[206:207]
	v_cvt_pk_bf16_f32 v232, v244, v245
	v_cvt_pk_bf16_f32 v233, v242, v243
	v_cvt_pk_bf16_f32 v234, v248, v249
	v_cvt_pk_bf16_f32 v235, v246, v247
	global_store_dwordx4 v[208:209], v[232:235], off
	global_load_dwordx4 v[232:235], v[202:203], off nt
	v_lshl_add_u64 v[224:225], v[162:163], 0, v[194:195]
	global_load_dwordx4 v[160:163], v[224:225], off nt
	v_lshl_add_u64 v[182:183], v[158:159], 0, v[240:241]
	v_lshl_add_u64 v[194:195], v[158:159], 0, v[194:195]
	v_add_u32_e32 v158, s12, v200
	v_add_u32_e32 v200, s12, v206
	v_ashrrev_i32_e32 v159, 31, v158
	v_ashrrev_i32_e32 v201, 31, v200
	v_lshlrev_b64 v[158:159], 11, v[158:159]
	v_lshlrev_b64 v[200:201], 11, v[200:201]
	v_lshl_add_u64 v[158:159], s[8:9], 0, v[158:159]
	v_lshl_add_u64 v[200:201], s[8:9], 0, v[200:201]
	v_lshl_add_u64 v[206:207], v[158:159], 0, v[156:157]
	v_lshl_add_u64 v[200:201], v[200:201], 0, v[156:157]
	s_waitcnt vmcnt(1)
	v_cvt_f32_f16_e32 v158, v234
	v_cvt_f32_f16_sdwa v159, v234 dst_sel:DWORD dst_unused:UNUSED_PAD src0_sel:WORD_1
	v_cvt_f32_f16_e32 v156, v235
	v_cvt_f32_f16_sdwa v157, v235 dst_sel:DWORD dst_unused:UNUSED_PAD src0_sel:WORD_1
	v_cvt_f32_f16_e32 v234, v232
	v_cvt_f32_f16_sdwa v235, v232 dst_sel:DWORD dst_unused:UNUSED_PAD src0_sel:WORD_1
	v_cvt_f32_f16_e32 v232, v233
	v_cvt_f32_f16_sdwa v233, v233 dst_sel:DWORD dst_unused:UNUSED_PAD src0_sel:WORD_1
	s_waitcnt vmcnt(0)
	v_cvt_f32_f16_e32 v236, v162
	v_cvt_f32_f16_sdwa v237, v162 dst_sel:DWORD dst_unused:UNUSED_PAD src0_sel:WORD_1
	v_cvt_f32_f16_e32 v238, v163
	v_cvt_f32_f16_sdwa v239, v163 dst_sel:DWORD dst_unused:UNUSED_PAD src0_sel:WORD_1
	v_cvt_f32_f16_e32 v240, v160
	v_cvt_f32_f16_sdwa v241, v160 dst_sel:DWORD dst_unused:UNUSED_PAD src0_sel:WORD_1
	v_cvt_f32_f16_e32 v242, v161
	v_cvt_f32_f16_sdwa v243, v161 dst_sel:DWORD dst_unused:UNUSED_PAD src0_sel:WORD_1
	v_pk_fma_f32 v[160:161], v[80:81], v[136:137], v[232:233]
	v_pk_fma_f32 v[162:163], v[78:79], v[134:135], v[234:235]
	v_pk_fma_f32 v[156:157], v[76:77], v[132:133], v[156:157]
	v_pk_fma_f32 v[158:159], v[74:75], v[130:131], v[158:159]
	v_pk_fma_f32 v[74:75], v[68:69], v[132:133], v[238:239]
	v_pk_fma_f32 v[76:77], v[66:67], v[130:131], v[236:237]
	v_cvt_pk_f16_f32 v69, v156, v157
	v_cvt_pk_f16_f32 v67, v160, v161
	v_cvt_pk_f16_f32 v68, v158, v159
	v_cvt_pk_f16_f32 v66, v162, v163
	v_pk_fma_f32 v[78:79], v[72:73], v[136:137], v[242:243]
	v_pk_fma_f32 v[80:81], v[70:71], v[134:135], v[240:241]
	v_pk_mul_f32 v[130:131], v[216:217], v[160:161]
	v_pk_mul_f32 v[132:133], v[218:219], v[162:163]
	v_pk_mul_f32 v[134:135], v[220:221], v[156:157]
	v_pk_mul_f32 v[136:137], v[222:223], v[158:159]
	global_store_dwordx4 v[182:183], v[66:69], off
	v_cvt_pk_f16_f32 v73, v74, v75
	v_cvt_pk_f16_f32 v71, v78, v79
	v_cvt_pk_bf16_f32 v66, v132, v133
	v_cvt_pk_bf16_f32 v67, v130, v131
	v_cvt_pk_bf16_f32 v68, v136, v137
	v_cvt_pk_bf16_f32 v69, v134, v135
	v_cvt_pk_f16_f32 v72, v76, v77
	v_cvt_pk_f16_f32 v70, v80, v81
	v_pk_mul_f32 v[216:217], v[216:217], v[78:79]
	v_pk_mul_f32 v[218:219], v[218:219], v[80:81]
	v_pk_mul_f32 v[220:221], v[220:221], v[74:75]
	v_pk_mul_f32 v[222:223], v[222:223], v[76:77]
	global_store_dwordx4 v[206:207], v[66:69], off
	global_store_dwordx4 v[194:195], v[70:73], off
	s_nop 0
	v_cvt_pk_bf16_f32 v66, v218, v219
	v_cvt_pk_bf16_f32 v67, v216, v217
	v_cvt_pk_bf16_f32 v68, v222, v223
	v_cvt_pk_bf16_f32 v69, v220, v221
	global_store_dwordx4 v[200:201], v[66:69], off
	global_load_dwordx4 v[130:133], v[172:173], off offset:512
	global_load_dwordx4 v[134:137], v[172:173], off offset:528
	s_nop 0
	global_load_dwordx4 v[172:175], v[174:175], off offset:256 nt
	s_nop 0
	global_load_dwordx4 v[216:219], v[178:179], off offset:256 nt
	v_or_b32_e32 v66, 0x80, v166
	v_ashrrev_i32_e32 v67, 31, v66
	v_lshl_add_u64 v[66:67], v[66:67], 2, s[0:1]
	global_load_dwordx4 v[220:223], v[66:67], off
	global_load_dwordx4 v[232:235], v[66:67], off offset:16
	global_load_dwordx4 v[70:73], v[176:177], off offset:512
	s_nop 0
	global_load_dwordx4 v[66:69], v[176:177], off offset:528
	s_waitcnt vmcnt(7)
	v_pk_add_f32 v[132:133], v[132:133], 1.0 op_sel_hi:[1,0]
	v_pk_add_f32 v[166:167], v[130:131], 1.0 op_sel_hi:[1,0]
	s_waitcnt vmcnt(5)
	v_cvt_f32_f16_e32 v178, v174
	v_cvt_f32_f16_sdwa v179, v174 dst_sel:DWORD dst_unused:UNUSED_PAD src0_sel:WORD_1
	v_cvt_f32_f16_e32 v174, v175
	v_cvt_f32_f16_sdwa v175, v175 dst_sel:DWORD dst_unused:UNUSED_PAD src0_sel:WORD_1
	v_cvt_f32_f16_e32 v236, v172
	v_cvt_f32_f16_sdwa v237, v172 dst_sel:DWORD dst_unused:UNUSED_PAD src0_sel:WORD_1
	v_cvt_f32_f16_e32 v172, v173
	v_cvt_f32_f16_sdwa v173, v173 dst_sel:DWORD dst_unused:UNUSED_PAD src0_sel:WORD_1
	s_waitcnt vmcnt(4)
	v_cvt_f32_f16_e32 v238, v218
	v_cvt_f32_f16_sdwa v239, v218 dst_sel:DWORD dst_unused:UNUSED_PAD src0_sel:WORD_1
	v_cvt_f32_f16_e32 v218, v219
	v_cvt_f32_f16_sdwa v219, v219 dst_sel:DWORD dst_unused:UNUSED_PAD src0_sel:WORD_1
	v_cvt_f32_f16_e32 v240, v216
	v_cvt_f32_f16_sdwa v241, v216 dst_sel:DWORD dst_unused:UNUSED_PAD src0_sel:WORD_1
	v_cvt_f32_f16_e32 v216, v217
	v_cvt_f32_f16_sdwa v217, v217 dst_sel:DWORD dst_unused:UNUSED_PAD src0_sel:WORD_1
	v_pk_add_f32 v[136:137], v[136:137], 1.0 op_sel_hi:[1,0]
	v_pk_add_f32 v[176:177], v[134:135], 1.0 op_sel_hi:[1,0]
	s_waitcnt vmcnt(3)
	v_pk_mul_f32 v[130:131], v[222:223], v[132:133]
	s_waitcnt vmcnt(1)
	v_pk_fma_f32 v[64:65], v[64:65], v[72:73], v[172:173]
	v_pk_fma_f32 v[62:63], v[62:63], v[70:71], v[236:237]
	s_waitcnt vmcnt(0)
	v_pk_fma_f32 v[60:61], v[60:61], v[68:69], v[174:175]
	v_pk_fma_f32 v[58:59], v[58:59], v[66:67], v[178:179]
	v_pk_mul_f32 v[132:133], v[220:221], v[166:167]
	v_pk_mul_f32 v[134:135], v[234:235], v[136:137]
	v_pk_mul_f32 v[136:137], v[232:233], v[176:177]
	v_cvt_pk_f16_f32 v175, v60, v61
	v_cvt_pk_f16_f32 v173, v64, v65
	v_cvt_pk_f16_f32 v174, v58, v59
	v_cvt_pk_f16_f32 v172, v62, v63
	v_pk_mul_f32 v[166:167], v[130:131], v[64:65]
	v_pk_fma_f32 v[56:57], v[56:57], v[72:73], v[216:217]
	v_pk_fma_f32 v[54:55], v[54:55], v[70:71], v[240:241]
	v_pk_fma_f32 v[52:53], v[52:53], v[68:69], v[218:219]
	v_pk_fma_f32 v[50:51], v[50:51], v[66:67], v[238:239]
	v_pk_mul_f32 v[216:217], v[132:133], v[62:63]
	v_pk_mul_f32 v[218:219], v[134:135], v[60:61]
	v_pk_mul_f32 v[220:221], v[136:137], v[58:59]
	global_store_dwordx4 v[164:165], v[172:175], off offset:256
	v_cvt_pk_bf16_f32 v164, v216, v217
	v_cvt_pk_bf16_f32 v165, v166, v167
	v_cvt_pk_bf16_f32 v166, v220, v221
	v_cvt_pk_bf16_f32 v167, v218, v219
	v_cvt_pk_f16_f32 v179, v52, v53
	v_cvt_pk_f16_f32 v177, v56, v57
	v_cvt_pk_f16_f32 v178, v50, v51
	v_cvt_pk_f16_f32 v176, v54, v55
	v_pk_mul_f32 v[222:223], v[130:131], v[56:57]
	v_pk_mul_f32 v[232:233], v[132:133], v[54:55]
	v_pk_mul_f32 v[234:235], v[134:135], v[52:53]
	v_pk_mul_f32 v[236:237], v[136:137], v[50:51]
	global_store_dwordx4 v[168:169], v[164:167], off offset:256
	global_store_dwordx4 v[180:181], v[176:179], off offset:256
	v_mul_f32_e32 v63, v63, v63
	v_cvt_pk_bf16_f32 v164, v232, v233
	v_cvt_pk_bf16_f32 v165, v222, v223
	v_cvt_pk_bf16_f32 v166, v236, v237
	v_cvt_pk_bf16_f32 v167, v234, v235
	global_store_dwordx4 v[186:187], v[164:167], off offset:256
	global_load_dwordx4 v[164:167], v[188:189], off offset:256 nt
	s_nop 0
	global_load_dwordx4 v[172:175], v[190:191], off offset:256 nt
	v_mul_f32_e32 v65, v65, v65
	v_mul_f32_e32 v59, v59, v59
	v_mul_f32_e32 v61, v61, v61
	v_fmac_f32_e32 v63, v62, v62
	v_fmac_f32_e32 v65, v64, v64
	v_fmac_f32_e32 v59, v58, v58
	v_fmac_f32_e32 v61, v60, v60
	v_add_f32_e32 v58, v63, v65
	v_add_f32_e32 v59, v59, v61
	v_add_f32_e32 v58, v58, v59
	v_add_f32_e32 v59, v122, v58
	v_xor_b32_e32 v58, 32, v231
	s_waitcnt vmcnt(1)
	v_cvt_f32_f16_e32 v168, v166
	v_cvt_f32_f16_sdwa v169, v166 dst_sel:DWORD dst_unused:UNUSED_PAD src0_sel:WORD_1
	v_cvt_f32_f16_e32 v166, v167
	v_cvt_f32_f16_sdwa v167, v167 dst_sel:DWORD dst_unused:UNUSED_PAD src0_sel:WORD_1
	v_cvt_f32_f16_e32 v176, v164
	v_cvt_f32_f16_sdwa v177, v164 dst_sel:DWORD dst_unused:UNUSED_PAD src0_sel:WORD_1
	v_cvt_f32_f16_e32 v164, v165
	v_cvt_f32_f16_sdwa v165, v165 dst_sel:DWORD dst_unused:UNUSED_PAD src0_sel:WORD_1
	s_waitcnt vmcnt(0)
	v_cvt_f32_f16_e32 v178, v174
	v_cvt_f32_f16_sdwa v179, v174 dst_sel:DWORD dst_unused:UNUSED_PAD src0_sel:WORD_1
	v_cvt_f32_f16_e32 v174, v175
	v_cvt_f32_f16_sdwa v175, v175 dst_sel:DWORD dst_unused:UNUSED_PAD src0_sel:WORD_1
	v_cvt_f32_f16_e32 v180, v172
	v_cvt_f32_f16_sdwa v181, v172 dst_sel:DWORD dst_unused:UNUSED_PAD src0_sel:WORD_1
	v_cvt_f32_f16_e32 v172, v173
	v_cvt_f32_f16_sdwa v173, v173 dst_sel:DWORD dst_unused:UNUSED_PAD src0_sel:WORD_1
	v_pk_fma_f32 v[48:49], v[48:49], v[72:73], v[164:165]
	v_pk_fma_f32 v[46:47], v[46:47], v[70:71], v[176:177]
	v_pk_fma_f32 v[44:45], v[44:45], v[68:69], v[166:167]
	v_pk_fma_f32 v[42:43], v[42:43], v[66:67], v[168:169]
	v_cvt_pk_f16_f32 v167, v44, v45
	v_cvt_pk_f16_f32 v165, v48, v49
	v_cvt_pk_f16_f32 v166, v42, v43
	v_cvt_pk_f16_f32 v164, v46, v47
	v_pk_fma_f32 v[40:41], v[40:41], v[72:73], v[172:173]
	v_pk_fma_f32 v[38:39], v[38:39], v[70:71], v[180:181]
	v_pk_fma_f32 v[36:37], v[36:37], v[68:69], v[174:175]
	v_pk_fma_f32 v[34:35], v[34:35], v[66:67], v[178:179]
	v_pk_mul_f32 v[168:169], v[130:131], v[48:49]
	v_pk_mul_f32 v[176:177], v[132:133], v[46:47]
	v_pk_mul_f32 v[178:179], v[134:135], v[44:45]
	v_pk_mul_f32 v[180:181], v[136:137], v[42:43]
	global_store_dwordx4 v[170:171], v[164:167], off offset:256
	v_cvt_pk_f16_f32 v175, v36, v37
	v_cvt_pk_f16_f32 v173, v40, v41
	v_cvt_pk_bf16_f32 v164, v176, v177
	v_cvt_pk_bf16_f32 v165, v168, v169
	v_cvt_pk_bf16_f32 v166, v180, v181
	v_cvt_pk_bf16_f32 v167, v178, v179
	v_cvt_pk_f16_f32 v174, v34, v35
	v_cvt_pk_f16_f32 v172, v38, v39
	v_pk_mul_f32 v[186:187], v[130:131], v[40:41]
	v_pk_mul_f32 v[188:189], v[132:133], v[38:39]
	v_pk_mul_f32 v[190:191], v[134:135], v[36:37]
	v_pk_mul_f32 v[216:217], v[136:137], v[34:35]
	global_store_dwordx4 v[192:193], v[164:167], off offset:256
	global_store_dwordx4 v[184:185], v[172:175], off offset:256
	s_nop 0
	v_cvt_pk_bf16_f32 v164, v188, v189
	v_cvt_pk_bf16_f32 v165, v186, v187
	v_cvt_pk_bf16_f32 v166, v216, v217
	v_cvt_pk_bf16_f32 v167, v190, v191
	global_store_dwordx4 v[196:197], v[164:167], off offset:256
	global_load_dwordx4 v[164:167], v[198:199], off offset:256 nt
	s_nop 0
	global_load_dwordx4 v[168:171], v[204:205], off offset:256 nt
	s_waitcnt vmcnt(1)
	v_cvt_f32_f16_e32 v172, v166
	v_cvt_f32_f16_sdwa v173, v166 dst_sel:DWORD dst_unused:UNUSED_PAD src0_sel:WORD_1
	v_cvt_f32_f16_e32 v166, v167
	v_cvt_f32_f16_sdwa v167, v167 dst_sel:DWORD dst_unused:UNUSED_PAD src0_sel:WORD_1
	v_cvt_f32_f16_e32 v174, v164
	v_cvt_f32_f16_sdwa v175, v164 dst_sel:DWORD dst_unused:UNUSED_PAD src0_sel:WORD_1
	v_cvt_f32_f16_e32 v164, v165
	v_cvt_f32_f16_sdwa v165, v165 dst_sel:DWORD dst_unused:UNUSED_PAD src0_sel:WORD_1
	s_waitcnt vmcnt(0)
	v_cvt_f32_f16_e32 v176, v170
	v_cvt_f32_f16_sdwa v177, v170 dst_sel:DWORD dst_unused:UNUSED_PAD src0_sel:WORD_1
	v_cvt_f32_f16_e32 v170, v171
	v_cvt_f32_f16_sdwa v171, v171 dst_sel:DWORD dst_unused:UNUSED_PAD src0_sel:WORD_1
	v_cvt_f32_f16_e32 v178, v168
	v_cvt_f32_f16_sdwa v179, v168 dst_sel:DWORD dst_unused:UNUSED_PAD src0_sel:WORD_1
	v_cvt_f32_f16_e32 v168, v169
	v_cvt_f32_f16_sdwa v169, v169 dst_sel:DWORD dst_unused:UNUSED_PAD src0_sel:WORD_1
	v_pk_fma_f32 v[32:33], v[32:33], v[72:73], v[164:165]
	v_pk_fma_f32 v[30:31], v[30:31], v[70:71], v[174:175]
	v_pk_fma_f32 v[28:29], v[28:29], v[68:69], v[166:167]
	v_pk_fma_f32 v[26:27], v[26:27], v[66:67], v[172:173]
	v_cvt_pk_f16_f32 v167, v28, v29
	v_cvt_pk_f16_f32 v165, v32, v33
	v_cvt_pk_f16_f32 v166, v26, v27
	v_cvt_pk_f16_f32 v164, v30, v31
	v_pk_fma_f32 v[24:25], v[24:25], v[72:73], v[168:169]
	v_pk_fma_f32 v[22:23], v[22:23], v[70:71], v[178:179]
	v_pk_fma_f32 v[20:21], v[20:21], v[68:69], v[170:171]
	v_pk_fma_f32 v[18:19], v[18:19], v[66:67], v[176:177]
	v_pk_mul_f32 v[172:173], v[130:131], v[32:33]
	v_pk_mul_f32 v[174:175], v[132:133], v[30:31]
	v_pk_mul_f32 v[176:177], v[134:135], v[28:29]
	v_pk_mul_f32 v[178:179], v[136:137], v[26:27]
	global_store_dwordx4 v[212:213], v[164:167], off offset:256
	v_cvt_pk_f16_f32 v171, v20, v21
	v_cvt_pk_f16_f32 v169, v24, v25
	v_cvt_pk_bf16_f32 v164, v174, v175
	v_cvt_pk_bf16_f32 v165, v172, v173
	v_cvt_pk_bf16_f32 v166, v178, v179
	v_cvt_pk_bf16_f32 v167, v176, v177
	v_cvt_pk_f16_f32 v170, v18, v19
	v_cvt_pk_f16_f32 v168, v22, v23
	v_pk_mul_f32 v[180:181], v[130:131], v[24:25]
	v_pk_mul_f32 v[184:185], v[132:133], v[22:23]
	v_pk_mul_f32 v[186:187], v[134:135], v[20:21]
	v_pk_mul_f32 v[188:189], v[136:137], v[18:19]
	global_store_dwordx4 v[214:215], v[164:167], off offset:256
	global_store_dwordx4 v[210:211], v[168:171], off offset:256
	s_nop 0
	v_cvt_pk_bf16_f32 v164, v184, v185
	v_cvt_pk_bf16_f32 v165, v180, v181
	v_cvt_pk_bf16_f32 v166, v188, v189
	v_cvt_pk_bf16_f32 v167, v186, v187
	global_store_dwordx4 v[208:209], v[164:167], off offset:256
	global_load_dwordx4 v[166:169], v[202:203], off offset:256 nt
	s_nop 0
	global_load_dwordx4 v[170:173], v[224:225], off offset:256 nt
	v_and_b32_e32 v165, 64, v231
	v_xor_b32_e32 v164, 16, v231
	v_add_u32_e32 v165, 64, v165
	v_cmp_lt_i32_e32 vcc, v164, v165
	s_waitcnt vmcnt(1)
	v_cvt_f32_f16_e32 v62, v168
	v_cndmask_b32_e32 v164, v231, v164, vcc
	v_lshlrev_b32_e32 v164, 2, v164
	ds_bpermute_b32 v60, v164, v59
	v_cmp_lt_i32_e32 vcc, v58, v165
	v_cvt_f32_f16_sdwa v63, v168 dst_sel:DWORD dst_unused:UNUSED_PAD src0_sel:WORD_1
	v_cvt_f32_f16_e32 v64, v169
	v_cndmask_b32_e32 v58, v231, v58, vcc
	v_cvt_f32_f16_sdwa v65, v169 dst_sel:DWORD dst_unused:UNUSED_PAD src0_sel:WORD_1
	v_cvt_f32_f16_e32 v122, v166
	v_cvt_f32_f16_sdwa v123, v166 dst_sel:DWORD dst_unused:UNUSED_PAD src0_sel:WORD_1
	v_cvt_f32_f16_e32 v124, v167
	v_cvt_f32_f16_sdwa v125, v167 dst_sel:DWORD dst_unused:UNUSED_PAD src0_sel:WORD_1
	v_lshlrev_b32_e32 v58, 2, v58
	s_waitcnt lgkmcnt(0)
	v_add_f32_e32 v59, v59, v60
	ds_bpermute_b32 v60, v58, v59
	s_waitcnt vmcnt(0)
	v_cvt_f32_f16_e32 v126, v172
	v_cvt_f32_f16_sdwa v127, v172 dst_sel:DWORD dst_unused:UNUSED_PAD src0_sel:WORD_1
	v_cvt_f32_f16_e32 v128, v173
	v_cvt_f32_f16_sdwa v129, v173 dst_sel:DWORD dst_unused:UNUSED_PAD src0_sel:WORD_1
	v_cvt_f32_f16_e32 v166, v170
	v_cvt_f32_f16_sdwa v167, v170 dst_sel:DWORD dst_unused:UNUSED_PAD src0_sel:WORD_1
	v_cvt_f32_f16_e32 v168, v171
	v_cvt_f32_f16_sdwa v169, v171 dst_sel:DWORD dst_unused:UNUSED_PAD src0_sel:WORD_1
	v_pk_fma_f32 v[16:17], v[16:17], v[72:73], v[124:125]
	v_pk_fma_f32 v[14:15], v[14:15], v[70:71], v[122:123]
	v_pk_fma_f32 v[12:13], v[12:13], v[68:69], v[64:65]
	v_pk_fma_f32 v[10:11], v[10:11], v[66:67], v[62:63]
	v_cvt_pk_f16_f32 v65, v12, v13
	v_cvt_pk_f16_f32 v63, v16, v17
	v_cvt_pk_f16_f32 v64, v10, v11
	v_cvt_pk_f16_f32 v62, v14, v15
	v_pk_fma_f32 v[8:9], v[8:9], v[72:73], v[168:169]
	v_pk_fma_f32 v[6:7], v[6:7], v[70:71], v[166:167]
	v_pk_fma_f32 v[4:5], v[4:5], v[68:69], v[128:129]
	v_pk_fma_f32 v[2:3], v[2:3], v[66:67], v[126:127]
	v_pk_mul_f32 v[70:71], v[130:131], v[16:17]
	v_pk_mul_f32 v[72:73], v[132:133], v[14:15]
	v_pk_mul_f32 v[122:123], v[134:135], v[12:13]
	v_pk_mul_f32 v[124:125], v[136:137], v[10:11]
	global_store_dwordx4 v[182:183], v[62:65], off offset:256
	v_cvt_pk_f16_f32 v69, v4, v5
	v_cvt_pk_f16_f32 v67, v8, v9
	v_cvt_pk_bf16_f32 v62, v72, v73
	v_cvt_pk_bf16_f32 v63, v70, v71
	v_cvt_pk_bf16_f32 v64, v124, v125
	v_cvt_pk_bf16_f32 v65, v122, v123
	v_cvt_pk_f16_f32 v68, v2, v3
	v_cvt_pk_f16_f32 v66, v6, v7
	v_pk_mul_f32 v[126:127], v[130:131], v[8:9]
	v_pk_mul_f32 v[128:129], v[132:133], v[6:7]
	v_pk_mul_f32 v[130:131], v[134:135], v[4:5]
	v_pk_mul_f32 v[132:133], v[136:137], v[2:3]
	global_store_dwordx4 v[206:207], v[62:65], off offset:256
	global_store_dwordx4 v[194:195], v[66:69], off offset:256
	s_nop 0
	v_cvt_pk_bf16_f32 v62, v128, v129
	v_cvt_pk_bf16_f32 v63, v126, v127
	v_cvt_pk_bf16_f32 v64, v132, v133
	v_cvt_pk_bf16_f32 v65, v130, v131
	global_store_dwordx4 v[200:201], v[62:65], off offset:256
	s_and_saveexec_b64 s[30:31], s[4:5]
	s_cbranch_execz .LBB0_1397
	v_lshl_add_u64 v[62:63], v[154:155], 2, s[10:11]
	s_waitcnt lgkmcnt(0)
	v_add_f32_e32 v59, v59, v60
	global_atomic_add_f32 v[62:63], v59, off

.LBB0_1479:
	ds_read_b128 v[98:101], v176
	ds_read_b128 v[102:105], v176 offset:1024
	ds_read_b128 v[106:109], v176 offset:2048
	ds_read_b128 v[110:113], v176 offset:3072
	ds_read_b128 v[182:185], v177
	ds_read_b128 v[186:189], v177 offset:1024
	ds_read_b128 v[190:193], v177 offset:2048
	ds_read_b128 v[194:197], v177 offset:3072
	s_add_u32 s13, s0, 0xfffc0080
	s_addc_u32 s44, s1, -1
	s_cmp_eq_u32 s12, 12
	s_cselect_b32 s47, s31, s44
	s_cselect_b32 s46, s43, s13
	s_cselect_b32 s45, s29, s69
	s_cselect_b32 s44, s67, s68
	s_add_i32 m0, s52, 0xc000
	ds_read_b128 v[198:201], v178
	ds_read_b128 v[202:205], v178 offset:1024
	ds_read_b128 v[206:209], v178 offset:2048
	ds_read_b128 v[210:213], v178 offset:3072
	ds_read_b128 v[214:217], v178 offset:4096
	ds_read_b128 v[218:221], v178 offset:5120
	ds_read_b128 v[222:225], v178 offset:6144
	ds_read_b128 v[226:229], v178 offset:7168
	global_load_lds_dwordx4 v158, s[0:1]
	s_add_i32 m0, s52, 0xe000
	s_nop 0
	global_load_lds_dwordx4 v160, s[0:1]
	s_waitcnt vmcnt(8)
	s_waitcnt lgkmcnt(0)
	s_barrier
	s_setprio 1
	s_waitcnt lgkmcnt(0)
	v_mfma_f32_16x16x32_bf16 v[142:145], v[98:101], v[198:201], v[142:145]
	v_mfma_f32_16x16x32_bf16 v[138:141], v[106:109], v[198:201], v[138:141]
	v_mfma_f32_16x16x32_bf16 v[126:129], v[98:101], v[206:209], v[126:129]
	v_mfma_f32_16x16x32_bf16 v[122:125], v[106:109], v[206:209], v[122:125]
	v_mfma_f32_16x16x32_bf16 v[94:97], v[98:101], v[214:217], v[94:97]
	v_mfma_f32_16x16x32_bf16 v[90:93], v[106:109], v[214:217], v[90:93]
	v_mfma_f32_16x16x32_bf16 v[78:81], v[98:101], v[222:225], v[78:81]
	v_mfma_f32_16x16x32_bf16 v[74:77], v[106:109], v[222:225], v[74:77]
	v_mfma_f32_16x16x32_bf16 v[142:145], v[102:105], v[202:205], v[142:145]
	v_mfma_f32_16x16x32_bf16 v[138:141], v[110:113], v[202:205], v[138:141]
	v_mfma_f32_16x16x32_bf16 v[126:129], v[102:105], v[210:213], v[126:129]
	v_mfma_f32_16x16x32_bf16 v[122:125], v[110:113], v[210:213], v[122:125]
	v_mfma_f32_16x16x32_bf16 v[94:97], v[102:105], v[218:221], v[94:97]
	v_mfma_f32_16x16x32_bf16 v[90:93], v[110:113], v[218:221], v[90:93]
	v_mfma_f32_16x16x32_bf16 v[78:81], v[102:105], v[226:229], v[78:81]
	v_mfma_f32_16x16x32_bf16 v[74:77], v[110:113], v[226:229], v[74:77]
	s_setprio 0
	s_setprio 1
	v_mfma_f32_16x16x32_bf16 v[134:137], v[182:185], v[198:201], v[134:137]
	v_mfma_f32_16x16x32_bf16 v[130:133], v[190:193], v[198:201], v[130:133]
	v_mfma_f32_16x16x32_bf16 v[118:121], v[182:185], v[206:209], v[118:121]
	v_mfma_f32_16x16x32_bf16 v[114:117], v[190:193], v[206:209], v[114:117]
	v_mfma_f32_16x16x32_bf16 v[86:89], v[182:185], v[214:217], v[86:89]
	v_mfma_f32_16x16x32_bf16 v[82:85], v[190:193], v[214:217], v[82:85]
	v_mfma_f32_16x16x32_bf16 v[70:73], v[182:185], v[222:225], v[70:73]
	v_mfma_f32_16x16x32_bf16 v[66:69], v[190:193], v[222:225], v[66:69]
	v_mfma_f32_16x16x32_bf16 v[134:137], v[186:189], v[202:205], v[134:137]
	v_mfma_f32_16x16x32_bf16 v[130:133], v[194:197], v[202:205], v[130:133]
	v_mfma_f32_16x16x32_bf16 v[118:121], v[186:189], v[210:213], v[118:121]
	v_mfma_f32_16x16x32_bf16 v[114:117], v[194:197], v[210:213], v[114:117]
	v_mfma_f32_16x16x32_bf16 v[86:89], v[186:189], v[218:221], v[86:89]
	v_mfma_f32_16x16x32_bf16 v[82:85], v[194:197], v[218:221], v[82:85]
	v_mfma_f32_16x16x32_bf16 v[70:73], v[186:189], v[226:229], v[70:73]
	v_mfma_f32_16x16x32_bf16 v[66:69], v[194:197], v[226:229], v[66:69]
	s_setprio 0
	s_barrier
	s_add_i32 s13, s61, s49
	s_mov_b32 m0, s13
	ds_read_b128 v[198:201], v178 offset:16384
	ds_read_b128 v[202:205], v178 offset:17408
	ds_read_b128 v[206:209], v178 offset:18432
	ds_read_b128 v[210:213], v178 offset:19456
	ds_read_b128 v[214:217], v178 offset:20480
	ds_read_b128 v[218:221], v178 offset:21504
	ds_read_b128 v[222:225], v178 offset:22528
	ds_read_b128 v[226:229], v178 offset:23552
	global_load_lds_dwordx4 v152, s[44:45]
	s_add_i32 m0, s13, 0x2000
	s_add_u32 s70, s44, 0x40000
	v_lshl_add_u64 v[232:233], s[44:45], 0, v[148:149]
	s_addc_u32 s71, s45, 0
	s_add_i32 s13, s62, s49
	global_load_lds_dwordx4 v148, s[44:45]
	s_mov_b32 m0, s13
	v_lshl_add_u64 v[236:237], s[46:47], 0, v[150:151]
	global_load_lds_dwordx4 v152, s[70:71]
	s_add_i32 m0, s13, 0x2000
	s_nop 0
	global_load_lds_dwordx4 v148, s[70:71]
	v_lshl_add_u64 v[234:235], s[46:47], 0, v[154:155]
	s_mov_b32 m0, s52
	s_nop 0
	global_load_lds_dwordx4 v154, s[46:47]
	s_mov_b32 m0, s53
	s_nop 0
	global_load_lds_dwordx4 v150, s[46:47]
	s_waitcnt vmcnt(8)
	s_waitcnt lgkmcnt(0)
	s_barrier
	s_setprio 1
	s_waitcnt lgkmcnt(0)
	v_mfma_f32_16x16x32_bf16 v[62:65], v[98:101], v[198:201], v[62:65]
	v_mfma_f32_16x16x32_bf16 v[58:61], v[106:109], v[198:201], v[58:61]
	v_mfma_f32_16x16x32_bf16 v[46:49], v[98:101], v[206:209], v[46:49]
	v_mfma_f32_16x16x32_bf16 v[42:45], v[106:109], v[206:209], v[42:45]
	v_mfma_f32_16x16x32_bf16 v[30:33], v[98:101], v[214:217], v[30:33]
	v_mfma_f32_16x16x32_bf16 v[26:29], v[106:109], v[214:217], v[26:29]
	v_mfma_f32_16x16x32_bf16 v[14:17], v[98:101], v[222:225], v[14:17]
	v_mfma_f32_16x16x32_bf16 v[10:13], v[106:109], v[222:225], v[10:13]
	v_mfma_f32_16x16x32_bf16 v[62:65], v[102:105], v[202:205], v[62:65]
	v_mfma_f32_16x16x32_bf16 v[58:61], v[110:113], v[202:205], v[58:61]
	v_mfma_f32_16x16x32_bf16 v[46:49], v[102:105], v[210:213], v[46:49]
	v_mfma_f32_16x16x32_bf16 v[42:45], v[110:113], v[210:213], v[42:45]
	v_mfma_f32_16x16x32_bf16 v[30:33], v[102:105], v[218:221], v[30:33]
	v_mfma_f32_16x16x32_bf16 v[26:29], v[110:113], v[218:221], v[26:29]
	v_mfma_f32_16x16x32_bf16 v[14:17], v[102:105], v[226:229], v[14:17]
	v_mfma_f32_16x16x32_bf16 v[10:13], v[110:113], v[226:229], v[10:13]
	s_setprio 0
	s_setprio 1
	v_mfma_f32_16x16x32_bf16 v[54:57], v[182:185], v[198:201], v[54:57]
	v_mfma_f32_16x16x32_bf16 v[50:53], v[190:193], v[198:201], v[50:53]
	v_mfma_f32_16x16x32_bf16 v[38:41], v[182:185], v[206:209], v[38:41]
	v_mfma_f32_16x16x32_bf16 v[34:37], v[190:193], v[206:209], v[34:37]
	v_mfma_f32_16x16x32_bf16 v[22:25], v[182:185], v[214:217], v[22:25]
	v_mfma_f32_16x16x32_bf16 v[18:21], v[190:193], v[214:217], v[18:21]
	v_mfma_f32_16x16x32_bf16 v[6:9], v[182:185], v[222:225], v[6:9]
	v_mfma_f32_16x16x32_bf16 v[2:5], v[190:193], v[222:225], v[2:5]
	v_mfma_f32_16x16x32_bf16 v[54:57], v[186:189], v[202:205], v[54:57]
	v_mfma_f32_16x16x32_bf16 v[50:53], v[194:197], v[202:205], v[50:53]
	v_mfma_f32_16x16x32_bf16 v[38:41], v[186:189], v[210:213], v[38:41]
	v_mfma_f32_16x16x32_bf16 v[34:37], v[194:197], v[210:213], v[34:37]
	v_mfma_f32_16x16x32_bf16 v[22:25], v[186:189], v[218:221], v[22:25]
	v_mfma_f32_16x16x32_bf16 v[18:21], v[194:197], v[218:221], v[18:21]
	v_mfma_f32_16x16x32_bf16 v[6:9], v[186:189], v[226:229], v[6:9]
	v_mfma_f32_16x16x32_bf16 v[2:5], v[194:197], v[226:229], v[2:5]
	s_setprio 0
	s_barrier
	s_add_i32 s13, 0, 0x18000
	s_add_i32 s70, 0, 0x1c000
	v_add_u32_e32 v110, s13, v167
	v_add_u32_e32 v181, s70, v167
	ds_read_b128 v[98:101], v110
	ds_read_b128 v[102:105], v110 offset:1024
	ds_read_b128 v[106:109], v110 offset:2048
	ds_read_b128 v[110:113], v110 offset:3072
	ds_read_b128 v[182:185], v181
	ds_read_b128 v[186:189], v181 offset:1024
	ds_read_b128 v[190:193], v181 offset:2048
	ds_read_b128 v[194:197], v181 offset:3072
	s_add_u32 s46, s46, 0x40000
	s_addc_u32 s47, s47, 0
	s_mov_b32 m0, s54
	ds_read_b128 v[198:201], v178 offset:32768
	ds_read_b128 v[202:205], v178 offset:33792
	ds_read_b128 v[206:209], v178 offset:34816
	ds_read_b128 v[210:213], v178 offset:35840
	ds_read_b128 v[214:217], v178 offset:36864
	ds_read_b128 v[218:221], v178 offset:37888
	ds_read_b128 v[222:225], v178 offset:38912
	ds_read_b128 v[226:229], v178 offset:39936
	global_load_lds_dwordx4 v154, s[46:47]
	s_mov_b32 m0, s55
	s_nop 0
	global_load_lds_dwordx4 v150, s[46:47]
	s_waitcnt vmcnt(8)
	s_waitcnt lgkmcnt(0)
	s_barrier
	s_setprio 1
	s_waitcnt lgkmcnt(0)
	v_mfma_f32_16x16x32_bf16 v[142:145], v[98:101], v[198:201], v[142:145]
	v_mfma_f32_16x16x32_bf16 v[138:141], v[106:109], v[198:201], v[138:141]
	v_mfma_f32_16x16x32_bf16 v[126:129], v[98:101], v[206:209], v[126:129]
	v_mfma_f32_16x16x32_bf16 v[122:125], v[106:109], v[206:209], v[122:125]
	v_mfma_f32_16x16x32_bf16 v[94:97], v[98:101], v[214:217], v[94:97]
	v_mfma_f32_16x16x32_bf16 v[90:93], v[106:109], v[214:217], v[90:93]
	v_mfma_f32_16x16x32_bf16 v[78:81], v[98:101], v[222:225], v[78:81]
	v_mfma_f32_16x16x32_bf16 v[74:77], v[106:109], v[222:225], v[74:77]
	v_mfma_f32_16x16x32_bf16 v[142:145], v[102:105], v[202:205], v[142:145]
	v_mfma_f32_16x16x32_bf16 v[138:141], v[110:113], v[202:205], v[138:141]
	v_mfma_f32_16x16x32_bf16 v[126:129], v[102:105], v[210:213], v[126:129]
	v_mfma_f32_16x16x32_bf16 v[122:125], v[110:113], v[210:213], v[122:125]
	v_mfma_f32_16x16x32_bf16 v[94:97], v[102:105], v[218:221], v[94:97]
	v_mfma_f32_16x16x32_bf16 v[90:93], v[110:113], v[218:221], v[90:93]
	v_mfma_f32_16x16x32_bf16 v[78:81], v[102:105], v[226:229], v[78:81]
	v_mfma_f32_16x16x32_bf16 v[74:77], v[110:113], v[226:229], v[74:77]
	s_setprio 0
	s_setprio 1
	v_mfma_f32_16x16x32_bf16 v[134:137], v[182:185], v[198:201], v[134:137]
	v_mfma_f32_16x16x32_bf16 v[130:133], v[190:193], v[198:201], v[130:133]
	v_mfma_f32_16x16x32_bf16 v[118:121], v[182:185], v[206:209], v[118:121]
	v_mfma_f32_16x16x32_bf16 v[114:117], v[190:193], v[206:209], v[114:117]
	v_mfma_f32_16x16x32_bf16 v[86:89], v[182:185], v[214:217], v[86:89]
	v_mfma_f32_16x16x32_bf16 v[82:85], v[190:193], v[214:217], v[82:85]
	v_mfma_f32_16x16x32_bf16 v[70:73], v[182:185], v[222:225], v[70:73]
	v_mfma_f32_16x16x32_bf16 v[66:69], v[190:193], v[222:225], v[66:69]
	v_mfma_f32_16x16x32_bf16 v[134:137], v[186:189], v[202:205], v[134:137]
	v_mfma_f32_16x16x32_bf16 v[130:133], v[194:197], v[202:205], v[130:133]
	v_mfma_f32_16x16x32_bf16 v[118:121], v[186:189], v[210:213], v[118:121]
	v_mfma_f32_16x16x32_bf16 v[114:117], v[194:197], v[210:213], v[114:117]
	v_mfma_f32_16x16x32_bf16 v[86:89], v[186:189], v[218:221], v[86:89]
	v_mfma_f32_16x16x32_bf16 v[82:85], v[194:197], v[218:221], v[82:85]
	v_mfma_f32_16x16x32_bf16 v[70:73], v[186:189], v[226:229], v[70:73]
	v_mfma_f32_16x16x32_bf16 v[66:69], v[194:197], v[226:229], v[66:69]
	s_setprio 0
	s_barrier
	s_add_i32 s13, s13, s49
	s_mov_b32 m0, s13
	ds_read_b128 v[198:201], v178 offset:49152
	ds_read_b128 v[202:205], v178 offset:50176
	ds_read_b128 v[206:209], v178 offset:51200
	ds_read_b128 v[210:213], v178 offset:52224
	ds_read_b128 v[214:217], v178 offset:53248
	ds_read_b128 v[218:221], v178 offset:54272
	ds_read_b128 v[222:225], v178 offset:55296
	ds_read_b128 v[226:229], v178 offset:56320
	global_load_lds_dwordx4 v251, s[44:45]
	s_add_i32 m0, s13, 0x2000
	s_add_u32 s44, s44, 0x40080
	v_lshl_add_u64 v[230:231], v[232:233], 0, s[20:21]
	s_addc_u32 s45, s45, 0
	s_add_i32 s13, s70, s49
	global_load_lds_dwordx4 v[230:231], off
	s_mov_b32 m0, s13
	s_nop 0
	global_load_lds_dwordx4 v152, s[44:45]
	s_add_i32 m0, s13, 0x2000
	s_nop 0
	global_load_lds_dwordx4 v148, s[44:45]
	v_lshl_add_u64 v[230:231], v[234:235], 0, s[20:21]
	s_mov_b32 m0, s58
	s_nop 0
	global_load_lds_dwordx4 v[230:231], off
	v_lshl_add_u64 v[230:231], v[236:237], 0, s[20:21]
	s_mov_b32 m0, s59
	s_nop 0
	global_load_lds_dwordx4 v[230:231], off
	s_waitcnt vmcnt(8)
	s_waitcnt lgkmcnt(0)
	s_barrier
	s_setprio 1
	s_waitcnt lgkmcnt(0)
	v_mfma_f32_16x16x32_bf16 v[62:65], v[98:101], v[198:201], v[62:65]
	v_mfma_f32_16x16x32_bf16 v[58:61], v[106:109], v[198:201], v[58:61]
	v_mfma_f32_16x16x32_bf16 v[46:49], v[98:101], v[206:209], v[46:49]
	v_mfma_f32_16x16x32_bf16 v[42:45], v[106:109], v[206:209], v[42:45]
	v_mfma_f32_16x16x32_bf16 v[30:33], v[98:101], v[214:217], v[30:33]
	v_mfma_f32_16x16x32_bf16 v[26:29], v[106:109], v[214:217], v[26:29]
	v_mfma_f32_16x16x32_bf16 v[14:17], v[98:101], v[222:225], v[14:17]
	v_mfma_f32_16x16x32_bf16 v[10:13], v[106:109], v[222:225], v[10:13]
	v_mfma_f32_16x16x32_bf16 v[62:65], v[102:105], v[202:205], v[62:65]
	v_mfma_f32_16x16x32_bf16 v[58:61], v[110:113], v[202:205], v[58:61]
	v_mfma_f32_16x16x32_bf16 v[46:49], v[102:105], v[210:213], v[46:49]
	v_mfma_f32_16x16x32_bf16 v[42:45], v[110:113], v[210:213], v[42:45]
	v_mfma_f32_16x16x32_bf16 v[30:33], v[102:105], v[218:221], v[30:33]
	v_mfma_f32_16x16x32_bf16 v[26:29], v[110:113], v[218:221], v[26:29]
	v_mfma_f32_16x16x32_bf16 v[14:17], v[102:105], v[226:229], v[14:17]
	v_mfma_f32_16x16x32_bf16 v[10:13], v[110:113], v[226:229], v[10:13]
	s_setprio 0
	s_setprio 1
	v_mfma_f32_16x16x32_bf16 v[54:57], v[182:185], v[198:201], v[54:57]
	v_mfma_f32_16x16x32_bf16 v[50:53], v[190:193], v[198:201], v[50:53]
	v_mfma_f32_16x16x32_bf16 v[38:41], v[182:185], v[206:209], v[38:41]
	v_mfma_f32_16x16x32_bf16 v[34:37], v[190:193], v[206:209], v[34:37]
	v_mfma_f32_16x16x32_bf16 v[22:25], v[182:185], v[214:217], v[22:25]
	v_mfma_f32_16x16x32_bf16 v[18:21], v[190:193], v[214:217], v[18:21]
	v_mfma_f32_16x16x32_bf16 v[6:9], v[182:185], v[222:225], v[6:9]
	v_mfma_f32_16x16x32_bf16 v[2:5], v[190:193], v[222:225], v[2:5]
	v_mfma_f32_16x16x32_bf16 v[54:57], v[186:189], v[202:205], v[54:57]
	v_mfma_f32_16x16x32_bf16 v[50:53], v[194:197], v[202:205], v[50:53]
	v_mfma_f32_16x16x32_bf16 v[38:41], v[186:189], v[210:213], v[38:41]
	v_mfma_f32_16x16x32_bf16 v[34:37], v[194:197], v[210:213], v[34:37]
	v_mfma_f32_16x16x32_bf16 v[22:25], v[186:189], v[218:221], v[22:25]
	v_mfma_f32_16x16x32_bf16 v[18:21], v[194:197], v[218:221], v[18:21]
	v_mfma_f32_16x16x32_bf16 v[6:9], v[186:189], v[226:229], v[6:9]
	v_mfma_f32_16x16x32_bf16 v[2:5], v[194:197], v[226:229], v[2:5]
	s_setprio 0
	s_barrier
	s_add_i32 s12, s12, 2
	s_add_u32 s0, s0, 0x100
	s_addc_u32 s1, s1, 0
	s_add_u32 s68, s68, 0x100
	s_addc_u32 s69, s69, 0
	s_cmp_gt_u32 s12, 13
	s_cbranch_scc0 .LBB0_1479
	s_and_b64 vcc, exec, s[24:25]
	s_cbranch_vccz .LBB0_1482
	s_barrier

.LBB0_1561:
	ds_read_b128 v[130:133], v228
	ds_read_b128 v[134:137], v228 offset:1024
	ds_read_b128 v[154:157], v228 offset:2048
	ds_read_b128 v[158:161], v228 offset:3072
	ds_read_b128 v[162:165], v229
	ds_read_b128 v[166:169], v229 offset:1024
	ds_read_b128 v[170:173], v229 offset:2048
	ds_read_b128 v[174:177], v229 offset:3072
	s_add_u32 s30, s28, 0x100
	s_addc_u32 s31, s29, 0
	s_cmp_eq_u32 s12, 40
	s_cselect_b32 s39, s1, s31
	s_cselect_b32 s38, s0, s30
	s_cselect_b32 s37, s9, s67
	s_cselect_b32 s36, s8, s27
	v_lshl_add_u64 v[210:211], s[28:29], 0, v[146:147]
	s_add_i32 m0, s41, 0xc000
	ds_read_b128 v[178:181], v230
	ds_read_b128 v[182:185], v230 offset:1024
	ds_read_b128 v[186:189], v230 offset:2048
	ds_read_b128 v[190:193], v230 offset:3072
	ds_read_b128 v[194:197], v230 offset:4096
	ds_read_b128 v[198:201], v230 offset:5120
	ds_read_b128 v[202:205], v230 offset:6144
	ds_read_b128 v[206:209], v230 offset:7168
	global_load_lds_dwordx4 v[210:211], off
	v_lshl_add_u64 v[210:211], s[28:29], 0, v[148:149]
	s_add_i32 m0, s41, 0xe000
	s_nop 0
	global_load_lds_dwordx4 v[210:211], off
	s_waitcnt vmcnt(8)
	s_waitcnt lgkmcnt(0)
	s_barrier
	s_setprio 1
	s_waitcnt lgkmcnt(0)
	v_mfma_f32_16x16x32_bf16 v[126:129], v[130:133], v[178:181], v[126:129]
	v_mfma_f32_16x16x32_bf16 v[122:125], v[154:157], v[178:181], v[122:125]
	v_mfma_f32_16x16x32_bf16 v[118:121], v[130:133], v[186:189], v[118:121]
	v_mfma_f32_16x16x32_bf16 v[114:117], v[154:157], v[186:189], v[114:117]
	v_mfma_f32_16x16x32_bf16 v[110:113], v[130:133], v[194:197], v[110:113]
	v_mfma_f32_16x16x32_bf16 v[106:109], v[154:157], v[194:197], v[106:109]
	v_mfma_f32_16x16x32_bf16 v[102:105], v[130:133], v[202:205], v[102:105]
	v_mfma_f32_16x16x32_bf16 v[98:101], v[154:157], v[202:205], v[98:101]
	v_mfma_f32_16x16x32_bf16 v[126:129], v[134:137], v[182:185], v[126:129]
	v_mfma_f32_16x16x32_bf16 v[122:125], v[158:161], v[182:185], v[122:125]
	v_mfma_f32_16x16x32_bf16 v[118:121], v[134:137], v[190:193], v[118:121]
	v_mfma_f32_16x16x32_bf16 v[114:117], v[158:161], v[190:193], v[114:117]
	v_mfma_f32_16x16x32_bf16 v[110:113], v[134:137], v[198:201], v[110:113]
	v_mfma_f32_16x16x32_bf16 v[106:109], v[158:161], v[198:201], v[106:109]
	v_mfma_f32_16x16x32_bf16 v[102:105], v[134:137], v[206:209], v[102:105]
	v_mfma_f32_16x16x32_bf16 v[98:101], v[158:161], v[206:209], v[98:101]
	s_setprio 0
	s_setprio 1
	v_mfma_f32_16x16x32_bf16 v[62:65], v[162:165], v[178:181], v[62:65]
	v_mfma_f32_16x16x32_bf16 v[58:61], v[170:173], v[178:181], v[58:61]
	v_mfma_f32_16x16x32_bf16 v[54:57], v[162:165], v[186:189], v[54:57]
	v_mfma_f32_16x16x32_bf16 v[50:53], v[170:173], v[186:189], v[50:53]
	v_mfma_f32_16x16x32_bf16 v[46:49], v[162:165], v[194:197], v[46:49]
	v_mfma_f32_16x16x32_bf16 v[42:45], v[170:173], v[194:197], v[42:45]
	v_mfma_f32_16x16x32_bf16 v[38:41], v[162:165], v[202:205], v[38:41]
	v_mfma_f32_16x16x32_bf16 v[34:37], v[170:173], v[202:205], v[34:37]
	v_mfma_f32_16x16x32_bf16 v[62:65], v[166:169], v[182:185], v[62:65]
	v_mfma_f32_16x16x32_bf16 v[58:61], v[174:177], v[182:185], v[58:61]
	v_mfma_f32_16x16x32_bf16 v[54:57], v[166:169], v[190:193], v[54:57]
	v_mfma_f32_16x16x32_bf16 v[50:53], v[174:177], v[190:193], v[50:53]
	v_mfma_f32_16x16x32_bf16 v[46:49], v[166:169], v[198:201], v[46:49]
	v_mfma_f32_16x16x32_bf16 v[42:45], v[174:177], v[198:201], v[42:45]
	v_mfma_f32_16x16x32_bf16 v[38:41], v[166:169], v[206:209], v[38:41]
	v_mfma_f32_16x16x32_bf16 v[34:37], v[174:177], v[206:209], v[34:37]
	s_setprio 0
	s_barrier
	s_add_i32 s13, s60, s40
	s_mov_b32 m0, s13
	ds_read_b128 v[178:181], v230 offset:16384
	ds_read_b128 v[182:185], v230 offset:17408
	ds_read_b128 v[186:189], v230 offset:18432
	ds_read_b128 v[190:193], v230 offset:19456
	ds_read_b128 v[194:197], v230 offset:20480
	ds_read_b128 v[198:201], v230 offset:21504
	ds_read_b128 v[202:205], v230 offset:22528
	ds_read_b128 v[206:209], v230 offset:23552
	global_load_lds_dwordx4 v140, s[36:37]
	s_add_i32 m0, s13, 0x2000
	s_add_u32 s28, s36, 0xb0000
	s_addc_u32 s29, s37, 0
	s_add_i32 s13, s61, s40
	global_load_lds_dwordx4 v144, s[36:37]
	s_mov_b32 m0, s13
	s_nop 0
	global_load_lds_dwordx4 v140, s[28:29]
	s_add_i32 m0, s13, 0x2000
	s_nop 0
	global_load_lds_dwordx4 v144, s[28:29]
	s_mov_b32 m0, s41
	s_nop 0
	global_load_lds_dwordx4 v138, s[38:39]
	s_mov_b32 m0, s42
	s_nop 0
	global_load_lds_dwordx4 v142, s[38:39]
	s_waitcnt vmcnt(8)
	s_waitcnt lgkmcnt(0)
	s_barrier
	s_setprio 1
	s_waitcnt lgkmcnt(0)
	v_mfma_f32_16x16x32_bf16 v[94:97], v[130:133], v[178:181], v[94:97]
	v_mfma_f32_16x16x32_bf16 v[90:93], v[154:157], v[178:181], v[90:93]
	v_mfma_f32_16x16x32_bf16 v[86:89], v[130:133], v[186:189], v[86:89]
	v_mfma_f32_16x16x32_bf16 v[82:85], v[154:157], v[186:189], v[82:85]
	v_mfma_f32_16x16x32_bf16 v[78:81], v[130:133], v[194:197], v[78:81]
	v_mfma_f32_16x16x32_bf16 v[74:77], v[154:157], v[194:197], v[74:77]
	v_mfma_f32_16x16x32_bf16 v[70:73], v[130:133], v[202:205], v[70:73]
	v_mfma_f32_16x16x32_bf16 v[66:69], v[154:157], v[202:205], v[66:69]
	v_mfma_f32_16x16x32_bf16 v[94:97], v[134:137], v[182:185], v[94:97]
	v_mfma_f32_16x16x32_bf16 v[90:93], v[158:161], v[182:185], v[90:93]
	v_mfma_f32_16x16x32_bf16 v[86:89], v[134:137], v[190:193], v[86:89]
	v_mfma_f32_16x16x32_bf16 v[82:85], v[158:161], v[190:193], v[82:85]
	v_mfma_f32_16x16x32_bf16 v[78:81], v[134:137], v[198:201], v[78:81]
	v_mfma_f32_16x16x32_bf16 v[74:77], v[158:161], v[198:201], v[74:77]
	v_mfma_f32_16x16x32_bf16 v[70:73], v[134:137], v[206:209], v[70:73]
	v_mfma_f32_16x16x32_bf16 v[66:69], v[158:161], v[206:209], v[66:69]
	s_setprio 0
	s_setprio 1
	v_mfma_f32_16x16x32_bf16 v[30:33], v[162:165], v[178:181], v[30:33]
	v_mfma_f32_16x16x32_bf16 v[26:29], v[170:173], v[178:181], v[26:29]
	v_mfma_f32_16x16x32_bf16 v[22:25], v[162:165], v[186:189], v[22:25]
	v_mfma_f32_16x16x32_bf16 v[18:21], v[170:173], v[186:189], v[18:21]
	v_mfma_f32_16x16x32_bf16 v[14:17], v[162:165], v[194:197], v[14:17]
	v_mfma_f32_16x16x32_bf16 v[10:13], v[170:173], v[194:197], v[10:13]
	v_mfma_f32_16x16x32_bf16 v[6:9], v[162:165], v[202:205], v[6:9]
	v_mfma_f32_16x16x32_bf16 v[2:5], v[170:173], v[202:205], v[2:5]
	v_mfma_f32_16x16x32_bf16 v[30:33], v[166:169], v[182:185], v[30:33]
	v_mfma_f32_16x16x32_bf16 v[26:29], v[174:177], v[182:185], v[26:29]
	v_mfma_f32_16x16x32_bf16 v[22:25], v[166:169], v[190:193], v[22:25]
	v_mfma_f32_16x16x32_bf16 v[18:21], v[174:177], v[190:193], v[18:21]
	v_mfma_f32_16x16x32_bf16 v[14:17], v[166:169], v[198:201], v[14:17]
	v_mfma_f32_16x16x32_bf16 v[10:13], v[174:177], v[198:201], v[10:13]
	v_mfma_f32_16x16x32_bf16 v[6:9], v[166:169], v[206:209], v[6:9]
	v_mfma_f32_16x16x32_bf16 v[2:5], v[174:177], v[206:209], v[2:5]
	s_setprio 0
	s_barrier
	s_add_i32 s13, 0, 0x18000
	s_add_i32 s68, 0, 0x1c000
	v_add_u32_e32 v158, s13, v226
	v_add_u32_e32 v174, s68, v226
	ds_read_b128 v[130:133], v158
	ds_read_b128 v[134:137], v158 offset:1024
	ds_read_b128 v[154:157], v158 offset:2048
	ds_read_b128 v[158:161], v158 offset:3072
	ds_read_b128 v[162:165], v174
	ds_read_b128 v[166:169], v174 offset:1024
	ds_read_b128 v[170:173], v174 offset:2048
	ds_read_b128 v[174:177], v174 offset:3072
	s_add_u32 s28, s38, 0xb0000
	s_addc_u32 s29, s39, 0
	s_mov_b32 m0, s43
	ds_read_b128 v[178:181], v230 offset:32768
	ds_read_b128 v[182:185], v230 offset:33792
	ds_read_b128 v[186:189], v230 offset:34816
	ds_read_b128 v[190:193], v230 offset:35840
	ds_read_b128 v[194:197], v230 offset:36864
	ds_read_b128 v[198:201], v230 offset:37888
	ds_read_b128 v[202:205], v230 offset:38912
	ds_read_b128 v[206:209], v230 offset:39936
	global_load_lds_dwordx4 v138, s[28:29]
	s_mov_b32 m0, s44
	s_nop 0
	global_load_lds_dwordx4 v142, s[28:29]
	s_waitcnt vmcnt(8)
	s_waitcnt lgkmcnt(0)
	s_barrier
	s_setprio 1
	s_waitcnt lgkmcnt(0)
	v_mfma_f32_16x16x32_bf16 v[126:129], v[130:133], v[178:181], v[126:129]
	v_mfma_f32_16x16x32_bf16 v[122:125], v[154:157], v[178:181], v[122:125]
	v_mfma_f32_16x16x32_bf16 v[118:121], v[130:133], v[186:189], v[118:121]
	v_mfma_f32_16x16x32_bf16 v[114:117], v[154:157], v[186:189], v[114:117]
	v_mfma_f32_16x16x32_bf16 v[110:113], v[130:133], v[194:197], v[110:113]
	v_mfma_f32_16x16x32_bf16 v[106:109], v[154:157], v[194:197], v[106:109]
	v_mfma_f32_16x16x32_bf16 v[102:105], v[130:133], v[202:205], v[102:105]
	v_mfma_f32_16x16x32_bf16 v[98:101], v[154:157], v[202:205], v[98:101]
	v_mfma_f32_16x16x32_bf16 v[126:129], v[134:137], v[182:185], v[126:129]
	v_mfma_f32_16x16x32_bf16 v[122:125], v[158:161], v[182:185], v[122:125]
	v_mfma_f32_16x16x32_bf16 v[118:121], v[134:137], v[190:193], v[118:121]
	v_mfma_f32_16x16x32_bf16 v[114:117], v[158:161], v[190:193], v[114:117]
	v_mfma_f32_16x16x32_bf16 v[110:113], v[134:137], v[198:201], v[110:113]
	v_mfma_f32_16x16x32_bf16 v[106:109], v[158:161], v[198:201], v[106:109]
	v_mfma_f32_16x16x32_bf16 v[102:105], v[134:137], v[206:209], v[102:105]
	v_mfma_f32_16x16x32_bf16 v[98:101], v[158:161], v[206:209], v[98:101]
	s_setprio 0
	s_setprio 1
	v_mfma_f32_16x16x32_bf16 v[62:65], v[162:165], v[178:181], v[62:65]
	v_mfma_f32_16x16x32_bf16 v[58:61], v[170:173], v[178:181], v[58:61]
	v_mfma_f32_16x16x32_bf16 v[54:57], v[162:165], v[186:189], v[54:57]
	v_mfma_f32_16x16x32_bf16 v[50:53], v[170:173], v[186:189], v[50:53]
	v_mfma_f32_16x16x32_bf16 v[46:49], v[162:165], v[194:197], v[46:49]
	v_mfma_f32_16x16x32_bf16 v[42:45], v[170:173], v[194:197], v[42:45]
	v_mfma_f32_16x16x32_bf16 v[38:41], v[162:165], v[202:205], v[38:41]
	v_mfma_f32_16x16x32_bf16 v[34:37], v[170:173], v[202:205], v[34:37]
	v_mfma_f32_16x16x32_bf16 v[62:65], v[166:169], v[182:185], v[62:65]
	v_mfma_f32_16x16x32_bf16 v[58:61], v[174:177], v[182:185], v[58:61]
	v_mfma_f32_16x16x32_bf16 v[54:57], v[166:169], v[190:193], v[54:57]
	v_mfma_f32_16x16x32_bf16 v[50:53], v[174:177], v[190:193], v[50:53]
	v_mfma_f32_16x16x32_bf16 v[46:49], v[166:169], v[198:201], v[46:49]
	v_mfma_f32_16x16x32_bf16 v[42:45], v[174:177], v[198:201], v[42:45]
	v_mfma_f32_16x16x32_bf16 v[38:41], v[166:169], v[206:209], v[38:41]
	v_mfma_f32_16x16x32_bf16 v[34:37], v[174:177], v[206:209], v[34:37]
	s_setprio 0
	s_barrier
	s_add_i32 s13, s13, s40
	s_mov_b32 m0, s13
	ds_read_b128 v[178:181], v230 offset:49152
	ds_read_b128 v[182:185], v230 offset:50176
	ds_read_b128 v[186:189], v230 offset:51200
	ds_read_b128 v[190:193], v230 offset:52224
	ds_read_b128 v[194:197], v230 offset:53248
	ds_read_b128 v[198:201], v230 offset:54272
	ds_read_b128 v[202:205], v230 offset:55296
	ds_read_b128 v[206:209], v230 offset:56320
	global_load_lds_dwordx4 v251, s[36:37]
	s_add_i32 m0, s13, 0x2000
	s_add_u32 s28, s36, 0xb0080
	s_addc_u32 s29, s37, 0
	s_add_i32 s13, s68, s40
	global_load_lds_dwordx4 v252, s[36:37]
	s_mov_b32 m0, s13
	s_nop 0
	global_load_lds_dwordx4 v140, s[28:29]
	s_add_i32 m0, s13, 0x2000
	s_nop 0
	global_load_lds_dwordx4 v144, s[28:29]
	s_mov_b32 m0, s57
	s_nop 0
	global_load_lds_dwordx4 v253, s[38:39]
	s_mov_b32 m0, s58
	s_nop 0
	global_load_lds_dwordx4 v254, s[38:39]
	s_waitcnt vmcnt(8)
	s_waitcnt lgkmcnt(0)
	s_barrier
	s_setprio 1
	s_waitcnt lgkmcnt(0)
	v_mfma_f32_16x16x32_bf16 v[94:97], v[130:133], v[178:181], v[94:97]
	v_mfma_f32_16x16x32_bf16 v[90:93], v[154:157], v[178:181], v[90:93]
	v_mfma_f32_16x16x32_bf16 v[86:89], v[130:133], v[186:189], v[86:89]
	v_mfma_f32_16x16x32_bf16 v[82:85], v[154:157], v[186:189], v[82:85]
	v_mfma_f32_16x16x32_bf16 v[78:81], v[130:133], v[194:197], v[78:81]
	v_mfma_f32_16x16x32_bf16 v[74:77], v[154:157], v[194:197], v[74:77]
	v_mfma_f32_16x16x32_bf16 v[70:73], v[130:133], v[202:205], v[70:73]
	v_mfma_f32_16x16x32_bf16 v[66:69], v[154:157], v[202:205], v[66:69]
	v_mfma_f32_16x16x32_bf16 v[94:97], v[134:137], v[182:185], v[94:97]
	v_mfma_f32_16x16x32_bf16 v[90:93], v[158:161], v[182:185], v[90:93]
	v_mfma_f32_16x16x32_bf16 v[86:89], v[134:137], v[190:193], v[86:89]
	v_mfma_f32_16x16x32_bf16 v[82:85], v[158:161], v[190:193], v[82:85]
	v_mfma_f32_16x16x32_bf16 v[78:81], v[134:137], v[198:201], v[78:81]
	v_mfma_f32_16x16x32_bf16 v[74:77], v[158:161], v[198:201], v[74:77]
	v_mfma_f32_16x16x32_bf16 v[70:73], v[134:137], v[206:209], v[70:73]
	v_mfma_f32_16x16x32_bf16 v[66:69], v[158:161], v[206:209], v[66:69]
	s_setprio 0
	s_setprio 1
	v_mfma_f32_16x16x32_bf16 v[30:33], v[162:165], v[178:181], v[30:33]
	v_mfma_f32_16x16x32_bf16 v[26:29], v[170:173], v[178:181], v[26:29]
	v_mfma_f32_16x16x32_bf16 v[22:25], v[162:165], v[186:189], v[22:25]
	v_mfma_f32_16x16x32_bf16 v[18:21], v[170:173], v[186:189], v[18:21]
	v_mfma_f32_16x16x32_bf16 v[14:17], v[162:165], v[194:197], v[14:17]
	v_mfma_f32_16x16x32_bf16 v[10:13], v[170:173], v[194:197], v[10:13]
	v_mfma_f32_16x16x32_bf16 v[6:9], v[162:165], v[202:205], v[6:9]
	v_mfma_f32_16x16x32_bf16 v[2:5], v[170:173], v[202:205], v[2:5]
	v_mfma_f32_16x16x32_bf16 v[30:33], v[166:169], v[182:185], v[30:33]
	v_mfma_f32_16x16x32_bf16 v[26:29], v[174:177], v[182:185], v[26:29]
	v_mfma_f32_16x16x32_bf16 v[22:25], v[166:169], v[190:193], v[22:25]
	v_mfma_f32_16x16x32_bf16 v[18:21], v[174:177], v[190:193], v[18:21]
	v_mfma_f32_16x16x32_bf16 v[14:17], v[166:169], v[198:201], v[14:17]
	v_mfma_f32_16x16x32_bf16 v[10:13], v[174:177], v[198:201], v[10:13]
	v_mfma_f32_16x16x32_bf16 v[6:9], v[166:169], v[206:209], v[6:9]
	v_mfma_f32_16x16x32_bf16 v[2:5], v[174:177], v[206:209], v[2:5]
	s_setprio 0
	s_barrier
	s_add_i32 s12, s12, 2
	s_add_u32 s27, s27, 0x100
	s_addc_u32 s67, s67, 0
	s_cmp_gt_u32 s12, 41
	s_mov_b64 s[28:29], s[30:31]
	s_cbranch_scc0 .LBB0_1561
	s_ashr_i32 s12, s26, 3
	s_ashr_i32 s27, s26, 31
	s_mul_i32 s37, s12, 0x6000
	s_mul_hi_i32 s36, s12, 0x6000
	s_add_u32 s12, s54, s37
	v_mov_b32_e32 v130, v1
	s_addc_u32 s13, s55, s36
	s_lshl_b64 s[28:29], s[26:27], 19
	v_lshl_or_b32 v166, s66, 8, v227
	s_add_u32 s30, s46, s28
	v_add_u32_e32 v160, s56, v130
	v_ashrrev_i32_e32 v167, 31, v166
	s_addc_u32 s31, s47, s29
	v_lshlrev_b64 v[156:157], 1, v[166:167]
	v_ashrrev_i32_e32 v161, 31, v160
	v_lshlrev_b64 v[130:131], 2, v[166:167]
	v_lshl_add_u64 v[162:163], s[30:31], 0, v[156:157]
	v_lshlrev_b64 v[154:155], 11, v[160:161]
	v_add_u32_e32 v170, 16, v160
	v_lshl_add_u64 v[172:173], s[12:13], 0, v[130:131]
	v_lshl_add_u64 v[174:175], v[162:163], 0, v[154:155]
	v_ashrrev_i32_e32 v171, 31, v170
	s_add_u32 s12, s48, s28
	v_lshl_add_u64 v[132:133], s[16:17], 0, v[130:131]
	global_load_dwordx4 v[180:183], v[172:173], off offset:16
	global_load_dwordx4 v[184:187], v[172:173], off
	global_load_dwordx4 v[188:191], v[132:133], off offset:16
	global_load_dwordx4 v[192:195], v[132:133], off
	global_load_dwordx4 v[196:199], v[174:175], off nt
	v_lshlrev_b64 v[204:205], 11, v[170:171]
	s_addc_u32 s13, s49, s29
	v_lshl_add_u64 v[178:179], v[162:163], 0, v[204:205]
	s_add_u32 s28, s50, s37
	global_load_dwordx4 v[200:203], v[178:179], off nt
	s_addc_u32 s29, s51, s36
	v_lshl_add_u64 v[176:177], s[28:29], 0, v[130:131]
	global_load_dwordx4 v[134:137], v[176:177], off
	global_load_dwordx4 v[130:133], v[176:177], off offset:16
	v_lshl_add_u64 v[158:159], s[12:13], 0, v[156:157]
	s_lshl_b32 s12, s26, 8
	v_lshl_add_u64 v[164:165], v[158:159], 0, v[154:155]
	v_add_u32_e32 v154, s12, v160
	v_ashrrev_i32_e32 v155, 31, v154
	v_lshlrev_b64 v[168:169], 11, v[154:155]
	v_lshl_add_u64 v[168:169], s[10:11], 0, v[168:169]
	v_add_u32_e32 v170, s12, v170
	v_lshl_add_u64 v[168:169], v[168:169], 0, v[156:157]
	v_ashrrev_i32_e32 v171, 31, v170
	v_lshlrev_b64 v[170:171], 11, v[170:171]
	v_lshl_add_u64 v[170:171], s[10:11], 0, v[170:171]
	s_waitcnt vmcnt(0)
	v_pk_add_f32 v[182:183], v[182:183], 1.0 op_sel_hi:[1,0]
	v_pk_add_f32 v[186:187], v[186:187], 1.0 op_sel_hi:[1,0]
	v_pk_add_f32 v[184:185], v[184:185], 1.0 op_sel_hi:[1,0]
	v_pk_add_f32 v[180:181], v[180:181], 1.0 op_sel_hi:[1,0]
	v_pk_mul_f32 v[216:217], v[194:195], v[186:187]
	v_pk_mul_f32 v[218:219], v[192:193], v[184:185]
	v_pk_mul_f32 v[220:221], v[190:191], v[182:183]
	v_pk_mul_f32 v[222:223], v[188:189], v[180:181]
	v_cvt_f32_f16_e32 v180, v198
	v_cvt_f32_f16_sdwa v181, v198 dst_sel:DWORD dst_unused:UNUSED_PAD src0_sel:WORD_1
	v_cvt_f32_f16_e32 v182, v199
	v_cvt_f32_f16_sdwa v183, v199 dst_sel:DWORD dst_unused:UNUSED_PAD src0_sel:WORD_1
	v_cvt_f32_f16_e32 v184, v196
	v_cvt_f32_f16_sdwa v185, v196 dst_sel:DWORD dst_unused:UNUSED_PAD src0_sel:WORD_1
	v_cvt_f32_f16_e32 v186, v197
	v_cvt_f32_f16_sdwa v187, v197 dst_sel:DWORD dst_unused:UNUSED_PAD src0_sel:WORD_1
	v_cvt_f32_f16_e32 v188, v202
	v_cvt_f32_f16_sdwa v189, v202 dst_sel:DWORD dst_unused:UNUSED_PAD src0_sel:WORD_1
	v_cvt_f32_f16_e32 v190, v203
	v_cvt_f32_f16_sdwa v191, v203 dst_sel:DWORD dst_unused:UNUSED_PAD src0_sel:WORD_1
	v_cvt_f32_f16_e32 v192, v200
	v_cvt_f32_f16_sdwa v193, v200 dst_sel:DWORD dst_unused:UNUSED_PAD src0_sel:WORD_1
	v_cvt_f32_f16_e32 v194, v201
	v_cvt_f32_f16_sdwa v195, v201 dst_sel:DWORD dst_unused:UNUSED_PAD src0_sel:WORD_1
	v_pk_fma_f32 v[128:129], v[128:129], v[136:137], v[186:187]
	v_pk_fma_f32 v[126:127], v[126:127], v[134:135], v[184:185]
	v_pk_fma_f32 v[124:125], v[124:125], v[132:133], v[182:183]
	v_pk_fma_f32 v[122:123], v[122:123], v[130:131], v[180:181]
	v_cvt_pk_f16_f32 v183, v124, v125
	v_cvt_pk_f16_f32 v181, v128, v129
	v_cvt_pk_f16_f32 v182, v122, v123
	v_cvt_pk_f16_f32 v180, v126, v127
	v_pk_fma_f32 v[120:121], v[120:121], v[136:137], v[194:195]
	v_pk_fma_f32 v[118:119], v[118:119], v[134:135], v[192:193]
	v_pk_fma_f32 v[116:117], v[116:117], v[132:133], v[190:191]
	v_pk_fma_f32 v[114:115], v[114:115], v[130:131], v[188:189]
	v_pk_mul_f32 v[188:189], v[216:217], v[128:129]
	v_pk_mul_f32 v[190:191], v[218:219], v[126:127]
	global_store_dwordx4 v[164:165], v[180:183], off
	v_pk_mul_f32 v[192:193], v[220:221], v[124:125]
	v_pk_mul_f32 v[194:195], v[222:223], v[122:123]
	v_cvt_pk_bf16_f32 v180, v190, v191
	v_cvt_pk_bf16_f32 v181, v188, v189
	v_cvt_pk_f16_f32 v187, v116, v117
	v_cvt_pk_f16_f32 v185, v120, v121
	v_cvt_pk_f16_f32 v186, v114, v115
	v_cvt_pk_bf16_f32 v182, v194, v195
	v_cvt_pk_bf16_f32 v183, v192, v193
	global_store_dwordx4 v[168:169], v[180:183], off
	v_cvt_pk_f16_f32 v184, v118, v119
	v_pk_mul_f32 v[188:189], v[222:223], v[114:115]
	v_lshl_add_u64 v[180:181], v[158:159], 0, v[204:205]
	global_store_dwordx4 v[180:181], v[184:187], off
	v_pk_mul_f32 v[182:183], v[218:219], v[118:119]
	v_add_u32_e32 v192, 48, v160
	v_pk_mul_f32 v[184:185], v[216:217], v[120:121]
	v_pk_mul_f32 v[186:187], v[220:221], v[116:117]
	v_cvt_pk_bf16_f32 v182, v182, v183
	v_cvt_pk_bf16_f32 v183, v184, v185
	v_cvt_pk_bf16_f32 v184, v188, v189
	v_ashrrev_i32_e32 v193, 31, v192
	v_cvt_pk_bf16_f32 v185, v186, v187
	v_lshl_add_u64 v[186:187], v[170:171], 0, v[156:157]
	global_store_dwordx4 v[186:187], v[182:185], off
	v_mul_f32_e32 v127, v127, v127
	v_mul_f32_e32 v129, v129, v129
	v_add_u32_e32 v182, 32, v160
	v_ashrrev_i32_e32 v183, 31, v182
	v_lshlrev_b64 v[170:171], 11, v[182:183]
	v_lshl_add_u64 v[188:189], v[162:163], 0, v[170:171]
	global_load_dwordx4 v[194:197], v[188:189], off nt
	v_lshlrev_b64 v[184:185], 11, v[192:193]
	v_lshl_add_u64 v[190:191], v[162:163], 0, v[184:185]
	global_load_dwordx4 v[198:201], v[190:191], off nt
	v_add_u32_e32 v182, s12, v182
	v_add_u32_e32 v192, s12, v192
	v_ashrrev_i32_e32 v183, 31, v182
	v_ashrrev_i32_e32 v193, 31, v192
	v_lshlrev_b64 v[182:183], 11, v[182:183]
	v_lshlrev_b64 v[192:193], 11, v[192:193]
	v_lshl_add_u64 v[182:183], s[10:11], 0, v[182:183]
	v_lshl_add_u64 v[202:203], s[10:11], 0, v[192:193]
	v_lshl_add_u64 v[192:193], v[182:183], 0, v[156:157]
	v_lshl_add_u64 v[170:171], v[158:159], 0, v[170:171]
	v_lshl_add_u64 v[184:185], v[158:159], 0, v[184:185]
	v_mul_f32_e32 v123, v123, v123
	v_mul_f32_e32 v125, v125, v125
	v_fmac_f32_e32 v127, v126, v126
	v_fmac_f32_e32 v129, v128, v128
	v_fmac_f32_e32 v123, v122, v122
	v_fmac_f32_e32 v125, v124, v124
	v_add_f32_e32 v122, v127, v129
	v_add_f32_e32 v123, v123, v125
	v_add_f32_e32 v122, v122, v123
	s_waitcnt vmcnt(1)
	v_cvt_f32_f16_e32 v182, v196
	v_cvt_f32_f16_sdwa v183, v196 dst_sel:DWORD dst_unused:UNUSED_PAD src0_sel:WORD_1
	v_cvt_f32_f16_e32 v196, v197
	v_cvt_f32_f16_sdwa v197, v197 dst_sel:DWORD dst_unused:UNUSED_PAD src0_sel:WORD_1
	v_cvt_f32_f16_e32 v204, v194
	v_cvt_f32_f16_sdwa v205, v194 dst_sel:DWORD dst_unused:UNUSED_PAD src0_sel:WORD_1
	v_cvt_f32_f16_e32 v194, v195
	v_cvt_f32_f16_sdwa v195, v195 dst_sel:DWORD dst_unused:UNUSED_PAD src0_sel:WORD_1
	s_waitcnt vmcnt(0)
	v_cvt_f32_f16_e32 v206, v200
	v_cvt_f32_f16_sdwa v207, v200 dst_sel:DWORD dst_unused:UNUSED_PAD src0_sel:WORD_1
	v_cvt_f32_f16_e32 v208, v198
	v_cvt_f32_f16_sdwa v209, v198 dst_sel:DWORD dst_unused:UNUSED_PAD src0_sel:WORD_1
	v_cvt_f32_f16_e32 v198, v199
	v_cvt_f32_f16_sdwa v199, v199 dst_sel:DWORD dst_unused:UNUSED_PAD src0_sel:WORD_1
	v_cvt_f32_f16_e32 v200, v201
	v_cvt_f32_f16_sdwa v201, v201 dst_sel:DWORD dst_unused:UNUSED_PAD src0_sel:WORD_1
	v_pk_fma_f32 v[112:113], v[112:113], v[136:137], v[194:195]
	v_pk_fma_f32 v[110:111], v[110:111], v[134:135], v[204:205]
	v_pk_fma_f32 v[108:109], v[108:109], v[132:133], v[196:197]
	v_pk_fma_f32 v[106:107], v[106:107], v[130:131], v[182:183]
	v_cvt_pk_f16_f32 v197, v108, v109
	v_cvt_pk_f16_f32 v195, v112, v113
	v_cvt_pk_f16_f32 v196, v106, v107
	v_cvt_pk_f16_f32 v194, v110, v111
	v_pk_mul_f32 v[182:183], v[216:217], v[112:113]
	v_pk_fma_f32 v[104:105], v[104:105], v[136:137], v[198:199]
	v_pk_fma_f32 v[102:103], v[102:103], v[134:135], v[208:209]
	v_pk_fma_f32 v[98:99], v[98:99], v[130:131], v[206:207]
	v_pk_mul_f32 v[204:205], v[218:219], v[110:111]
	v_pk_mul_f32 v[206:207], v[220:221], v[108:109]
	global_store_dwordx4 v[170:171], v[194:197], off
	v_pk_fma_f32 v[100:101], v[100:101], v[132:133], v[200:201]
	v_pk_mul_f32 v[208:209], v[222:223], v[106:107]
	v_cvt_pk_bf16_f32 v194, v204, v205
	v_cvt_pk_bf16_f32 v195, v182, v183
	v_add_u32_e32 v182, 0x80, v160
	v_cvt_pk_f16_f32 v199, v104, v105
	v_cvt_pk_f16_f32 v198, v102, v103
	v_cvt_pk_bf16_f32 v196, v208, v209
	v_cvt_pk_bf16_f32 v197, v206, v207
	v_ashrrev_i32_e32 v183, 31, v182
	v_add_u32_e32 v206, 0x90, v160
	v_cvt_pk_f16_f32 v201, v100, v101
	v_cvt_pk_f16_f32 v200, v98, v99
	v_pk_mul_f32 v[210:211], v[216:217], v[104:105]
	v_pk_mul_f32 v[212:213], v[218:219], v[102:103]
	global_store_dwordx4 v[192:193], v[194:197], off
	global_store_dwordx4 v[184:185], v[198:201], off
	v_ashrrev_i32_e32 v207, 31, v206
	v_lshl_add_u64 v[196:197], v[202:203], 0, v[156:157]
	v_cvt_pk_bf16_f32 v198, v212, v213
	v_cvt_pk_bf16_f32 v199, v210, v211
	v_lshlrev_b64 v[194:195], 11, v[182:183]
	v_pk_mul_f32 v[214:215], v[220:221], v[100:101]
	v_pk_mul_f32 v[224:225], v[222:223], v[98:99]
	v_lshlrev_b64 v[208:209], 11, v[206:207]
	v_cvt_pk_bf16_f32 v200, v224, v225
	v_cvt_pk_bf16_f32 v201, v214, v215
	global_store_dwordx4 v[196:197], v[198:201], off
	v_lshl_add_u64 v[204:205], v[162:163], 0, v[208:209]
	global_load_dwordx4 v[236:239], v[204:205], off nt
	v_lshl_add_u64 v[198:199], v[162:163], 0, v[194:195]
	global_load_dwordx4 v[232:235], v[198:199], off nt
	v_lshl_add_u64 v[212:213], v[158:159], 0, v[194:195]
	v_add_u32_e32 v182, s12, v182
	v_add_u32_e32 v194, s12, v206
	v_ashrrev_i32_e32 v183, 31, v182
	v_ashrrev_i32_e32 v195, 31, v194
	v_lshlrev_b64 v[182:183], 11, v[182:183]
	v_lshlrev_b64 v[194:195], 11, v[194:195]
	v_lshl_add_u64 v[182:183], s[10:11], 0, v[182:183]
	v_lshl_add_u64 v[194:195], s[10:11], 0, v[194:195]
	v_lshl_add_u64 v[210:211], v[158:159], 0, v[208:209]
	v_lshl_add_u64 v[214:215], v[182:183], 0, v[156:157]
	v_lshl_add_u64 v[208:209], v[194:195], 0, v[156:157]
	v_add_u32_e32 v200, 0xa0, v160
	v_ashrrev_i32_e32 v201, 31, v200
	v_lshlrev_b64 v[240:241], 11, v[200:201]
	v_lshl_add_u64 v[202:203], v[162:163], 0, v[240:241]
	s_waitcnt vmcnt(0)
	v_cvt_f32_f16_e32 v182, v234
	v_cvt_f32_f16_sdwa v183, v234 dst_sel:DWORD dst_unused:UNUSED_PAD src0_sel:WORD_1
	v_cvt_f32_f16_e32 v194, v235
	v_cvt_f32_f16_sdwa v195, v235 dst_sel:DWORD dst_unused:UNUSED_PAD src0_sel:WORD_1
	v_cvt_f32_f16_e32 v206, v232
	v_cvt_f32_f16_sdwa v207, v232 dst_sel:DWORD dst_unused:UNUSED_PAD src0_sel:WORD_1
	v_cvt_f32_f16_e32 v224, v233
	v_cvt_f32_f16_sdwa v225, v233 dst_sel:DWORD dst_unused:UNUSED_PAD src0_sel:WORD_1
	v_cvt_f32_f16_e32 v232, v238
	v_cvt_f32_f16_sdwa v233, v238 dst_sel:DWORD dst_unused:UNUSED_PAD src0_sel:WORD_1
	v_cvt_f32_f16_e32 v234, v239
	v_cvt_f32_f16_sdwa v235, v239 dst_sel:DWORD dst_unused:UNUSED_PAD src0_sel:WORD_1
	v_cvt_f32_f16_e32 v238, v236
	v_cvt_f32_f16_sdwa v239, v236 dst_sel:DWORD dst_unused:UNUSED_PAD src0_sel:WORD_1
	v_cvt_f32_f16_e32 v236, v237
	v_cvt_f32_f16_sdwa v237, v237 dst_sel:DWORD dst_unused:UNUSED_PAD src0_sel:WORD_1
	v_pk_fma_f32 v[96:97], v[96:97], v[136:137], v[224:225]
	v_pk_fma_f32 v[94:95], v[94:95], v[134:135], v[206:207]
	v_pk_fma_f32 v[92:93], v[92:93], v[132:133], v[194:195]
	v_pk_fma_f32 v[90:91], v[90:91], v[130:131], v[182:183]
	v_pk_fma_f32 v[84:85], v[84:85], v[132:133], v[234:235]
	v_pk_fma_f32 v[82:83], v[82:83], v[130:131], v[232:233]
	v_cvt_pk_f16_f32 v235, v92, v93
	v_cvt_pk_f16_f32 v233, v96, v97
	v_cvt_pk_f16_f32 v234, v90, v91
	v_cvt_pk_f16_f32 v232, v94, v95
	v_pk_mul_f32 v[206:207], v[220:221], v[92:93]
	v_pk_mul_f32 v[182:183], v[216:217], v[96:97]
	v_pk_mul_f32 v[194:195], v[218:219], v[94:95]
	v_pk_mul_f32 v[224:225], v[222:223], v[90:91]
	global_store_dwordx4 v[212:213], v[232:235], off
	v_pk_fma_f32 v[88:89], v[88:89], v[136:137], v[236:237]
	v_pk_fma_f32 v[86:87], v[86:87], v[134:135], v[238:239]
	v_cvt_pk_bf16_f32 v232, v194, v195
	v_cvt_pk_bf16_f32 v233, v182, v183
	v_cvt_pk_bf16_f32 v234, v224, v225
	v_cvt_pk_bf16_f32 v235, v206, v207
	v_add_u32_e32 v206, 0xb0, v160
	v_ashrrev_i32_e32 v207, 31, v206
	v_cvt_pk_f16_f32 v239, v84, v85
	v_cvt_pk_f16_f32 v237, v88, v89
	v_cvt_pk_f16_f32 v238, v82, v83
	v_cvt_pk_f16_f32 v236, v86, v87
	v_pk_mul_f32 v[242:243], v[216:217], v[88:89]
	v_pk_mul_f32 v[244:245], v[218:219], v[86:87]
	v_pk_mul_f32 v[246:247], v[220:221], v[84:85]
	v_pk_mul_f32 v[248:249], v[222:223], v[82:83]
	global_store_dwordx4 v[214:215], v[232:235], off
	global_store_dwordx4 v[210:211], v[236:239], off
	v_lshlrev_b64 v[194:195], 11, v[206:207]
	v_cvt_pk_bf16_f32 v232, v244, v245
	v_cvt_pk_bf16_f32 v233, v242, v243
	v_cvt_pk_bf16_f32 v234, v248, v249
	v_cvt_pk_bf16_f32 v235, v246, v247
	global_store_dwordx4 v[208:209], v[232:235], off
	global_load_dwordx4 v[232:235], v[202:203], off nt
	v_lshl_add_u64 v[224:225], v[162:163], 0, v[194:195]
	global_load_dwordx4 v[160:163], v[224:225], off nt
	v_lshl_add_u64 v[182:183], v[158:159], 0, v[240:241]
	v_lshl_add_u64 v[194:195], v[158:159], 0, v[194:195]
	v_add_u32_e32 v158, s12, v200
	v_add_u32_e32 v200, s12, v206
	v_ashrrev_i32_e32 v159, 31, v158
	v_ashrrev_i32_e32 v201, 31, v200
	v_lshlrev_b64 v[158:159], 11, v[158:159]
	v_lshlrev_b64 v[200:201], 11, v[200:201]
	v_lshl_add_u64 v[158:159], s[10:11], 0, v[158:159]
	v_lshl_add_u64 v[200:201], s[10:11], 0, v[200:201]
	v_lshl_add_u64 v[206:207], v[158:159], 0, v[156:157]
	v_lshl_add_u64 v[200:201], v[200:201], 0, v[156:157]
	s_waitcnt vmcnt(1)
	v_cvt_f32_f16_e32 v158, v234
	v_cvt_f32_f16_sdwa v159, v234 dst_sel:DWORD dst_unused:UNUSED_PAD src0_sel:WORD_1
	v_cvt_f32_f16_e32 v156, v235
	v_cvt_f32_f16_sdwa v157, v235 dst_sel:DWORD dst_unused:UNUSED_PAD src0_sel:WORD_1
	v_cvt_f32_f16_e32 v234, v232
	v_cvt_f32_f16_sdwa v235, v232 dst_sel:DWORD dst_unused:UNUSED_PAD src0_sel:WORD_1
	v_cvt_f32_f16_e32 v232, v233
	v_cvt_f32_f16_sdwa v233, v233 dst_sel:DWORD dst_unused:UNUSED_PAD src0_sel:WORD_1
	s_waitcnt vmcnt(0)
	v_cvt_f32_f16_e32 v236, v162
	v_cvt_f32_f16_sdwa v237, v162 dst_sel:DWORD dst_unused:UNUSED_PAD src0_sel:WORD_1
	v_cvt_f32_f16_e32 v238, v163
	v_cvt_f32_f16_sdwa v239, v163 dst_sel:DWORD dst_unused:UNUSED_PAD src0_sel:WORD_1
	v_cvt_f32_f16_e32 v240, v160
	v_cvt_f32_f16_sdwa v241, v160 dst_sel:DWORD dst_unused:UNUSED_PAD src0_sel:WORD_1
	v_cvt_f32_f16_e32 v242, v161
	v_cvt_f32_f16_sdwa v243, v161 dst_sel:DWORD dst_unused:UNUSED_PAD src0_sel:WORD_1
	v_pk_fma_f32 v[160:161], v[80:81], v[136:137], v[232:233]
	v_pk_fma_f32 v[162:163], v[78:79], v[134:135], v[234:235]
	v_pk_fma_f32 v[156:157], v[76:77], v[132:133], v[156:157]
	v_pk_fma_f32 v[158:159], v[74:75], v[130:131], v[158:159]
	v_pk_fma_f32 v[74:75], v[68:69], v[132:133], v[238:239]
	v_pk_fma_f32 v[76:77], v[66:67], v[130:131], v[236:237]
	v_cvt_pk_f16_f32 v69, v156, v157
	v_cvt_pk_f16_f32 v67, v160, v161
	v_cvt_pk_f16_f32 v68, v158, v159
	v_cvt_pk_f16_f32 v66, v162, v163
	v_pk_fma_f32 v[78:79], v[72:73], v[136:137], v[242:243]
	v_pk_fma_f32 v[80:81], v[70:71], v[134:135], v[240:241]
	v_pk_mul_f32 v[130:131], v[216:217], v[160:161]
	v_pk_mul_f32 v[132:133], v[218:219], v[162:163]
	v_pk_mul_f32 v[134:135], v[220:221], v[156:157]
	v_pk_mul_f32 v[136:137], v[222:223], v[158:159]
	global_store_dwordx4 v[182:183], v[66:69], off
	v_cvt_pk_f16_f32 v73, v74, v75
	v_cvt_pk_f16_f32 v71, v78, v79
	v_cvt_pk_bf16_f32 v66, v132, v133
	v_cvt_pk_bf16_f32 v67, v130, v131
	v_cvt_pk_bf16_f32 v68, v136, v137
	v_cvt_pk_bf16_f32 v69, v134, v135
	v_cvt_pk_f16_f32 v72, v76, v77
	v_cvt_pk_f16_f32 v70, v80, v81
	v_pk_mul_f32 v[216:217], v[216:217], v[78:79]
	v_pk_mul_f32 v[218:219], v[218:219], v[80:81]
	v_pk_mul_f32 v[220:221], v[220:221], v[74:75]
	v_pk_mul_f32 v[222:223], v[222:223], v[76:77]
	global_store_dwordx4 v[206:207], v[66:69], off
	global_store_dwordx4 v[194:195], v[70:73], off
	s_nop 0
	v_cvt_pk_bf16_f32 v66, v218, v219
	v_cvt_pk_bf16_f32 v67, v216, v217
	v_cvt_pk_bf16_f32 v68, v222, v223
	v_cvt_pk_bf16_f32 v69, v220, v221
	global_store_dwordx4 v[200:201], v[66:69], off
	global_load_dwordx4 v[130:133], v[172:173], off offset:512
	global_load_dwordx4 v[134:137], v[172:173], off offset:528
	s_nop 0
	global_load_dwordx4 v[172:175], v[174:175], off offset:256 nt
	s_nop 0
	global_load_dwordx4 v[216:219], v[178:179], off offset:256 nt
	v_or_b32_e32 v66, 0x80, v166
	v_ashrrev_i32_e32 v67, 31, v66
	v_lshl_add_u64 v[66:67], v[66:67], 2, s[16:17]
	global_load_dwordx4 v[220:223], v[66:67], off
	global_load_dwordx4 v[232:235], v[66:67], off offset:16
	global_load_dwordx4 v[70:73], v[176:177], off offset:512
	s_nop 0
	global_load_dwordx4 v[66:69], v[176:177], off offset:528
	s_waitcnt vmcnt(7)
	v_pk_add_f32 v[132:133], v[132:133], 1.0 op_sel_hi:[1,0]
	v_pk_add_f32 v[166:167], v[130:131], 1.0 op_sel_hi:[1,0]
	s_waitcnt vmcnt(5)
	v_cvt_f32_f16_e32 v178, v174
	v_cvt_f32_f16_sdwa v179, v174 dst_sel:DWORD dst_unused:UNUSED_PAD src0_sel:WORD_1
	v_cvt_f32_f16_e32 v174, v175
	v_cvt_f32_f16_sdwa v175, v175 dst_sel:DWORD dst_unused:UNUSED_PAD src0_sel:WORD_1
	v_cvt_f32_f16_e32 v236, v172
	v_cvt_f32_f16_sdwa v237, v172 dst_sel:DWORD dst_unused:UNUSED_PAD src0_sel:WORD_1
	v_cvt_f32_f16_e32 v172, v173
	v_cvt_f32_f16_sdwa v173, v173 dst_sel:DWORD dst_unused:UNUSED_PAD src0_sel:WORD_1
	s_waitcnt vmcnt(4)
	v_cvt_f32_f16_e32 v238, v218
	v_cvt_f32_f16_sdwa v239, v218 dst_sel:DWORD dst_unused:UNUSED_PAD src0_sel:WORD_1
	v_cvt_f32_f16_e32 v218, v219
	v_cvt_f32_f16_sdwa v219, v219 dst_sel:DWORD dst_unused:UNUSED_PAD src0_sel:WORD_1
	v_cvt_f32_f16_e32 v240, v216
	v_cvt_f32_f16_sdwa v241, v216 dst_sel:DWORD dst_unused:UNUSED_PAD src0_sel:WORD_1
	v_cvt_f32_f16_e32 v216, v217
	v_cvt_f32_f16_sdwa v217, v217 dst_sel:DWORD dst_unused:UNUSED_PAD src0_sel:WORD_1
	v_pk_add_f32 v[136:137], v[136:137], 1.0 op_sel_hi:[1,0]
	v_pk_add_f32 v[176:177], v[134:135], 1.0 op_sel_hi:[1,0]
	s_waitcnt vmcnt(3)
	v_pk_mul_f32 v[130:131], v[222:223], v[132:133]
	s_waitcnt vmcnt(1)
	v_pk_fma_f32 v[64:65], v[64:65], v[72:73], v[172:173]
	v_pk_fma_f32 v[62:63], v[62:63], v[70:71], v[236:237]
	s_waitcnt vmcnt(0)
	v_pk_fma_f32 v[60:61], v[60:61], v[68:69], v[174:175]
	v_pk_fma_f32 v[58:59], v[58:59], v[66:67], v[178:179]
	v_pk_mul_f32 v[132:133], v[220:221], v[166:167]
	v_pk_mul_f32 v[134:135], v[234:235], v[136:137]
	v_pk_mul_f32 v[136:137], v[232:233], v[176:177]
	v_cvt_pk_f16_f32 v175, v60, v61
	v_cvt_pk_f16_f32 v173, v64, v65
	v_cvt_pk_f16_f32 v174, v58, v59
	v_cvt_pk_f16_f32 v172, v62, v63
	v_pk_mul_f32 v[166:167], v[130:131], v[64:65]
	v_pk_fma_f32 v[56:57], v[56:57], v[72:73], v[216:217]
	v_pk_fma_f32 v[54:55], v[54:55], v[70:71], v[240:241]
	v_pk_fma_f32 v[52:53], v[52:53], v[68:69], v[218:219]
	v_pk_fma_f32 v[50:51], v[50:51], v[66:67], v[238:239]
	v_pk_mul_f32 v[216:217], v[132:133], v[62:63]
	v_pk_mul_f32 v[218:219], v[134:135], v[60:61]
	v_pk_mul_f32 v[220:221], v[136:137], v[58:59]
	global_store_dwordx4 v[164:165], v[172:175], off offset:256
	v_cvt_pk_bf16_f32 v164, v216, v217
	v_cvt_pk_bf16_f32 v165, v166, v167
	v_cvt_pk_bf16_f32 v166, v220, v221
	v_cvt_pk_bf16_f32 v167, v218, v219
	v_cvt_pk_f16_f32 v179, v52, v53
	v_cvt_pk_f16_f32 v177, v56, v57
	v_cvt_pk_f16_f32 v178, v50, v51
	v_cvt_pk_f16_f32 v176, v54, v55
	v_pk_mul_f32 v[222:223], v[130:131], v[56:57]
	v_pk_mul_f32 v[232:233], v[132:133], v[54:55]
	v_pk_mul_f32 v[234:235], v[134:135], v[52:53]
	v_pk_mul_f32 v[236:237], v[136:137], v[50:51]
	global_store_dwordx4 v[168:169], v[164:167], off offset:256
	global_store_dwordx4 v[180:181], v[176:179], off offset:256
	v_mul_f32_e32 v63, v63, v63
	v_cvt_pk_bf16_f32 v164, v232, v233
	v_cvt_pk_bf16_f32 v165, v222, v223
	v_cvt_pk_bf16_f32 v166, v236, v237
	v_cvt_pk_bf16_f32 v167, v234, v235
	global_store_dwordx4 v[186:187], v[164:167], off offset:256
	global_load_dwordx4 v[164:167], v[188:189], off offset:256 nt
	s_nop 0
	global_load_dwordx4 v[172:175], v[190:191], off offset:256 nt
	v_mul_f32_e32 v65, v65, v65
	v_mul_f32_e32 v59, v59, v59
	v_mul_f32_e32 v61, v61, v61
	v_fmac_f32_e32 v63, v62, v62
	v_fmac_f32_e32 v65, v64, v64
	v_fmac_f32_e32 v59, v58, v58
	v_fmac_f32_e32 v61, v60, v60
	v_add_f32_e32 v58, v63, v65
	v_add_f32_e32 v59, v59, v61
	v_add_f32_e32 v58, v58, v59
	v_add_f32_e32 v59, v122, v58
	v_xor_b32_e32 v58, 32, v231
	s_waitcnt vmcnt(1)
	v_cvt_f32_f16_e32 v168, v166
	v_cvt_f32_f16_sdwa v169, v166 dst_sel:DWORD dst_unused:UNUSED_PAD src0_sel:WORD_1
	v_cvt_f32_f16_e32 v166, v167
	v_cvt_f32_f16_sdwa v167, v167 dst_sel:DWORD dst_unused:UNUSED_PAD src0_sel:WORD_1
	v_cvt_f32_f16_e32 v176, v164
	v_cvt_f32_f16_sdwa v177, v164 dst_sel:DWORD dst_unused:UNUSED_PAD src0_sel:WORD_1
	v_cvt_f32_f16_e32 v164, v165
	v_cvt_f32_f16_sdwa v165, v165 dst_sel:DWORD dst_unused:UNUSED_PAD src0_sel:WORD_1
	s_waitcnt vmcnt(0)
	v_cvt_f32_f16_e32 v178, v174
	v_cvt_f32_f16_sdwa v179, v174 dst_sel:DWORD dst_unused:UNUSED_PAD src0_sel:WORD_1
	v_cvt_f32_f16_e32 v174, v175
	v_cvt_f32_f16_sdwa v175, v175 dst_sel:DWORD dst_unused:UNUSED_PAD src0_sel:WORD_1
	v_cvt_f32_f16_e32 v180, v172
	v_cvt_f32_f16_sdwa v181, v172 dst_sel:DWORD dst_unused:UNUSED_PAD src0_sel:WORD_1
	v_cvt_f32_f16_e32 v172, v173
	v_cvt_f32_f16_sdwa v173, v173 dst_sel:DWORD dst_unused:UNUSED_PAD src0_sel:WORD_1
	v_pk_fma_f32 v[48:49], v[48:49], v[72:73], v[164:165]
	v_pk_fma_f32 v[46:47], v[46:47], v[70:71], v[176:177]
	v_pk_fma_f32 v[44:45], v[44:45], v[68:69], v[166:167]
	v_pk_fma_f32 v[42:43], v[42:43], v[66:67], v[168:169]
	v_cvt_pk_f16_f32 v167, v44, v45
	v_cvt_pk_f16_f32 v165, v48, v49
	v_cvt_pk_f16_f32 v166, v42, v43
	v_cvt_pk_f16_f32 v164, v46, v47
	v_pk_fma_f32 v[40:41], v[40:41], v[72:73], v[172:173]
	v_pk_fma_f32 v[38:39], v[38:39], v[70:71], v[180:181]
	v_pk_fma_f32 v[36:37], v[36:37], v[68:69], v[174:175]
	v_pk_fma_f32 v[34:35], v[34:35], v[66:67], v[178:179]
	v_pk_mul_f32 v[168:169], v[130:131], v[48:49]
	v_pk_mul_f32 v[176:177], v[132:133], v[46:47]
	v_pk_mul_f32 v[178:179], v[134:135], v[44:45]
	v_pk_mul_f32 v[180:181], v[136:137], v[42:43]
	global_store_dwordx4 v[170:171], v[164:167], off offset:256
	v_cvt_pk_f16_f32 v175, v36, v37
	v_cvt_pk_f16_f32 v173, v40, v41
	v_cvt_pk_bf16_f32 v164, v176, v177
	v_cvt_pk_bf16_f32 v165, v168, v169
	v_cvt_pk_bf16_f32 v166, v180, v181
	v_cvt_pk_bf16_f32 v167, v178, v179
	v_cvt_pk_f16_f32 v174, v34, v35
	v_cvt_pk_f16_f32 v172, v38, v39
	v_pk_mul_f32 v[186:187], v[130:131], v[40:41]
	v_pk_mul_f32 v[188:189], v[132:133], v[38:39]
	v_pk_mul_f32 v[190:191], v[134:135], v[36:37]
	v_pk_mul_f32 v[216:217], v[136:137], v[34:35]
	global_store_dwordx4 v[192:193], v[164:167], off offset:256
	global_store_dwordx4 v[184:185], v[172:175], off offset:256
	s_nop 0
	v_cvt_pk_bf16_f32 v164, v188, v189
	v_cvt_pk_bf16_f32 v165, v186, v187
	v_cvt_pk_bf16_f32 v166, v216, v217
	v_cvt_pk_bf16_f32 v167, v190, v191
	global_store_dwordx4 v[196:197], v[164:167], off offset:256
	global_load_dwordx4 v[164:167], v[198:199], off offset:256 nt
	s_nop 0
	global_load_dwordx4 v[168:171], v[204:205], off offset:256 nt
	s_waitcnt vmcnt(1)
	v_cvt_f32_f16_e32 v172, v166
	v_cvt_f32_f16_sdwa v173, v166 dst_sel:DWORD dst_unused:UNUSED_PAD src0_sel:WORD_1
	v_cvt_f32_f16_e32 v166, v167
	v_cvt_f32_f16_sdwa v167, v167 dst_sel:DWORD dst_unused:UNUSED_PAD src0_sel:WORD_1
	v_cvt_f32_f16_e32 v174, v164
	v_cvt_f32_f16_sdwa v175, v164 dst_sel:DWORD dst_unused:UNUSED_PAD src0_sel:WORD_1
	v_cvt_f32_f16_e32 v164, v165
	v_cvt_f32_f16_sdwa v165, v165 dst_sel:DWORD dst_unused:UNUSED_PAD src0_sel:WORD_1
	s_waitcnt vmcnt(0)
	v_cvt_f32_f16_e32 v176, v170
	v_cvt_f32_f16_sdwa v177, v170 dst_sel:DWORD dst_unused:UNUSED_PAD src0_sel:WORD_1
	v_cvt_f32_f16_e32 v170, v171
	v_cvt_f32_f16_sdwa v171, v171 dst_sel:DWORD dst_unused:UNUSED_PAD src0_sel:WORD_1
	v_cvt_f32_f16_e32 v178, v168
	v_cvt_f32_f16_sdwa v179, v168 dst_sel:DWORD dst_unused:UNUSED_PAD src0_sel:WORD_1
	v_cvt_f32_f16_e32 v168, v169
	v_cvt_f32_f16_sdwa v169, v169 dst_sel:DWORD dst_unused:UNUSED_PAD src0_sel:WORD_1
	v_pk_fma_f32 v[32:33], v[32:33], v[72:73], v[164:165]
	v_pk_fma_f32 v[30:31], v[30:31], v[70:71], v[174:175]
	v_pk_fma_f32 v[28:29], v[28:29], v[68:69], v[166:167]
	v_pk_fma_f32 v[26:27], v[26:27], v[66:67], v[172:173]
	v_cvt_pk_f16_f32 v167, v28, v29
	v_cvt_pk_f16_f32 v165, v32, v33
	v_cvt_pk_f16_f32 v166, v26, v27
	v_cvt_pk_f16_f32 v164, v30, v31
	v_pk_fma_f32 v[24:25], v[24:25], v[72:73], v[168:169]
	v_pk_fma_f32 v[22:23], v[22:23], v[70:71], v[178:179]
	v_pk_fma_f32 v[20:21], v[20:21], v[68:69], v[170:171]
	v_pk_fma_f32 v[18:19], v[18:19], v[66:67], v[176:177]
	v_pk_mul_f32 v[172:173], v[130:131], v[32:33]
	v_pk_mul_f32 v[174:175], v[132:133], v[30:31]
	v_pk_mul_f32 v[176:177], v[134:135], v[28:29]
	v_pk_mul_f32 v[178:179], v[136:137], v[26:27]
	global_store_dwordx4 v[212:213], v[164:167], off offset:256
	v_cvt_pk_f16_f32 v171, v20, v21
	v_cvt_pk_f16_f32 v169, v24, v25
	v_cvt_pk_bf16_f32 v164, v174, v175
	v_cvt_pk_bf16_f32 v165, v172, v173
	v_cvt_pk_bf16_f32 v166, v178, v179
	v_cvt_pk_bf16_f32 v167, v176, v177
	v_cvt_pk_f16_f32 v170, v18, v19
	v_cvt_pk_f16_f32 v168, v22, v23
	v_pk_mul_f32 v[180:181], v[130:131], v[24:25]
	v_pk_mul_f32 v[184:185], v[132:133], v[22:23]
	v_pk_mul_f32 v[186:187], v[134:135], v[20:21]
	v_pk_mul_f32 v[188:189], v[136:137], v[18:19]
	global_store_dwordx4 v[214:215], v[164:167], off offset:256
	global_store_dwordx4 v[210:211], v[168:171], off offset:256
	s_nop 0
	v_cvt_pk_bf16_f32 v164, v184, v185
	v_cvt_pk_bf16_f32 v165, v180, v181
	v_cvt_pk_bf16_f32 v166, v188, v189
	v_cvt_pk_bf16_f32 v167, v186, v187
	global_store_dwordx4 v[208:209], v[164:167], off offset:256
	global_load_dwordx4 v[166:169], v[202:203], off offset:256 nt
	s_nop 0
	global_load_dwordx4 v[170:173], v[224:225], off offset:256 nt
	v_and_b32_e32 v165, 64, v231
	v_xor_b32_e32 v164, 16, v231
	v_add_u32_e32 v165, 64, v165
	v_cmp_lt_i32_e32 vcc, v164, v165
	s_waitcnt vmcnt(1)
	v_cvt_f32_f16_e32 v62, v168
	v_cndmask_b32_e32 v164, v231, v164, vcc
	v_lshlrev_b32_e32 v164, 2, v164
	ds_bpermute_b32 v60, v164, v59
	v_cmp_lt_i32_e32 vcc, v58, v165
	v_cvt_f32_f16_sdwa v63, v168 dst_sel:DWORD dst_unused:UNUSED_PAD src0_sel:WORD_1
	v_cvt_f32_f16_e32 v64, v169
	v_cndmask_b32_e32 v58, v231, v58, vcc
	v_cvt_f32_f16_sdwa v65, v169 dst_sel:DWORD dst_unused:UNUSED_PAD src0_sel:WORD_1
	v_cvt_f32_f16_e32 v122, v166
	v_cvt_f32_f16_sdwa v123, v166 dst_sel:DWORD dst_unused:UNUSED_PAD src0_sel:WORD_1
	v_cvt_f32_f16_e32 v124, v167
	v_cvt_f32_f16_sdwa v125, v167 dst_sel:DWORD dst_unused:UNUSED_PAD src0_sel:WORD_1
	v_lshlrev_b32_e32 v58, 2, v58
	s_waitcnt lgkmcnt(0)
	v_add_f32_e32 v59, v59, v60
	ds_bpermute_b32 v60, v58, v59
	s_waitcnt vmcnt(0)
	v_cvt_f32_f16_e32 v126, v172
	v_cvt_f32_f16_sdwa v127, v172 dst_sel:DWORD dst_unused:UNUSED_PAD src0_sel:WORD_1
	v_cvt_f32_f16_e32 v128, v173
	v_cvt_f32_f16_sdwa v129, v173 dst_sel:DWORD dst_unused:UNUSED_PAD src0_sel:WORD_1
	v_cvt_f32_f16_e32 v166, v170
	v_cvt_f32_f16_sdwa v167, v170 dst_sel:DWORD dst_unused:UNUSED_PAD src0_sel:WORD_1
	v_cvt_f32_f16_e32 v168, v171
	v_cvt_f32_f16_sdwa v169, v171 dst_sel:DWORD dst_unused:UNUSED_PAD src0_sel:WORD_1
	v_pk_fma_f32 v[16:17], v[16:17], v[72:73], v[124:125]
	v_pk_fma_f32 v[14:15], v[14:15], v[70:71], v[122:123]
	v_pk_fma_f32 v[12:13], v[12:13], v[68:69], v[64:65]
	v_pk_fma_f32 v[10:11], v[10:11], v[66:67], v[62:63]
	v_cvt_pk_f16_f32 v65, v12, v13
	v_cvt_pk_f16_f32 v63, v16, v17
	v_cvt_pk_f16_f32 v64, v10, v11
	v_cvt_pk_f16_f32 v62, v14, v15
	v_pk_fma_f32 v[8:9], v[8:9], v[72:73], v[168:169]
	v_pk_fma_f32 v[6:7], v[6:7], v[70:71], v[166:167]
	v_pk_fma_f32 v[4:5], v[4:5], v[68:69], v[128:129]
	v_pk_fma_f32 v[2:3], v[2:3], v[66:67], v[126:127]
	v_pk_mul_f32 v[70:71], v[130:131], v[16:17]
	v_pk_mul_f32 v[72:73], v[132:133], v[14:15]
	v_pk_mul_f32 v[122:123], v[134:135], v[12:13]
	v_pk_mul_f32 v[124:125], v[136:137], v[10:11]
	global_store_dwordx4 v[182:183], v[62:65], off offset:256
	v_cvt_pk_f16_f32 v69, v4, v5
	v_cvt_pk_f16_f32 v67, v8, v9
	v_cvt_pk_bf16_f32 v62, v72, v73
	v_cvt_pk_bf16_f32 v63, v70, v71
	v_cvt_pk_bf16_f32 v64, v124, v125
	v_cvt_pk_bf16_f32 v65, v122, v123
	v_cvt_pk_f16_f32 v68, v2, v3
	v_cvt_pk_f16_f32 v66, v6, v7
	v_pk_mul_f32 v[126:127], v[130:131], v[8:9]
	v_pk_mul_f32 v[128:129], v[132:133], v[6:7]
	v_pk_mul_f32 v[130:131], v[134:135], v[4:5]
	v_pk_mul_f32 v[132:133], v[136:137], v[2:3]
	global_store_dwordx4 v[206:207], v[62:65], off offset:256
	global_store_dwordx4 v[194:195], v[66:69], off offset:256
	s_nop 0
	v_cvt_pk_bf16_f32 v62, v128, v129
	v_cvt_pk_bf16_f32 v63, v126, v127
	v_cvt_pk_bf16_f32 v64, v132, v133
	v_cvt_pk_bf16_f32 v65, v130, v131
	global_store_dwordx4 v[200:201], v[62:65], off offset:256
	s_and_saveexec_b64 s[26:27], s[4:5]
	s_cbranch_execz .LBB0_1564
	v_lshl_add_u64 v[62:63], v[154:155], 2, s[22:23]
	s_waitcnt lgkmcnt(0)
	v_add_f32_e32 v59, v59, v60
	global_atomic_add_f32 v[62:63], v59, off

.LBB0_1606:
	ds_read_b128 v[106:109], v201
	ds_read_b128 v[110:113], v201 offset:1024
	ds_read_b128 v[138:141], v201 offset:2048
	ds_read_b128 v[158:161], v201 offset:3072
	ds_read_b128 v[162:165], v202
	ds_read_b128 v[166:169], v202 offset:1024
	ds_read_b128 v[170:173], v202 offset:2048
	ds_read_b128 v[174:177], v202 offset:3072
	s_add_u32 s0, s10, 0x100
	s_addc_u32 s1, s11, 0
	s_cmp_eq_u32 s12, 40
	s_cselect_b32 s51, s45, s1
	s_cselect_b32 s50, s44, s0
	s_cselect_b32 s49, s47, s77
	s_cselect_b32 s48, s46, s9
	v_lshl_add_u64 v[220:221], s[10:11], 0, v[150:151]
	s_add_i32 m0, s54, 0xc000
	ds_read_b128 v[178:181], v203
	ds_read_b128 v[182:185], v203 offset:1024
	ds_read_b128 v[186:189], v203 offset:2048
	ds_read_b128 v[190:193], v203 offset:3072
	ds_read_b128 v[194:197], v203 offset:4096
	ds_read_b128 v[208:211], v203 offset:5120
	ds_read_b128 v[212:215], v203 offset:6144
	ds_read_b128 v[216:219], v203 offset:7168
	global_load_lds_dwordx4 v[220:221], off
	v_lshl_add_u64 v[220:221], s[10:11], 0, v[152:153]
	s_add_i32 m0, s54, 0xe000
	s_nop 0
	global_load_lds_dwordx4 v[220:221], off
	s_waitcnt vmcnt(8)
	s_waitcnt lgkmcnt(0)
	s_barrier
	s_setprio 1
	s_waitcnt lgkmcnt(0)
	v_mfma_f32_16x16x32_bf16 v[74:77], v[106:109], v[178:181], v[74:77]
	v_mfma_f32_16x16x32_bf16 v[70:73], v[138:141], v[178:181], v[70:73]
	v_mfma_f32_16x16x32_bf16 v[134:137], v[106:109], v[186:189], v[134:137]
	v_mfma_f32_16x16x32_bf16 v[130:133], v[138:141], v[186:189], v[130:133]
	v_mfma_f32_16x16x32_bf16 v[54:57], v[106:109], v[194:197], v[54:57]
	v_mfma_f32_16x16x32_bf16 v[50:53], v[138:141], v[194:197], v[50:53]
	v_mfma_f32_16x16x32_bf16 v[126:129], v[106:109], v[212:215], v[126:129]
	v_mfma_f32_16x16x32_bf16 v[122:125], v[138:141], v[212:215], v[122:125]
	v_mfma_f32_16x16x32_bf16 v[74:77], v[110:113], v[182:185], v[74:77]
	v_mfma_f32_16x16x32_bf16 v[70:73], v[158:161], v[182:185], v[70:73]
	v_mfma_f32_16x16x32_bf16 v[134:137], v[110:113], v[190:193], v[134:137]
	v_mfma_f32_16x16x32_bf16 v[130:133], v[158:161], v[190:193], v[130:133]
	v_mfma_f32_16x16x32_bf16 v[54:57], v[110:113], v[208:211], v[54:57]
	v_mfma_f32_16x16x32_bf16 v[50:53], v[158:161], v[208:211], v[50:53]
	v_mfma_f32_16x16x32_bf16 v[126:129], v[110:113], v[216:219], v[126:129]
	v_mfma_f32_16x16x32_bf16 v[122:125], v[158:161], v[216:219], v[122:125]
	s_setprio 0
	s_setprio 1
	v_mfma_f32_16x16x32_bf16 v[62:65], v[162:165], v[178:181], v[62:65]
	v_mfma_f32_16x16x32_bf16 v[58:61], v[170:173], v[178:181], v[58:61]
	v_mfma_f32_16x16x32_bf16 v[94:97], v[162:165], v[186:189], v[94:97]
	v_mfma_f32_16x16x32_bf16 v[90:93], v[170:173], v[186:189], v[90:93]
	v_mfma_f32_16x16x32_bf16 v[38:41], v[162:165], v[194:197], v[38:41]
	v_mfma_f32_16x16x32_bf16 v[34:37], v[170:173], v[194:197], v[34:37]
	v_mfma_f32_16x16x32_bf16 v[86:89], v[162:165], v[212:215], v[86:89]
	v_mfma_f32_16x16x32_bf16 v[82:85], v[170:173], v[212:215], v[82:85]
	v_mfma_f32_16x16x32_bf16 v[62:65], v[166:169], v[182:185], v[62:65]
	v_mfma_f32_16x16x32_bf16 v[58:61], v[174:177], v[182:185], v[58:61]
	v_mfma_f32_16x16x32_bf16 v[94:97], v[166:169], v[190:193], v[94:97]
	v_mfma_f32_16x16x32_bf16 v[90:93], v[174:177], v[190:193], v[90:93]
	v_mfma_f32_16x16x32_bf16 v[38:41], v[166:169], v[208:211], v[38:41]
	v_mfma_f32_16x16x32_bf16 v[34:37], v[174:177], v[208:211], v[34:37]
	v_mfma_f32_16x16x32_bf16 v[86:89], v[166:169], v[216:219], v[86:89]
	v_mfma_f32_16x16x32_bf16 v[82:85], v[174:177], v[216:219], v[82:85]
	s_setprio 0
	s_barrier
	s_add_i32 s10, s70, s33
	s_mov_b32 m0, s10
	ds_read_b128 v[178:181], v203 offset:16384
	ds_read_b128 v[182:185], v203 offset:17408
	ds_read_b128 v[186:189], v203 offset:18432
	ds_read_b128 v[190:193], v203 offset:19456
	ds_read_b128 v[194:197], v203 offset:20480
	ds_read_b128 v[208:211], v203 offset:21504
	ds_read_b128 v[212:215], v203 offset:22528
	ds_read_b128 v[216:219], v203 offset:23552
	global_load_lds_dwordx4 v144, s[48:49]
	s_add_i32 m0, s10, 0x2000
	s_add_u32 s10, s48, 0xb0000
	s_addc_u32 s11, s49, 0
	s_add_i32 s13, s71, s33
	global_load_lds_dwordx4 v148, s[48:49]
	s_mov_b32 m0, s13
	s_nop 0
	global_load_lds_dwordx4 v144, s[10:11]
	s_add_i32 m0, s13, 0x2000
	s_nop 0
	global_load_lds_dwordx4 v148, s[10:11]
	s_mov_b32 m0, s54
	s_nop 0
	global_load_lds_dwordx4 v142, s[50:51]
	s_mov_b32 m0, s55
	s_nop 0
	global_load_lds_dwordx4 v146, s[50:51]
	s_waitcnt vmcnt(8)
	s_waitcnt lgkmcnt(0)
	s_barrier
	s_setprio 1
	s_waitcnt lgkmcnt(0)
	v_mfma_f32_16x16x32_bf16 v[30:33], v[106:109], v[178:181], v[30:33]
	v_mfma_f32_16x16x32_bf16 v[26:29], v[138:141], v[178:181], v[26:29]
	v_mfma_f32_16x16x32_bf16 v[118:121], v[106:109], v[186:189], v[118:121]
	v_mfma_f32_16x16x32_bf16 v[114:117], v[138:141], v[186:189], v[114:117]
	v_mfma_f32_16x16x32_bf16 v[14:17], v[106:109], v[194:197], v[14:17]
	v_mfma_f32_16x16x32_bf16 v[10:13], v[138:141], v[194:197], v[10:13]
	v_mfma_f32_16x16x32_bf16 v[102:105], v[106:109], v[212:215], v[102:105]
	v_mfma_f32_16x16x32_bf16 v[98:101], v[138:141], v[212:215], v[98:101]
	v_mfma_f32_16x16x32_bf16 v[30:33], v[110:113], v[182:185], v[30:33]
	v_mfma_f32_16x16x32_bf16 v[26:29], v[158:161], v[182:185], v[26:29]
	v_mfma_f32_16x16x32_bf16 v[118:121], v[110:113], v[190:193], v[118:121]
	v_mfma_f32_16x16x32_bf16 v[114:117], v[158:161], v[190:193], v[114:117]
	v_mfma_f32_16x16x32_bf16 v[14:17], v[110:113], v[208:211], v[14:17]
	v_mfma_f32_16x16x32_bf16 v[10:13], v[158:161], v[208:211], v[10:13]
	v_mfma_f32_16x16x32_bf16 v[102:105], v[110:113], v[216:219], v[102:105]
	v_mfma_f32_16x16x32_bf16 v[98:101], v[158:161], v[216:219], v[98:101]
	s_setprio 0
	s_setprio 1
	v_mfma_f32_16x16x32_bf16 v[22:25], v[162:165], v[178:181], v[22:25]
	v_mfma_f32_16x16x32_bf16 v[18:21], v[170:173], v[178:181], v[18:21]
	v_mfma_f32_16x16x32_bf16 v[78:81], v[162:165], v[186:189], v[78:81]
	v_mfma_f32_16x16x32_bf16 v[66:69], v[170:173], v[186:189], v[66:69]
	v_mfma_f32_16x16x32_bf16 v[6:9], v[162:165], v[194:197], v[6:9]
	v_mfma_f32_16x16x32_bf16 v[2:5], v[170:173], v[194:197], v[2:5]
	v_mfma_f32_16x16x32_bf16 v[46:49], v[162:165], v[212:215], v[46:49]
	v_mfma_f32_16x16x32_bf16 v[42:45], v[170:173], v[212:215], v[42:45]
	v_mfma_f32_16x16x32_bf16 v[22:25], v[166:169], v[182:185], v[22:25]
	v_mfma_f32_16x16x32_bf16 v[18:21], v[174:177], v[182:185], v[18:21]
	v_mfma_f32_16x16x32_bf16 v[78:81], v[166:169], v[190:193], v[78:81]
	v_mfma_f32_16x16x32_bf16 v[66:69], v[174:177], v[190:193], v[66:69]
	v_mfma_f32_16x16x32_bf16 v[6:9], v[166:169], v[208:211], v[6:9]
	v_mfma_f32_16x16x32_bf16 v[2:5], v[174:177], v[208:211], v[2:5]
	v_mfma_f32_16x16x32_bf16 v[46:49], v[166:169], v[216:219], v[46:49]
	v_mfma_f32_16x16x32_bf16 v[42:45], v[174:177], v[216:219], v[42:45]
	s_setprio 0
	s_barrier
	s_add_i32 s13, 0, 0x18000
	s_add_i32 s78, 0, 0x1c000
	v_add_u32_e32 v158, s13, v199
	v_add_u32_e32 v174, s78, v199
	ds_read_b128 v[106:109], v158
	ds_read_b128 v[110:113], v158 offset:1024
	ds_read_b128 v[138:141], v158 offset:2048
	ds_read_b128 v[158:161], v158 offset:3072
	ds_read_b128 v[162:165], v174
	ds_read_b128 v[166:169], v174 offset:1024
	ds_read_b128 v[170:173], v174 offset:2048
	ds_read_b128 v[174:177], v174 offset:3072
	s_add_u32 s10, s50, 0xb0000
	s_addc_u32 s11, s51, 0
	s_mov_b32 m0, s56
	ds_read_b128 v[178:181], v203 offset:32768
	ds_read_b128 v[182:185], v203 offset:33792
	ds_read_b128 v[186:189], v203 offset:34816
	ds_read_b128 v[190:193], v203 offset:35840
	ds_read_b128 v[194:197], v203 offset:36864
	ds_read_b128 v[208:211], v203 offset:37888
	ds_read_b128 v[212:215], v203 offset:38912
	ds_read_b128 v[216:219], v203 offset:39936
	global_load_lds_dwordx4 v142, s[10:11]
	s_mov_b32 m0, s57
	s_nop 0
	global_load_lds_dwordx4 v146, s[10:11]
	s_waitcnt vmcnt(8)
	s_waitcnt lgkmcnt(0)
	s_barrier
	s_setprio 1
	s_waitcnt lgkmcnt(0)
	v_mfma_f32_16x16x32_bf16 v[74:77], v[106:109], v[178:181], v[74:77]
	v_mfma_f32_16x16x32_bf16 v[70:73], v[138:141], v[178:181], v[70:73]
	v_mfma_f32_16x16x32_bf16 v[134:137], v[106:109], v[186:189], v[134:137]
	v_mfma_f32_16x16x32_bf16 v[130:133], v[138:141], v[186:189], v[130:133]
	v_mfma_f32_16x16x32_bf16 v[54:57], v[106:109], v[194:197], v[54:57]
	v_mfma_f32_16x16x32_bf16 v[50:53], v[138:141], v[194:197], v[50:53]
	v_mfma_f32_16x16x32_bf16 v[126:129], v[106:109], v[212:215], v[126:129]
	v_mfma_f32_16x16x32_bf16 v[122:125], v[138:141], v[212:215], v[122:125]
	v_mfma_f32_16x16x32_bf16 v[74:77], v[110:113], v[182:185], v[74:77]
	v_mfma_f32_16x16x32_bf16 v[70:73], v[158:161], v[182:185], v[70:73]
	v_mfma_f32_16x16x32_bf16 v[134:137], v[110:113], v[190:193], v[134:137]
	v_mfma_f32_16x16x32_bf16 v[130:133], v[158:161], v[190:193], v[130:133]
	v_mfma_f32_16x16x32_bf16 v[54:57], v[110:113], v[208:211], v[54:57]
	v_mfma_f32_16x16x32_bf16 v[50:53], v[158:161], v[208:211], v[50:53]
	v_mfma_f32_16x16x32_bf16 v[126:129], v[110:113], v[216:219], v[126:129]
	v_mfma_f32_16x16x32_bf16 v[122:125], v[158:161], v[216:219], v[122:125]
	s_setprio 0
	s_setprio 1
	v_mfma_f32_16x16x32_bf16 v[62:65], v[162:165], v[178:181], v[62:65]
	v_mfma_f32_16x16x32_bf16 v[58:61], v[170:173], v[178:181], v[58:61]
	v_mfma_f32_16x16x32_bf16 v[94:97], v[162:165], v[186:189], v[94:97]
	v_mfma_f32_16x16x32_bf16 v[90:93], v[170:173], v[186:189], v[90:93]
	v_mfma_f32_16x16x32_bf16 v[38:41], v[162:165], v[194:197], v[38:41]
	v_mfma_f32_16x16x32_bf16 v[34:37], v[170:173], v[194:197], v[34:37]
	v_mfma_f32_16x16x32_bf16 v[86:89], v[162:165], v[212:215], v[86:89]
	v_mfma_f32_16x16x32_bf16 v[82:85], v[170:173], v[212:215], v[82:85]
	v_mfma_f32_16x16x32_bf16 v[62:65], v[166:169], v[182:185], v[62:65]
	v_mfma_f32_16x16x32_bf16 v[58:61], v[174:177], v[182:185], v[58:61]
	v_mfma_f32_16x16x32_bf16 v[94:97], v[166:169], v[190:193], v[94:97]
	v_mfma_f32_16x16x32_bf16 v[90:93], v[174:177], v[190:193], v[90:93]
	v_mfma_f32_16x16x32_bf16 v[38:41], v[166:169], v[208:211], v[38:41]
	v_mfma_f32_16x16x32_bf16 v[34:37], v[174:177], v[208:211], v[34:37]
	v_mfma_f32_16x16x32_bf16 v[86:89], v[166:169], v[216:219], v[86:89]
	v_mfma_f32_16x16x32_bf16 v[82:85], v[174:177], v[216:219], v[82:85]
	s_setprio 0
	s_barrier
	s_add_i32 s10, s13, s33
	s_mov_b32 m0, s10
	ds_read_b128 v[178:181], v203 offset:49152
	ds_read_b128 v[182:185], v203 offset:50176
	ds_read_b128 v[186:189], v203 offset:51200
	ds_read_b128 v[190:193], v203 offset:52224
	ds_read_b128 v[194:197], v203 offset:53248
	ds_read_b128 v[208:211], v203 offset:54272
	ds_read_b128 v[212:215], v203 offset:55296
	ds_read_b128 v[216:219], v203 offset:56320
	global_load_lds_dwordx4 v251, s[48:49]
	s_add_i32 m0, s10, 0x2000
	s_add_u32 s10, s48, 0xb0080
	s_addc_u32 s11, s49, 0
	s_add_i32 s13, s78, s33
	global_load_lds_dwordx4 v252, s[48:49]
	s_mov_b32 m0, s13
	s_nop 0
	global_load_lds_dwordx4 v144, s[10:11]
	s_add_i32 m0, s13, 0x2000
	s_nop 0
	global_load_lds_dwordx4 v148, s[10:11]
	s_mov_b32 m0, s67
	s_nop 0
	global_load_lds_dwordx4 v253, s[50:51]
	s_mov_b32 m0, s68
	s_nop 0
	global_load_lds_dwordx4 v254, s[50:51]
	s_waitcnt vmcnt(8)
	s_waitcnt lgkmcnt(0)
	s_barrier
	s_setprio 1
	s_waitcnt lgkmcnt(0)
	v_mfma_f32_16x16x32_bf16 v[30:33], v[106:109], v[178:181], v[30:33]
	v_mfma_f32_16x16x32_bf16 v[26:29], v[138:141], v[178:181], v[26:29]
	v_mfma_f32_16x16x32_bf16 v[118:121], v[106:109], v[186:189], v[118:121]
	v_mfma_f32_16x16x32_bf16 v[114:117], v[138:141], v[186:189], v[114:117]
	v_mfma_f32_16x16x32_bf16 v[14:17], v[106:109], v[194:197], v[14:17]
	v_mfma_f32_16x16x32_bf16 v[10:13], v[138:141], v[194:197], v[10:13]
	v_mfma_f32_16x16x32_bf16 v[102:105], v[106:109], v[212:215], v[102:105]
	v_mfma_f32_16x16x32_bf16 v[98:101], v[138:141], v[212:215], v[98:101]
	v_mfma_f32_16x16x32_bf16 v[30:33], v[110:113], v[182:185], v[30:33]
	v_mfma_f32_16x16x32_bf16 v[26:29], v[158:161], v[182:185], v[26:29]
	v_mfma_f32_16x16x32_bf16 v[118:121], v[110:113], v[190:193], v[118:121]
	v_mfma_f32_16x16x32_bf16 v[114:117], v[158:161], v[190:193], v[114:117]
	v_mfma_f32_16x16x32_bf16 v[14:17], v[110:113], v[208:211], v[14:17]
	v_mfma_f32_16x16x32_bf16 v[10:13], v[158:161], v[208:211], v[10:13]
	v_mfma_f32_16x16x32_bf16 v[102:105], v[110:113], v[216:219], v[102:105]
	v_mfma_f32_16x16x32_bf16 v[98:101], v[158:161], v[216:219], v[98:101]
	s_setprio 0
	s_setprio 1
	v_mfma_f32_16x16x32_bf16 v[22:25], v[162:165], v[178:181], v[22:25]
	v_mfma_f32_16x16x32_bf16 v[18:21], v[170:173], v[178:181], v[18:21]
	v_mfma_f32_16x16x32_bf16 v[78:81], v[162:165], v[186:189], v[78:81]
	v_mfma_f32_16x16x32_bf16 v[66:69], v[170:173], v[186:189], v[66:69]
	v_mfma_f32_16x16x32_bf16 v[6:9], v[162:165], v[194:197], v[6:9]
	v_mfma_f32_16x16x32_bf16 v[2:5], v[170:173], v[194:197], v[2:5]
	v_mfma_f32_16x16x32_bf16 v[46:49], v[162:165], v[212:215], v[46:49]
	v_mfma_f32_16x16x32_bf16 v[42:45], v[170:173], v[212:215], v[42:45]
	v_mfma_f32_16x16x32_bf16 v[22:25], v[166:169], v[182:185], v[22:25]
	v_mfma_f32_16x16x32_bf16 v[18:21], v[174:177], v[182:185], v[18:21]
	v_mfma_f32_16x16x32_bf16 v[78:81], v[166:169], v[190:193], v[78:81]
	v_mfma_f32_16x16x32_bf16 v[66:69], v[174:177], v[190:193], v[66:69]
	v_mfma_f32_16x16x32_bf16 v[6:9], v[166:169], v[208:211], v[6:9]
	v_mfma_f32_16x16x32_bf16 v[2:5], v[174:177], v[208:211], v[2:5]
	v_mfma_f32_16x16x32_bf16 v[46:49], v[166:169], v[216:219], v[46:49]
	v_mfma_f32_16x16x32_bf16 v[42:45], v[174:177], v[216:219], v[42:45]
	s_setprio 0
	s_barrier
	s_add_i32 s12, s12, 2
	s_add_u32 s9, s9, 0x100
	s_addc_u32 s77, s77, 0
	s_cmp_gt_u32 s12, 41
	s_mov_b64 s[10:11], s[0:1]
	s_cbranch_scc0 .LBB0_1606
	s_and_b64 vcc, exec, s[28:29]
	s_cbranch_vccz .LBB0_1609
	s_barrier
